# epilogue-before-last-barrier for the lagging wave half in all six GEMM phases (flag cleared after the retention-context detour in the gated-merge phase)
# baseline (speedup 1.0000x reference)
.LBB0_376:
	s_mov_b32 s50, 0
	v_readlane_b32 s0, v251, 36
	s_mov_b32 s20, s91
	s_waitcnt vmcnt(0)
	v_lshl_add_u32 v8, s0, 6, v220
	s_cmpk_lt_i32 s20, 0x8a2
	s_cselect_b64 s[0:1], -1, 0
	s_cmpk_gt_i32 s20, 0x8a1
	v_readfirstlane_b32 s12, v8
	s_cbranch_scc1 .LBB0_386
	s_ashr_i32 s2, s20, 31
	s_lshr_b32 s2, s2, 29
	s_add_i32 s4, s20, s2
	s_and_b32 s2, s4, -8
	s_sub_i32 s5, s20, s2
	s_cmp_gt_i32 s5, 1
	s_mov_b64 s[2:3], -1
	s_cbranch_scc0 .LBB0_379
	s_mul_i32 s2, s5, 0x114
	s_or_b32 s6, s2, 2
	s_mov_b64 s[2:3], 0

.LBB0_390:
	s_mov_b32 s4, 0x3db504f3
	v_pk_mul_f32 v[92:93], v[92:93], s[4:5] op_sel_hi:[1,0]
	v_pk_mul_f32 v[90:91], v[90:91], s[4:5] op_sel_hi:[1,0]
	v_pk_mul_f32 v[96:97], v[96:97], s[4:5] op_sel_hi:[1,0]
	v_pk_mul_f32 v[94:95], v[94:95], s[4:5] op_sel_hi:[1,0]
	s_waitcnt vmcnt(0)
	v_pk_mul_f32 v[114:115], v[90:91], v[24:25]
	v_pk_mul_f32 v[116:117], v[92:93], v[28:29]
	v_pk_fma_f32 v[114:115], v[94:95], v[22:23], v[114:115] neg_lo:[0,0,1] neg_hi:[0,0,1]
	v_pk_fma_f32 v[116:117], v[96:97], v[26:27], v[116:117] neg_lo:[0,0,1] neg_hi:[0,0,1]
	v_pk_mul_f32 v[94:95], v[94:95], v[24:25]
	v_pk_mul_f32 v[96:97], v[96:97], v[28:29]
	v_pk_fma_f32 v[90:91], v[90:91], v[22:23], v[94:95]
	v_pk_fma_f32 v[92:93], v[92:93], v[26:27], v[96:97]
	v_pk_mul_f32 v[84:85], v[84:85], s[4:5] op_sel_hi:[1,0]
	v_cvt_pk_f16_f32 v93, v92, v93
	v_cvt_pk_f16_f32 v92, v90, v91
	v_pk_mul_f32 v[82:83], v[82:83], s[4:5] op_sel_hi:[1,0]
	global_store_dwordx2 v[4:5], v[92:93], off offset:256
	v_pk_mul_f32 v[88:89], v[88:89], s[4:5] op_sel_hi:[1,0]
	v_pk_mul_f32 v[86:87], v[86:87], s[4:5] op_sel_hi:[1,0]
	v_pk_mul_f32 v[90:91], v[82:83], v[20:21]
	v_pk_mul_f32 v[92:93], v[84:85], v[98:99]
	v_pk_fma_f32 v[90:91], v[86:87], v[18:19], v[90:91] neg_lo:[0,0,1] neg_hi:[0,0,1]
	v_pk_fma_f32 v[92:93], v[88:89], v[30:31], v[92:93] neg_lo:[0,0,1] neg_hi:[0,0,1]
	v_pk_mul_f32 v[86:87], v[86:87], v[20:21]
	v_pk_mul_f32 v[88:89], v[88:89], v[98:99]
	v_pk_fma_f32 v[82:83], v[82:83], v[18:19], v[86:87]
	v_pk_fma_f32 v[84:85], v[84:85], v[30:31], v[88:89]
	v_pk_mul_f32 v[76:77], v[76:77], s[4:5] op_sel_hi:[1,0]
	v_cvt_pk_f16_f32 v85, v84, v85
	v_cvt_pk_f16_f32 v84, v82, v83
	v_pk_mul_f32 v[74:75], v[74:75], s[4:5] op_sel_hi:[1,0]
	global_store_dwordx2 v[8:9], v[84:85], off offset:256
	v_pk_mul_f32 v[80:81], v[80:81], s[4:5] op_sel_hi:[1,0]
	v_pk_mul_f32 v[78:79], v[78:79], s[4:5] op_sel_hi:[1,0]
	v_pk_mul_f32 v[82:83], v[74:75], v[104:105]
	v_pk_mul_f32 v[84:85], v[76:77], v[108:109]
	v_pk_fma_f32 v[82:83], v[78:79], v[102:103], v[82:83] neg_lo:[0,0,1] neg_hi:[0,0,1]
	v_pk_fma_f32 v[84:85], v[80:81], v[106:107], v[84:85] neg_lo:[0,0,1] neg_hi:[0,0,1]
	v_pk_mul_f32 v[78:79], v[78:79], v[104:105]
	v_pk_mul_f32 v[80:81], v[80:81], v[108:109]
	v_cvt_pk_f16_f32 v95, v116, v117
	v_cvt_pk_f16_f32 v94, v114, v115
	v_pk_fma_f32 v[76:77], v[76:77], v[106:107], v[80:81]
	v_pk_fma_f32 v[74:75], v[74:75], v[102:103], v[78:79]
	v_cvt_pk_f16_f32 v79, v84, v85
	v_cvt_pk_f16_f32 v78, v82, v83
	global_store_dwordx2 v[2:3], v[94:95], off offset:256
	global_store_dwordx2 v[2:3], v[78:79], off offset:288
	v_cvt_pk_f16_f32 v3, v76, v77
	v_cvt_pk_f16_f32 v2, v74, v75
	v_pk_mul_f32 v[68:69], v[68:69], s[4:5] op_sel_hi:[1,0]
	v_pk_mul_f32 v[66:67], v[66:67], s[4:5] op_sel_hi:[1,0]
	global_store_dwordx2 v[4:5], v[2:3], off offset:288
	v_pk_mul_f32 v[2:3], v[72:73], s[4:5] op_sel_hi:[1,0]
	v_pk_mul_f32 v[4:5], v[70:71], s[4:5] op_sel_hi:[1,0]
	v_pk_mul_f32 v[70:71], v[66:67], v[100:101]
	v_pk_mul_f32 v[72:73], v[68:69], v[112:113]
	v_pk_fma_f32 v[70:71], v[4:5], v[0:1], v[70:71] neg_lo:[0,0,1] neg_hi:[0,0,1]
	v_pk_fma_f32 v[72:73], v[2:3], v[110:111], v[72:73] neg_lo:[0,0,1] neg_hi:[0,0,1]
	v_pk_mul_f32 v[4:5], v[4:5], v[100:101]
	v_pk_mul_f32 v[2:3], v[2:3], v[112:113]
	v_pk_fma_f32 v[4:5], v[66:67], v[0:1], v[4:5]
	v_pk_fma_f32 v[2:3], v[68:69], v[110:111], v[2:3]
	v_cvt_pk_f16_f32 v87, v92, v93
	v_cvt_pk_f16_f32 v86, v90, v91
	v_cvt_pk_f16_f32 v67, v72, v73
	v_cvt_pk_f16_f32 v66, v70, v71
	v_cvt_pk_f16_f32 v3, v2, v3
	v_cvt_pk_f16_f32 v2, v4, v5
	global_store_dwordx2 v[6:7], v[86:87], off offset:256
	global_store_dwordx2 v[6:7], v[66:67], off offset:288
	global_store_dwordx2 v[8:9], v[2:3], off offset:288
	v_pk_mul_f32 v[6:7], v[60:61], s[4:5] op_sel_hi:[1,0]
	v_pk_mul_f32 v[8:9], v[58:59], s[4:5] op_sel_hi:[1,0]
	v_pk_mul_f32 v[2:3], v[64:65], s[4:5] op_sel_hi:[1,0]
	v_pk_mul_f32 v[4:5], v[62:63], s[4:5] op_sel_hi:[1,0]
	v_pk_mul_f32 v[58:59], v[8:9], v[24:25]
	v_pk_mul_f32 v[60:61], v[6:7], v[28:29]
	v_pk_fma_f32 v[58:59], v[4:5], v[22:23], v[58:59] neg_lo:[0,0,1] neg_hi:[0,0,1]
	v_pk_fma_f32 v[60:61], v[2:3], v[26:27], v[60:61] neg_lo:[0,0,1] neg_hi:[0,0,1]
	v_pk_mul_f32 v[4:5], v[4:5], v[24:25]
	v_pk_mul_f32 v[2:3], v[2:3], v[28:29]
	v_pk_fma_f32 v[4:5], v[8:9], v[22:23], v[4:5]
	v_pk_fma_f32 v[2:3], v[6:7], v[26:27], v[2:3]
	v_cvt_pk_f16_f32 v7, v60, v61
	v_cvt_pk_f16_f32 v6, v58, v59
	global_store_dwordx2 v[10:11], v[6:7], off offset:256
	v_cvt_pk_f16_f32 v3, v2, v3
	v_cvt_pk_f16_f32 v2, v4, v5
	v_pk_mul_f32 v[6:7], v[52:53], s[4:5] op_sel_hi:[1,0]
	v_pk_mul_f32 v[8:9], v[50:51], s[4:5] op_sel_hi:[1,0]
	global_store_dwordx2 v[12:13], v[2:3], off offset:256
	v_pk_mul_f32 v[2:3], v[56:57], s[4:5] op_sel_hi:[1,0]
	v_pk_mul_f32 v[4:5], v[54:55], s[4:5] op_sel_hi:[1,0]
	v_pk_mul_f32 v[22:23], v[8:9], v[20:21]
	v_pk_mul_f32 v[24:25], v[6:7], v[98:99]
	v_pk_fma_f32 v[22:23], v[4:5], v[18:19], v[22:23] neg_lo:[0,0,1] neg_hi:[0,0,1]
	v_pk_fma_f32 v[24:25], v[2:3], v[30:31], v[24:25] neg_lo:[0,0,1] neg_hi:[0,0,1]
	v_pk_mul_f32 v[4:5], v[4:5], v[20:21]
	v_pk_mul_f32 v[2:3], v[2:3], v[98:99]
	v_pk_fma_f32 v[4:5], v[8:9], v[18:19], v[4:5]
	v_pk_fma_f32 v[2:3], v[6:7], v[30:31], v[2:3]
	v_cvt_pk_f16_f32 v7, v24, v25
	v_cvt_pk_f16_f32 v6, v22, v23
	global_store_dwordx2 v[14:15], v[6:7], off offset:256
	v_cvt_pk_f16_f32 v3, v2, v3
	v_cvt_pk_f16_f32 v2, v4, v5
	v_pk_mul_f32 v[6:7], v[44:45], s[4:5] op_sel_hi:[1,0]
	v_pk_mul_f32 v[8:9], v[42:43], s[4:5] op_sel_hi:[1,0]
	global_store_dwordx2 v[16:17], v[2:3], off offset:256
	v_pk_mul_f32 v[2:3], v[48:49], s[4:5] op_sel_hi:[1,0]
	v_pk_mul_f32 v[4:5], v[46:47], s[4:5] op_sel_hi:[1,0]
	v_pk_mul_f32 v[18:19], v[8:9], v[104:105]
	v_pk_mul_f32 v[20:21], v[6:7], v[108:109]
	v_pk_fma_f32 v[18:19], v[4:5], v[102:103], v[18:19] neg_lo:[0,0,1] neg_hi:[0,0,1]
	v_pk_fma_f32 v[20:21], v[2:3], v[106:107], v[20:21] neg_lo:[0,0,1] neg_hi:[0,0,1]
	v_pk_mul_f32 v[4:5], v[4:5], v[104:105]
	v_pk_mul_f32 v[2:3], v[2:3], v[108:109]
	v_pk_fma_f32 v[4:5], v[8:9], v[102:103], v[4:5]
	v_pk_fma_f32 v[2:3], v[6:7], v[106:107], v[2:3]
	v_cvt_pk_f16_f32 v7, v20, v21
	v_cvt_pk_f16_f32 v6, v18, v19
	global_store_dwordx2 v[10:11], v[6:7], off offset:288
	v_cvt_pk_f16_f32 v3, v2, v3
	v_cvt_pk_f16_f32 v2, v4, v5
	v_pk_mul_f32 v[6:7], v[36:37], s[4:5] op_sel_hi:[1,0]
	v_pk_mul_f32 v[8:9], v[34:35], s[4:5] op_sel_hi:[1,0]
	global_store_dwordx2 v[12:13], v[2:3], off offset:288
	v_pk_mul_f32 v[2:3], v[40:41], s[4:5] op_sel_hi:[1,0]
	v_pk_mul_f32 v[4:5], v[38:39], s[4:5] op_sel_hi:[1,0]
	v_pk_mul_f32 v[10:11], v[8:9], v[100:101]
	v_pk_mul_f32 v[12:13], v[6:7], v[112:113]
	v_pk_fma_f32 v[10:11], v[4:5], v[0:1], v[10:11] neg_lo:[0,0,1] neg_hi:[0,0,1]
	v_pk_fma_f32 v[12:13], v[2:3], v[110:111], v[12:13] neg_lo:[0,0,1] neg_hi:[0,0,1]
	v_pk_mul_f32 v[4:5], v[4:5], v[100:101]
	v_pk_mul_f32 v[2:3], v[2:3], v[112:113]
	v_pk_fma_f32 v[0:1], v[8:9], v[0:1], v[4:5]
	v_pk_fma_f32 v[2:3], v[6:7], v[110:111], v[2:3]
	v_cvt_pk_f16_f32 v5, v12, v13
	v_cvt_pk_f16_f32 v4, v10, v11
	v_cvt_pk_f16_f32 v3, v2, v3
	v_cvt_pk_f16_f32 v2, v0, v1
	global_store_dwordx2 v[14:15], v[4:5], off offset:288
	global_store_dwordx2 v[16:17], v[2:3], off offset:288
.LBB0_391:
	s_cmp_eq_u32 s50, 0
	s_cbranch_scc1 .Lepib_inp_nb
	s_mov_b32 s50, 0
	s_barrier
.Lepib_inp_nb:
	s_and_b64 vcc, exec, s[12:13]
	s_cbranch_vccnz .LBB0_451

.LBB0_403:
	s_add_u32 s14, s4, 0x100
	s_addc_u32 s15, s5, 0
	s_add_i32 s38, 0, 0x10000
	v_add_u32_e32 v12, s38, v193
	ds_read_b128 v[0:3], v12
	ds_read_b128 v[8:11], v12 offset:2048
	ds_read_b128 v[4:7], v12 offset:1024
	ds_read_b128 v[12:15], v12 offset:3072
	s_cmp_eq_u32 s37, 12
	s_cselect_b32 s19, s9, s15
	s_cselect_b32 s18, s8, s14
	s_cselect_b32 s17, s11, s36
	s_cselect_b32 s16, s10, s7
	v_lshl_add_u64 v[190:191], s[4:5], 0, v[186:187]
	s_add_i32 m0, s23, 0xc000
	ds_read_b128 v[16:19], v206
	ds_read_b128 v[24:27], v206 offset:2048
	ds_read_b128 v[162:165], v206 offset:4096
	ds_read_b128 v[170:173], v206 offset:6144
	ds_read_b128 v[20:23], v206 offset:1024
	ds_read_b128 v[28:31], v206 offset:3072
	ds_read_b128 v[166:169], v206 offset:5120
	ds_read_b128 v[174:177], v206 offset:7168
	global_load_lds_dwordx4 v[190:191], off
	v_lshl_add_u64 v[190:191], s[4:5], 0, v[188:189]
	s_add_i32 m0, s23, 0xe000
	s_nop 0
	global_load_lds_dwordx4 v[190:191], off
	s_waitcnt lgkmcnt(8)
	s_barrier
	s_waitcnt lgkmcnt(7)
	s_setprio 1
	v_mfma_f32_16x16x32_f16 v[158:161], v[0:3], v[16:19], v[158:161]
	v_mfma_f32_16x16x32_f16 v[142:145], v[8:11], v[16:19], v[142:145]
	s_waitcnt lgkmcnt(6)
	v_mfma_f32_16x16x32_f16 v[150:153], v[0:3], v[24:27], v[150:153]
	v_mfma_f32_16x16x32_f16 v[134:137], v[8:11], v[24:27], v[134:137]
	s_waitcnt lgkmcnt(5)
	v_mfma_f32_16x16x32_f16 v[154:157], v[0:3], v[162:165], v[154:157]
	v_mfma_f32_16x16x32_f16 v[138:141], v[8:11], v[162:165], v[138:141]
	s_waitcnt lgkmcnt(4)
	v_mfma_f32_16x16x32_f16 v[146:149], v[0:3], v[170:173], v[146:149]
	v_mfma_f32_16x16x32_f16 v[130:133], v[8:11], v[170:173], v[130:133]
	s_waitcnt lgkmcnt(3)
	v_mfma_f32_16x16x32_f16 v[158:161], v[4:7], v[20:23], v[158:161]
	v_mfma_f32_16x16x32_f16 v[142:145], v[12:15], v[20:23], v[142:145]
	s_waitcnt lgkmcnt(2)
	v_mfma_f32_16x16x32_f16 v[150:153], v[4:7], v[28:31], v[150:153]
	v_mfma_f32_16x16x32_f16 v[134:137], v[12:15], v[28:31], v[134:137]
	s_waitcnt lgkmcnt(1)
	v_mfma_f32_16x16x32_f16 v[154:157], v[4:7], v[166:169], v[154:157]
	v_mfma_f32_16x16x32_f16 v[138:141], v[12:15], v[166:169], v[138:141]
	s_waitcnt lgkmcnt(0)
	v_mfma_f32_16x16x32_f16 v[146:149], v[4:7], v[174:177], v[146:149]
	v_mfma_f32_16x16x32_f16 v[130:133], v[12:15], v[174:177], v[130:133]
	s_setprio 0
	s_barrier
	s_add_i32 s39, 0, 0x14000
	s_add_i32 s4, s38, s22
	v_add_u32_e32 v32, s39, v193
	v_lshl_add_u64 v[190:191], s[16:17], 0, v[178:179]
	s_mov_b32 m0, s4
	ds_read_b128 v[208:211], v32
	ds_read_b128 v[216:219], v32 offset:2048
	ds_read_b128 v[212:215], v32 offset:1024
	ds_read_b128 v[230:233], v32 offset:3072
	global_load_lds_dwordx4 v[190:191], off
	v_lshl_add_u64 v[238:239], s[16:17], 0, v[180:181]
	s_add_i32 m0, s4, 0x2000
	s_nop 0
	global_load_lds_dwordx4 v[238:239], off
	s_barrier
	s_waitcnt lgkmcnt(2)
	s_setprio 1
	v_mfma_f32_16x16x32_f16 v[94:97], v[208:211], v[16:19], v[94:97]
	v_mfma_f32_16x16x32_f16 v[16:19], v[216:219], v[16:19], v[78:81]
	s_waitcnt lgkmcnt(0)
	v_mfma_f32_16x16x32_f16 v[94:97], v[212:215], v[20:23], v[94:97]
	v_mfma_f32_16x16x32_f16 v[16:19], v[230:233], v[20:23], v[16:19]
	v_mfma_f32_16x16x32_f16 v[20:23], v[208:211], v[24:27], v[86:89]
	v_mfma_f32_16x16x32_f16 v[24:27], v[216:219], v[24:27], v[70:73]
	v_mfma_f32_16x16x32_f16 v[70:73], v[216:219], v[162:165], v[74:77]
	v_mfma_f32_16x16x32_f16 v[74:77], v[230:233], v[166:169], v[70:73]
	v_mfma_f32_16x16x32_f16 v[70:73], v[208:211], v[170:173], v[82:85]
	v_mfma_f32_16x16x32_f16 v[66:69], v[216:219], v[170:173], v[66:69]
	v_mfma_f32_16x16x32_f16 v[20:23], v[212:215], v[28:31], v[20:23]
	v_mfma_f32_16x16x32_f16 v[24:27], v[230:233], v[28:31], v[24:27]
	v_mfma_f32_16x16x32_f16 v[28:31], v[208:211], v[162:165], v[90:93]
	v_mfma_f32_16x16x32_f16 v[82:85], v[212:215], v[174:177], v[70:73]
	v_mfma_f32_16x16x32_f16 v[66:69], v[230:233], v[174:177], v[66:69]
	v_mfma_f32_16x16x32_f16 v[28:31], v[212:215], v[166:169], v[28:31]
	s_setprio 0
	s_mov_b32 m0, s23
	v_lshl_add_u64 v[240:241], s[18:19], 0, v[178:179]
	s_barrier
	ds_read_b128 v[70:73], v206 offset:16384
	ds_read_b128 v[86:89], v206 offset:18432
	ds_read_b128 v[162:165], v206 offset:20480
	ds_read_b128 v[170:173], v206 offset:22528
	ds_read_b128 v[78:81], v206 offset:17408
	ds_read_b128 v[90:93], v206 offset:19456
	ds_read_b128 v[166:169], v206 offset:21504
	ds_read_b128 v[174:177], v206 offset:23552
	global_load_lds_dwordx4 v[240:241], off
	v_lshl_add_u64 v[242:243], s[18:19], 0, v[180:181]
	s_mov_b32 m0, s24
	s_nop 0
	global_load_lds_dwordx4 v[242:243], off
	s_barrier
	s_waitcnt lgkmcnt(7)
	s_setprio 1
	v_mfma_f32_16x16x32_f16 v[126:129], v[0:3], v[70:73], v[126:129]
	v_mfma_f32_16x16x32_f16 v[110:113], v[8:11], v[70:73], v[110:113]
	s_waitcnt lgkmcnt(6)
	v_mfma_f32_16x16x32_f16 v[118:121], v[0:3], v[86:89], v[118:121]
	v_mfma_f32_16x16x32_f16 v[102:105], v[8:11], v[86:89], v[102:105]
	s_waitcnt lgkmcnt(5)
	v_mfma_f32_16x16x32_f16 v[122:125], v[0:3], v[162:165], v[122:125]
	v_mfma_f32_16x16x32_f16 v[106:109], v[8:11], v[162:165], v[106:109]
	s_waitcnt lgkmcnt(3)
	v_mfma_f32_16x16x32_f16 v[0:3], v[0:3], v[170:173], v[114:117]
	v_mfma_f32_16x16x32_f16 v[126:129], v[4:7], v[78:81], v[126:129]
	s_waitcnt lgkmcnt(2)
	v_mfma_f32_16x16x32_f16 v[110:113], v[12:15], v[78:81], v[110:113]
	v_mfma_f32_16x16x32_f16 v[118:121], v[4:7], v[90:93], v[118:121]
	s_waitcnt lgkmcnt(1)
	v_mfma_f32_16x16x32_f16 v[102:105], v[12:15], v[90:93], v[102:105]
	v_mfma_f32_16x16x32_f16 v[122:125], v[4:7], v[166:169], v[122:125]
	s_waitcnt lgkmcnt(0)
	v_mfma_f32_16x16x32_f16 v[106:109], v[12:15], v[166:169], v[106:109]
	v_mfma_f32_16x16x32_f16 v[0:3], v[4:7], v[174:177], v[0:3]
	v_mfma_f32_16x16x32_f16 v[4:7], v[8:11], v[170:173], v[98:101]
	v_mfma_f32_16x16x32_f16 v[4:7], v[12:15], v[174:177], v[4:7]
	s_setprio 0
	s_barrier
	s_add_u32 s4, s16, 0x40000
	s_addc_u32 s5, s17, 0
	s_add_i32 s38, s39, s22
	v_lshl_add_u64 v[8:9], s[4:5], 0, v[178:179]
	s_mov_b32 m0, s38
	s_nop 0
	global_load_lds_dwordx4 v[8:9], off
	v_lshl_add_u64 v[8:9], s[4:5], 0, v[180:181]
	s_add_i32 m0, s38, 0x2000
	s_nop 0
	global_load_lds_dwordx4 v[8:9], off
	s_waitcnt vmcnt(6)
	s_barrier
	s_setprio 1
	v_mfma_f32_16x16x32_f16 v[12:15], v[216:219], v[70:73], v[46:49]
	v_mfma_f32_16x16x32_f16 v[46:49], v[208:211], v[86:89], v[54:57]
	v_mfma_f32_16x16x32_f16 v[54:57], v[212:215], v[90:93], v[46:49]
	v_mfma_f32_16x16x32_f16 v[46:49], v[208:211], v[162:165], v[58:61]
	v_mfma_f32_16x16x32_f16 v[38:41], v[216:219], v[86:89], v[38:41]
	v_mfma_f32_16x16x32_f16 v[58:61], v[212:215], v[166:169], v[46:49]
	v_mfma_f32_16x16x32_f16 v[42:45], v[216:219], v[162:165], v[42:45]
	v_mfma_f32_16x16x32_f16 v[46:49], v[208:211], v[170:173], v[50:53]
	v_mfma_f32_16x16x32_f16 v[34:37], v[216:219], v[170:173], v[34:37]
	v_mfma_f32_16x16x32_f16 v[8:11], v[208:211], v[70:73], v[62:65]
	v_mfma_f32_16x16x32_f16 v[38:41], v[230:233], v[90:93], v[38:41]
	v_mfma_f32_16x16x32_f16 v[42:45], v[230:233], v[166:169], v[42:45]
	v_mfma_f32_16x16x32_f16 v[50:53], v[212:215], v[174:177], v[46:49]
	v_mfma_f32_16x16x32_f16 v[34:37], v[230:233], v[174:177], v[34:37]
	v_mfma_f32_16x16x32_f16 v[8:11], v[212:215], v[78:81], v[8:11]
	v_mfma_f32_16x16x32_f16 v[12:15], v[230:233], v[78:81], v[12:15]
	s_setprio 0
	s_add_i32 s38, 0, 0x18000
	v_add_u32_e32 v32, s38, v193
	s_barrier
	ds_read_b128 v[46:49], v32
	ds_read_b128 v[62:65], v32 offset:1024
	ds_read_b128 v[98:101], v32 offset:2048
	ds_read_b128 v[162:165], v32 offset:3072
	s_add_u32 s4, s18, 0x40000
	s_addc_u32 s5, s19, 0
	s_mov_b32 m0, s25
	v_lshl_add_u64 v[86:87], s[4:5], 0, v[178:179]
	ds_read_b128 v[70:73], v206 offset:32768
	ds_read_b128 v[78:81], v206 offset:33792
	ds_read_b128 v[90:93], v206 offset:34816
	ds_read_b128 v[114:117], v206 offset:35840
	ds_read_b128 v[166:169], v206 offset:36864
	ds_read_b128 v[170:173], v206 offset:37888
	ds_read_b128 v[174:177], v206 offset:38912
	ds_read_b128 v[208:211], v206 offset:39936
	global_load_lds_dwordx4 v[86:87], off
	v_lshl_add_u64 v[86:87], s[4:5], 0, v[180:181]
	s_mov_b32 m0, s26
	s_nop 0
	global_load_lds_dwordx4 v[86:87], off
	s_waitcnt lgkmcnt(8)
	s_barrier
	s_waitcnt lgkmcnt(6)
	s_setprio 1
	v_mfma_f32_16x16x32_f16 v[86:89], v[46:49], v[70:73], v[158:161]
	v_mfma_f32_16x16x32_f16 v[158:161], v[62:65], v[78:81], v[86:89]
	v_mfma_f32_16x16x32_f16 v[86:89], v[98:101], v[70:73], v[142:145]
	v_mfma_f32_16x16x32_f16 v[142:145], v[162:165], v[78:81], v[86:89]
	s_waitcnt lgkmcnt(4)
	v_mfma_f32_16x16x32_f16 v[86:89], v[46:49], v[90:93], v[150:153]
	v_mfma_f32_16x16x32_f16 v[150:153], v[62:65], v[114:117], v[86:89]
	v_mfma_f32_16x16x32_f16 v[86:89], v[98:101], v[90:93], v[134:137]
	v_mfma_f32_16x16x32_f16 v[134:137], v[162:165], v[114:117], v[86:89]
	s_waitcnt lgkmcnt(2)
	v_mfma_f32_16x16x32_f16 v[86:89], v[46:49], v[166:169], v[154:157]
	v_mfma_f32_16x16x32_f16 v[154:157], v[62:65], v[170:173], v[86:89]
	v_mfma_f32_16x16x32_f16 v[86:89], v[98:101], v[166:169], v[138:141]
	v_mfma_f32_16x16x32_f16 v[138:141], v[162:165], v[170:173], v[86:89]
	s_waitcnt lgkmcnt(0)
	v_mfma_f32_16x16x32_f16 v[86:89], v[46:49], v[174:177], v[146:149]
	v_mfma_f32_16x16x32_f16 v[146:149], v[62:65], v[208:211], v[86:89]
	v_mfma_f32_16x16x32_f16 v[86:89], v[98:101], v[174:177], v[130:133]
	v_mfma_f32_16x16x32_f16 v[130:133], v[162:165], v[208:211], v[86:89]
	s_setprio 0
	s_barrier
	s_add_i32 s18, 0, 0x1c000
	s_add_i32 s4, s38, s22
	v_add_u32_e32 v32, s18, v193
	s_nop 1
	v_lshl_add_u64 v[86:87], v[190:191], 0, s[84:85]
	s_mov_b32 m0, s4
	ds_read_b128 v[212:215], v32
	ds_read_b128 v[230:233], v32 offset:2048
	ds_read_b128 v[216:219], v32 offset:1024
	ds_read_b128 v[234:237], v32 offset:3072
	global_load_lds_dwordx4 v[86:87], off
	v_lshl_add_u64 v[86:87], v[238:239], 0, s[84:85]
	s_add_i32 m0, s4, 0x2000
	s_nop 0
	global_load_lds_dwordx4 v[86:87], off
	s_barrier
	s_waitcnt lgkmcnt(2)
	s_setprio 1
	v_mfma_f32_16x16x32_f16 v[86:89], v[212:215], v[70:73], v[94:97]
	v_mfma_f32_16x16x32_f16 v[16:19], v[230:233], v[70:73], v[16:19]
	s_waitcnt lgkmcnt(0)
	v_mfma_f32_16x16x32_f16 v[94:97], v[216:219], v[78:81], v[86:89]
	v_mfma_f32_16x16x32_f16 v[78:81], v[234:237], v[78:81], v[16:19]
	v_mfma_f32_16x16x32_f16 v[16:19], v[212:215], v[90:93], v[20:23]
	v_mfma_f32_16x16x32_f16 v[86:89], v[216:219], v[114:117], v[16:19]
	v_mfma_f32_16x16x32_f16 v[16:19], v[230:233], v[90:93], v[24:27]
	v_mfma_f32_16x16x32_f16 v[70:73], v[234:237], v[114:117], v[16:19]
	v_mfma_f32_16x16x32_f16 v[16:19], v[212:215], v[166:169], v[28:31]
	v_mfma_f32_16x16x32_f16 v[90:93], v[216:219], v[170:173], v[16:19]
	v_mfma_f32_16x16x32_f16 v[16:19], v[230:233], v[166:169], v[74:77]
	v_mfma_f32_16x16x32_f16 v[74:77], v[234:237], v[170:173], v[16:19]
	v_mfma_f32_16x16x32_f16 v[16:19], v[212:215], v[174:177], v[82:85]
	v_mfma_f32_16x16x32_f16 v[82:85], v[216:219], v[208:211], v[16:19]
	v_mfma_f32_16x16x32_f16 v[16:19], v[230:233], v[174:177], v[66:69]
	v_mfma_f32_16x16x32_f16 v[66:69], v[234:237], v[208:211], v[16:19]
	s_setprio 0
	s_mov_b32 m0, s28
	v_lshl_add_u64 v[114:115], v[240:241], 0, s[84:85]
	s_barrier
	s_nop 2
	ds_read_b128 v[16:19], v206 offset:49152
	ds_read_b128 v[20:23], v206 offset:50176
	ds_read_b128 v[24:27], v206 offset:51200
	ds_read_b128 v[28:31], v206 offset:52224
	ds_read_b128 v[166:169], v206 offset:53248
	ds_read_b128 v[174:177], v206 offset:55296
	ds_read_b128 v[170:173], v206 offset:54272
	ds_read_b128 v[208:211], v206 offset:56320
	global_load_lds_dwordx4 v[114:115], off
	v_lshl_add_u64 v[114:115], v[242:243], 0, s[84:85]
	s_mov_b32 m0, s29
	s_nop 0
	global_load_lds_dwordx4 v[114:115], off
	s_barrier
	s_waitcnt lgkmcnt(6)
	s_setprio 1
	v_mfma_f32_16x16x32_f16 v[114:117], v[46:49], v[16:19], v[126:129]
	v_mfma_f32_16x16x32_f16 v[126:129], v[62:65], v[20:23], v[114:117]
	s_waitcnt lgkmcnt(4)
	v_mfma_f32_16x16x32_f16 v[114:117], v[46:49], v[24:27], v[118:121]
	v_mfma_f32_16x16x32_f16 v[118:121], v[62:65], v[28:31], v[114:117]
	s_waitcnt lgkmcnt(2)
	v_mfma_f32_16x16x32_f16 v[114:117], v[46:49], v[166:169], v[122:125]
	v_mfma_f32_16x16x32_f16 v[0:3], v[46:49], v[174:177], v[0:3]
	v_mfma_f32_16x16x32_f16 v[110:113], v[98:101], v[16:19], v[110:113]
	v_mfma_f32_16x16x32_f16 v[102:105], v[98:101], v[24:27], v[102:105]
	s_waitcnt lgkmcnt(1)
	v_mfma_f32_16x16x32_f16 v[122:125], v[62:65], v[170:173], v[114:117]
	v_mfma_f32_16x16x32_f16 v[106:109], v[98:101], v[166:169], v[106:109]
	s_waitcnt lgkmcnt(0)
	v_mfma_f32_16x16x32_f16 v[114:117], v[62:65], v[208:211], v[0:3]
	v_mfma_f32_16x16x32_f16 v[0:3], v[98:101], v[174:177], v[4:7]
	v_mfma_f32_16x16x32_f16 v[110:113], v[162:165], v[20:23], v[110:113]
	v_mfma_f32_16x16x32_f16 v[102:105], v[162:165], v[28:31], v[102:105]
	v_mfma_f32_16x16x32_f16 v[106:109], v[162:165], v[170:173], v[106:109]
	v_mfma_f32_16x16x32_f16 v[98:101], v[162:165], v[208:211], v[0:3]
	s_setprio 0
	s_barrier
	s_add_u32 s4, s16, 0x40080
	s_addc_u32 s5, s17, 0
	s_add_i32 s16, s18, s22
	v_lshl_add_u64 v[0:1], s[4:5], 0, v[178:179]
	s_mov_b32 m0, s16
	s_nop 0
	global_load_lds_dwordx4 v[0:1], off
	v_lshl_add_u64 v[0:1], s[4:5], 0, v[180:181]
	s_add_i32 m0, s16, 0x2000
	s_nop 0
	global_load_lds_dwordx4 v[0:1], off
	s_waitcnt vmcnt(6)
	s_barrier
	s_setprio 1
	v_mfma_f32_16x16x32_f16 v[0:3], v[212:215], v[16:19], v[8:11]
	v_mfma_f32_16x16x32_f16 v[62:65], v[216:219], v[20:23], v[0:3]
	v_mfma_f32_16x16x32_f16 v[0:3], v[230:233], v[16:19], v[12:15]
	v_mfma_f32_16x16x32_f16 v[46:49], v[234:237], v[20:23], v[0:3]
	v_mfma_f32_16x16x32_f16 v[0:3], v[212:215], v[24:27], v[54:57]
	v_mfma_f32_16x16x32_f16 v[54:57], v[216:219], v[28:31], v[0:3]
	v_mfma_f32_16x16x32_f16 v[0:3], v[230:233], v[24:27], v[38:41]
	v_mfma_f32_16x16x32_f16 v[38:41], v[234:237], v[28:31], v[0:3]
	v_mfma_f32_16x16x32_f16 v[0:3], v[212:215], v[166:169], v[58:61]
	v_mfma_f32_16x16x32_f16 v[58:61], v[216:219], v[170:173], v[0:3]
	v_mfma_f32_16x16x32_f16 v[0:3], v[230:233], v[166:169], v[42:45]
	v_mfma_f32_16x16x32_f16 v[42:45], v[234:237], v[170:173], v[0:3]
	v_mfma_f32_16x16x32_f16 v[0:3], v[212:215], v[174:177], v[50:53]
	v_mfma_f32_16x16x32_f16 v[50:53], v[216:219], v[208:211], v[0:3]
	v_mfma_f32_16x16x32_f16 v[0:3], v[230:233], v[174:177], v[34:37]
	v_mfma_f32_16x16x32_f16 v[34:37], v[234:237], v[208:211], v[0:3]
	s_setprio 0
	s_add_i32 s37, s37, 2
	s_add_u32 s7, s7, 0x100
	s_addc_u32 s36, s36, 0
	s_cmp_gt_u32 s37, 13
	s_mov_b64 s[4:5], s[14:15]
	s_cbranch_scc0 .Lepib_inp_bar
	v_readlane_b32 s51, v251, 36
	s_cmp_gt_u32 s51, 3
	s_cbranch_scc0 .Lepib_inp_barx
	s_mov_b32 s50, 1
	s_branch .Lepib_inp_exit

.Lepib_inp_exit:
.Lpeelx0:
	s_lshl_b32 s7, s34, 8
	s_cmp_lt_i32 s35, 28
	s_mov_b64 s[4:5], -1
	s_cbranch_scc0 .LBB0_431
	s_add_i32 s16, s7, s27
	v_or_b32_e32 v207, s16, v192
	s_cmp_gt_i32 s35, 3
	s_cbranch_scc0 .LBB0_411
	s_add_i32 s4, s35, -12
	s_cmp_gt_u32 s4, 7
	s_mov_b64 s[4:5], -1
	s_cbranch_scc0 .LBB0_408
	s_lshl_b32 s4, s35, 8
	s_add_i32 s5, s4, 0xfffffc00
	s_cmp_lt_u32 s35, 12
	s_cselect_b32 s4, s4, s5
	v_and_b32_e32 v10, 7, v220
	v_and_b32_e32 v11, 8, v220
	v_cmp_ne_u32_e32 vcc, 0, v11
	v_and_b32_e32 v12, 0x60, v194
	v_lshlrev_b32_e32 v12, 1, v12
	v_lshl_or_b32 v12, v11, 2, v12
	v_and_b32_e32 v13, 0x18, v194
	v_or_b32_e32 v12, v12, v13
	v_or_b32_e32 v32, s4, v12
	v_or_b32_e32 v14, s16, v10
	v_mov_b64_e32 v[4:5], s[70:71]
	v_mad_i64_i32 v[0:1], s[4:5], v14, s33, v[4:5]
	v_lshlrev_b64 v[6:7], 1, v[32:33]
	v_lshl_add_u64 v[16:17], v[0:1], 0, v[6:7]
	v_mov_b32_e32 v32, 0x30000
	v_lshl_add_u64 v[18:19], v[16:17], 0, v[32:33]
	v_lshl_add_u64 v[20:21], v[18:19], 0, v[32:33]
	v_lshl_add_u64 v[22:23], v[20:21], 0, v[32:33]
	v_mov_b32_e32 v8, 0x180000
	v_mov_b32_e32 v9, 0
	v_lshl_add_u64 v[24:25], v[16:17], 0, v[8:9]
	v_lshl_add_u64 v[26:27], v[24:25], 0, v[32:33]
	v_lshl_add_u64 v[28:29], v[26:27], 0, v[32:33]
	v_lshl_add_u64 v[30:31], v[28:29], 0, v[32:33]
	v_mov_b32_e32 v8, 0x18000
	v_cvt_pk_f16_f32 v158, v158, v159
	v_cvt_pk_f16_f32 v159, v160, v161
	v_cvt_pk_f16_f32 v160, v142, v143
	v_cvt_pk_f16_f32 v161, v144, v145
	v_cvt_pk_f16_f32 v94, v94, v95
	v_cvt_pk_f16_f32 v95, v96, v97
	v_cvt_pk_f16_f32 v96, v78, v79
	v_cvt_pk_f16_f32 v97, v80, v81
	v_mov_b32_dpp v0, v158 row_ror:8 row_mask:0xf bank_mask:0xf
	v_mov_b32_dpp v1, v159 row_ror:8 row_mask:0xf bank_mask:0xf
	v_mov_b32_dpp v2, v160 row_ror:8 row_mask:0xf bank_mask:0xf
	v_mov_b32_dpp v3, v161 row_ror:8 row_mask:0xf bank_mask:0xf
	v_mov_b32_dpp v4, v94 row_ror:8 row_mask:0xf bank_mask:0xf
	v_mov_b32_dpp v5, v95 row_ror:8 row_mask:0xf bank_mask:0xf
	v_mov_b32_dpp v6, v96 row_ror:8 row_mask:0xf bank_mask:0xf
	v_mov_b32_dpp v7, v97 row_ror:8 row_mask:0xf bank_mask:0xf
	v_cndmask_b32_e32 v158, v158, v4, vcc
	v_cndmask_b32_e32 v159, v159, v5, vcc
	v_cndmask_b32_e32 v160, v160, v6, vcc
	v_cndmask_b32_e32 v161, v161, v7, vcc
	v_cndmask_b32_e32 v94, v0, v94, vcc
	v_cndmask_b32_e32 v95, v1, v95, vcc
	v_cndmask_b32_e32 v96, v2, v96, vcc
	v_cndmask_b32_e32 v97, v3, v97, vcc
	v_lshl_add_u64 v[10:11], v[16:17], 0, v[8:9]
	global_store_dwordx4 v[16:17], v[158:161], off
	global_store_dwordx4 v[10:11], v[94:97], off
	v_cvt_pk_f16_f32 v150, v150, v151
	v_cvt_pk_f16_f32 v151, v152, v153
	v_cvt_pk_f16_f32 v152, v134, v135
	v_cvt_pk_f16_f32 v153, v136, v137
	v_cvt_pk_f16_f32 v86, v86, v87
	v_cvt_pk_f16_f32 v87, v88, v89
	v_cvt_pk_f16_f32 v88, v70, v71
	v_cvt_pk_f16_f32 v89, v72, v73
	v_mov_b32_dpp v0, v150 row_ror:8 row_mask:0xf bank_mask:0xf
	v_mov_b32_dpp v1, v151 row_ror:8 row_mask:0xf bank_mask:0xf
	v_mov_b32_dpp v2, v152 row_ror:8 row_mask:0xf bank_mask:0xf
	v_mov_b32_dpp v3, v153 row_ror:8 row_mask:0xf bank_mask:0xf
	v_mov_b32_dpp v4, v86 row_ror:8 row_mask:0xf bank_mask:0xf
	v_mov_b32_dpp v5, v87 row_ror:8 row_mask:0xf bank_mask:0xf
	v_mov_b32_dpp v6, v88 row_ror:8 row_mask:0xf bank_mask:0xf
	v_mov_b32_dpp v7, v89 row_ror:8 row_mask:0xf bank_mask:0xf
	v_cndmask_b32_e32 v150, v150, v4, vcc
	v_cndmask_b32_e32 v151, v151, v5, vcc
	v_cndmask_b32_e32 v152, v152, v6, vcc
	v_cndmask_b32_e32 v153, v153, v7, vcc
	v_cndmask_b32_e32 v86, v0, v86, vcc
	v_cndmask_b32_e32 v87, v1, v87, vcc
	v_cndmask_b32_e32 v88, v2, v88, vcc
	v_cndmask_b32_e32 v89, v3, v89, vcc
	v_lshl_add_u64 v[10:11], v[18:19], 0, v[8:9]
	global_store_dwordx4 v[18:19], v[150:153], off
	global_store_dwordx4 v[10:11], v[86:89], off
	v_cvt_pk_f16_f32 v154, v154, v155
	v_cvt_pk_f16_f32 v155, v156, v157
	v_cvt_pk_f16_f32 v156, v138, v139
	v_cvt_pk_f16_f32 v157, v140, v141
	v_cvt_pk_f16_f32 v90, v90, v91
	v_cvt_pk_f16_f32 v91, v92, v93
	v_cvt_pk_f16_f32 v92, v74, v75
	v_cvt_pk_f16_f32 v93, v76, v77
	v_mov_b32_dpp v0, v154 row_ror:8 row_mask:0xf bank_mask:0xf
	v_mov_b32_dpp v1, v155 row_ror:8 row_mask:0xf bank_mask:0xf
	v_mov_b32_dpp v2, v156 row_ror:8 row_mask:0xf bank_mask:0xf
	v_mov_b32_dpp v3, v157 row_ror:8 row_mask:0xf bank_mask:0xf
	v_mov_b32_dpp v4, v90 row_ror:8 row_mask:0xf bank_mask:0xf
	v_mov_b32_dpp v5, v91 row_ror:8 row_mask:0xf bank_mask:0xf
	v_mov_b32_dpp v6, v92 row_ror:8 row_mask:0xf bank_mask:0xf
	v_mov_b32_dpp v7, v93 row_ror:8 row_mask:0xf bank_mask:0xf
	v_cndmask_b32_e32 v154, v154, v4, vcc
	v_cndmask_b32_e32 v155, v155, v5, vcc
	v_cndmask_b32_e32 v156, v156, v6, vcc
	v_cndmask_b32_e32 v157, v157, v7, vcc
	v_cndmask_b32_e32 v90, v0, v90, vcc
	v_cndmask_b32_e32 v91, v1, v91, vcc
	v_cndmask_b32_e32 v92, v2, v92, vcc
	v_cndmask_b32_e32 v93, v3, v93, vcc
	v_lshl_add_u64 v[10:11], v[20:21], 0, v[8:9]
	global_store_dwordx4 v[20:21], v[154:157], off
	global_store_dwordx4 v[10:11], v[90:93], off
	v_cvt_pk_f16_f32 v146, v146, v147
	v_cvt_pk_f16_f32 v147, v148, v149
	v_cvt_pk_f16_f32 v148, v130, v131
	v_cvt_pk_f16_f32 v149, v132, v133
	v_cvt_pk_f16_f32 v82, v82, v83
	v_cvt_pk_f16_f32 v83, v84, v85
	v_cvt_pk_f16_f32 v84, v66, v67
	v_cvt_pk_f16_f32 v85, v68, v69
	v_mov_b32_dpp v0, v146 row_ror:8 row_mask:0xf bank_mask:0xf
	v_mov_b32_dpp v1, v147 row_ror:8 row_mask:0xf bank_mask:0xf
	v_mov_b32_dpp v2, v148 row_ror:8 row_mask:0xf bank_mask:0xf
	v_mov_b32_dpp v3, v149 row_ror:8 row_mask:0xf bank_mask:0xf
	v_mov_b32_dpp v4, v82 row_ror:8 row_mask:0xf bank_mask:0xf
	v_mov_b32_dpp v5, v83 row_ror:8 row_mask:0xf bank_mask:0xf
	v_mov_b32_dpp v6, v84 row_ror:8 row_mask:0xf bank_mask:0xf
	v_mov_b32_dpp v7, v85 row_ror:8 row_mask:0xf bank_mask:0xf
	v_cndmask_b32_e32 v146, v146, v4, vcc
	v_cndmask_b32_e32 v147, v147, v5, vcc
	v_cndmask_b32_e32 v148, v148, v6, vcc
	v_cndmask_b32_e32 v149, v149, v7, vcc
	v_cndmask_b32_e32 v82, v0, v82, vcc
	v_cndmask_b32_e32 v83, v1, v83, vcc
	v_cndmask_b32_e32 v84, v2, v84, vcc
	v_cndmask_b32_e32 v85, v3, v85, vcc
	v_lshl_add_u64 v[10:11], v[22:23], 0, v[8:9]
	global_store_dwordx4 v[22:23], v[146:149], off
	global_store_dwordx4 v[10:11], v[82:85], off
	v_cvt_pk_f16_f32 v126, v126, v127
	v_cvt_pk_f16_f32 v127, v128, v129
	v_cvt_pk_f16_f32 v128, v110, v111
	v_cvt_pk_f16_f32 v129, v112, v113
	v_cvt_pk_f16_f32 v62, v62, v63
	v_cvt_pk_f16_f32 v63, v64, v65
	v_cvt_pk_f16_f32 v64, v46, v47
	v_cvt_pk_f16_f32 v65, v48, v49
	v_mov_b32_dpp v0, v126 row_ror:8 row_mask:0xf bank_mask:0xf
	v_mov_b32_dpp v1, v127 row_ror:8 row_mask:0xf bank_mask:0xf
	v_mov_b32_dpp v2, v128 row_ror:8 row_mask:0xf bank_mask:0xf
	v_mov_b32_dpp v3, v129 row_ror:8 row_mask:0xf bank_mask:0xf
	v_mov_b32_dpp v4, v62 row_ror:8 row_mask:0xf bank_mask:0xf
	v_mov_b32_dpp v5, v63 row_ror:8 row_mask:0xf bank_mask:0xf
	v_mov_b32_dpp v6, v64 row_ror:8 row_mask:0xf bank_mask:0xf
	v_mov_b32_dpp v7, v65 row_ror:8 row_mask:0xf bank_mask:0xf
	v_cndmask_b32_e32 v126, v126, v4, vcc
	v_cndmask_b32_e32 v127, v127, v5, vcc
	v_cndmask_b32_e32 v128, v128, v6, vcc
	v_cndmask_b32_e32 v129, v129, v7, vcc
	v_cndmask_b32_e32 v62, v0, v62, vcc
	v_cndmask_b32_e32 v63, v1, v63, vcc
	v_cndmask_b32_e32 v64, v2, v64, vcc
	v_cndmask_b32_e32 v65, v3, v65, vcc
	v_lshl_add_u64 v[10:11], v[24:25], 0, v[8:9]
	global_store_dwordx4 v[24:25], v[126:129], off
	global_store_dwordx4 v[10:11], v[62:65], off
	v_cvt_pk_f16_f32 v118, v118, v119
	v_cvt_pk_f16_f32 v119, v120, v121
	v_cvt_pk_f16_f32 v120, v102, v103
	v_cvt_pk_f16_f32 v121, v104, v105
	v_cvt_pk_f16_f32 v54, v54, v55
	v_cvt_pk_f16_f32 v55, v56, v57
	v_cvt_pk_f16_f32 v56, v38, v39
	v_cvt_pk_f16_f32 v57, v40, v41
	v_mov_b32_dpp v0, v118 row_ror:8 row_mask:0xf bank_mask:0xf
	v_mov_b32_dpp v1, v119 row_ror:8 row_mask:0xf bank_mask:0xf
	v_mov_b32_dpp v2, v120 row_ror:8 row_mask:0xf bank_mask:0xf
	v_mov_b32_dpp v3, v121 row_ror:8 row_mask:0xf bank_mask:0xf
	v_mov_b32_dpp v4, v54 row_ror:8 row_mask:0xf bank_mask:0xf
	v_mov_b32_dpp v5, v55 row_ror:8 row_mask:0xf bank_mask:0xf
	v_mov_b32_dpp v6, v56 row_ror:8 row_mask:0xf bank_mask:0xf
	v_mov_b32_dpp v7, v57 row_ror:8 row_mask:0xf bank_mask:0xf
	v_cndmask_b32_e32 v118, v118, v4, vcc
	v_cndmask_b32_e32 v119, v119, v5, vcc
	v_cndmask_b32_e32 v120, v120, v6, vcc
	v_cndmask_b32_e32 v121, v121, v7, vcc
	v_cndmask_b32_e32 v54, v0, v54, vcc
	v_cndmask_b32_e32 v55, v1, v55, vcc
	v_cndmask_b32_e32 v56, v2, v56, vcc
	v_cndmask_b32_e32 v57, v3, v57, vcc
	v_lshl_add_u64 v[10:11], v[26:27], 0, v[8:9]
	global_store_dwordx4 v[26:27], v[118:121], off
	global_store_dwordx4 v[10:11], v[54:57], off
	v_cvt_pk_f16_f32 v122, v122, v123
	v_cvt_pk_f16_f32 v123, v124, v125
	v_cvt_pk_f16_f32 v124, v106, v107
	v_cvt_pk_f16_f32 v125, v108, v109
	v_cvt_pk_f16_f32 v58, v58, v59
	v_cvt_pk_f16_f32 v59, v60, v61
	v_cvt_pk_f16_f32 v60, v42, v43
	v_cvt_pk_f16_f32 v61, v44, v45
	v_mov_b32_dpp v0, v122 row_ror:8 row_mask:0xf bank_mask:0xf
	v_mov_b32_dpp v1, v123 row_ror:8 row_mask:0xf bank_mask:0xf
	v_mov_b32_dpp v2, v124 row_ror:8 row_mask:0xf bank_mask:0xf
	v_mov_b32_dpp v3, v125 row_ror:8 row_mask:0xf bank_mask:0xf
	v_mov_b32_dpp v4, v58 row_ror:8 row_mask:0xf bank_mask:0xf
	v_mov_b32_dpp v5, v59 row_ror:8 row_mask:0xf bank_mask:0xf
	v_mov_b32_dpp v6, v60 row_ror:8 row_mask:0xf bank_mask:0xf
	v_mov_b32_dpp v7, v61 row_ror:8 row_mask:0xf bank_mask:0xf
	v_cndmask_b32_e32 v122, v122, v4, vcc
	v_cndmask_b32_e32 v123, v123, v5, vcc
	v_cndmask_b32_e32 v124, v124, v6, vcc
	v_cndmask_b32_e32 v125, v125, v7, vcc
	v_cndmask_b32_e32 v58, v0, v58, vcc
	v_cndmask_b32_e32 v59, v1, v59, vcc
	v_cndmask_b32_e32 v60, v2, v60, vcc
	v_cndmask_b32_e32 v61, v3, v61, vcc
	v_lshl_add_u64 v[10:11], v[28:29], 0, v[8:9]
	global_store_dwordx4 v[28:29], v[122:125], off
	global_store_dwordx4 v[10:11], v[58:61], off
	v_cvt_pk_f16_f32 v114, v114, v115
	v_cvt_pk_f16_f32 v115, v116, v117
	v_cvt_pk_f16_f32 v116, v98, v99
	v_cvt_pk_f16_f32 v117, v100, v101
	v_cvt_pk_f16_f32 v50, v50, v51
	v_cvt_pk_f16_f32 v51, v52, v53
	v_cvt_pk_f16_f32 v52, v34, v35
	v_cvt_pk_f16_f32 v53, v36, v37
	v_mov_b32_dpp v0, v114 row_ror:8 row_mask:0xf bank_mask:0xf
	v_mov_b32_dpp v1, v115 row_ror:8 row_mask:0xf bank_mask:0xf
	v_mov_b32_dpp v2, v116 row_ror:8 row_mask:0xf bank_mask:0xf
	v_mov_b32_dpp v3, v117 row_ror:8 row_mask:0xf bank_mask:0xf
	v_mov_b32_dpp v4, v50 row_ror:8 row_mask:0xf bank_mask:0xf
	v_mov_b32_dpp v5, v51 row_ror:8 row_mask:0xf bank_mask:0xf
	v_mov_b32_dpp v6, v52 row_ror:8 row_mask:0xf bank_mask:0xf
	v_mov_b32_dpp v7, v53 row_ror:8 row_mask:0xf bank_mask:0xf
	v_cndmask_b32_e32 v114, v114, v4, vcc
	v_cndmask_b32_e32 v115, v115, v5, vcc
	v_cndmask_b32_e32 v116, v116, v6, vcc
	v_cndmask_b32_e32 v117, v117, v7, vcc
	v_cndmask_b32_e32 v50, v0, v50, vcc
	v_cndmask_b32_e32 v51, v1, v51, vcc
	v_cndmask_b32_e32 v52, v2, v52, vcc
	v_cndmask_b32_e32 v53, v3, v53, vcc
	v_lshl_add_u64 v[10:11], v[30:31], 0, v[8:9]
	global_store_dwordx4 v[30:31], v[114:117], off
	global_store_dwordx4 v[10:11], v[50:53], off
	s_mov_b64 s[4:5], 0

.LBB0_931:
	v_mov_b32_e32 v197, v33
	v_lshl_add_u64 v[10:11], s[20:21], 0, v[196:197]
	v_mov_b32_e32 v199, v33
	s_lshl_b32 s1, s1, 5
	v_lshl_add_u64 v[12:13], s[20:21], 0, v[198:199]
	s_and_b32 s1, s1, 0x60
	s_add_i32 m0, s30, 0x18000
	v_lshl_add_u64 v[10:11], v[10:11], 0, s[84:85]
	v_lshl_add_u64 v[14:15], s[14:15], 0, v[196:197]
	s_lshl_b32 s4, s0, 13
	s_lshl_b32 s5, s1, 7
	s_waitcnt vmcnt(4)
	s_barrier
	global_load_lds_dwordx4 v[10:11], off
	v_lshl_add_u64 v[10:11], v[12:13], 0, s[84:85]
	s_add_i32 m0, s30, 0x1a000
	s_add_i32 s36, s30, 0x8000
	s_add_i32 s37, s30, 0xa000
	v_lshl_add_u64 v[16:17], s[14:15], 0, v[198:199]
	global_load_lds_dwordx4 v[10:11], off
	v_lshl_add_u64 v[10:11], v[14:15], 0, s[84:85]
	s_mov_b32 m0, s36
	s_add_u32 s2, s20, 0x40080
	global_load_lds_dwordx4 v[10:11], off
	v_lshl_add_u64 v[10:11], v[16:17], 0, s[84:85]
	s_mov_b32 m0, s37
	s_addc_u32 s3, s21, 0
	global_load_lds_dwordx4 v[10:11], off
	s_add_i32 m0, s30, 0x1c000
	v_lshl_add_u64 v[10:11], s[2:3], 0, v[196:197]
	global_load_lds_dwordx4 v[10:11], off
	v_lshl_add_u64 v[10:11], s[2:3], 0, v[198:199]
	s_add_i32 m0, s30, 0x1e000
	v_and_b32_e32 v9, 15, v0
	global_load_lds_dwordx4 v[10:11], off
	v_lshrrev_b32_e32 v10, 1, v0
	v_and_b32_e32 v10, 24, v10
	v_lshlrev_b32_e32 v11, 1, v10
	v_lshlrev_b32_e32 v0, 2, v0
	v_lshl_or_b32 v208, s0, 6, v9
	v_lshl_or_b32 v9, v9, 6, v11
	v_and_b32_e32 v0, 32, v0
	v_bitop3_b32 v11, v9, s4, v0 bitop3:0xde
	v_bitop3_b32 v209, v9, s5, v0 bitop3:0xde
	v_lshlrev_b32_e32 v0, 13, v1
	v_and_b32_e32 v0, 0x7fffc000, v0
	v_lshl_add_u32 v0, v2, 10, v0
	v_or_b32_e32 v0, v0, v3
	v_add_lshl_u32 v32, v0, v4, 1
	v_lshlrev_b32_e32 v0, 13, v5
	v_and_b32_e32 v0, 0x7fffc000, v0
	v_lshl_add_u32 v0, v6, 10, v0
	v_or_b32_e32 v210, s1, v10
	s_mov_b64 s[0:1], 0x40080
	v_or_b32_e32 v0, v0, v7
	v_lshl_add_u64 v[200:201], v[32:33], 0, s[0:1]
	v_add_lshl_u32 v32, v0, v8, 1
	s_waitcnt vmcnt(6)
	v_lshl_add_u64 v[202:203], v[32:33], 0, s[0:1]
	v_mov_b32_e32 v32, v33
	v_mov_b32_e32 v34, v33
	v_mov_b32_e32 v35, v33
	v_add_u32_e32 v211, 0, v11
	v_mov_b64_e32 v[0:1], v[32:33]
	v_mov_b64_e32 v[4:5], v[32:33]
	v_mov_b64_e32 v[8:9], v[32:33]
	v_mov_b64_e32 v[12:13], v[32:33]
	v_mov_b64_e32 v[16:17], v[32:33]
	v_mov_b64_e32 v[20:21], v[32:33]
	v_mov_b64_e32 v[24:25], v[32:33]
	v_mov_b64_e32 v[28:29], v[32:33]
	v_mov_b64_e32 v[38:39], v[34:35]
	v_mov_b64_e32 v[42:43], v[34:35]
	v_mov_b64_e32 v[46:47], v[34:35]
	v_mov_b64_e32 v[50:51], v[34:35]
	v_mov_b64_e32 v[54:55], v[34:35]
	v_mov_b64_e32 v[58:59], v[34:35]
	v_mov_b64_e32 v[62:63], v[34:35]
	v_mov_b64_e32 v[66:67], v[34:35]
	v_mov_b64_e32 v[70:71], v[34:35]
	v_mov_b64_e32 v[74:75], v[34:35]
	v_mov_b64_e32 v[78:79], v[34:35]
	v_mov_b64_e32 v[82:83], v[34:35]
	v_mov_b64_e32 v[86:87], v[34:35]
	v_mov_b64_e32 v[90:91], v[34:35]
	v_mov_b64_e32 v[94:95], v[34:35]
	v_mov_b64_e32 v[98:99], v[34:35]
	v_mov_b64_e32 v[102:103], v[34:35]
	v_mov_b64_e32 v[106:107], v[34:35]
	v_mov_b64_e32 v[110:111], v[34:35]
	v_mov_b64_e32 v[114:115], v[34:35]
	v_mov_b64_e32 v[118:119], v[34:35]
	v_mov_b64_e32 v[122:123], v[34:35]
	v_mov_b64_e32 v[126:127], v[34:35]
	v_mov_b64_e32 v[130:131], v[34:35]
	s_mov_b32 s13, 0
	v_mov_b64_e32 v[2:3], v[34:35]
	v_mov_b64_e32 v[6:7], v[34:35]
	v_mov_b64_e32 v[10:11], v[34:35]
	v_mov_b64_e32 v[14:15], v[34:35]
	v_mov_b64_e32 v[18:19], v[34:35]
	v_mov_b64_e32 v[22:23], v[34:35]
	v_mov_b64_e32 v[26:27], v[34:35]
	v_mov_b64_e32 v[30:31], v[34:35]
	v_mov_b64_e32 v[36:37], v[32:33]
	v_mov_b64_e32 v[40:41], v[32:33]
	v_mov_b64_e32 v[44:45], v[32:33]
	v_mov_b64_e32 v[48:49], v[32:33]
	v_mov_b64_e32 v[52:53], v[32:33]
	v_mov_b64_e32 v[56:57], v[32:33]
	v_mov_b64_e32 v[60:61], v[32:33]
	v_mov_b64_e32 v[64:65], v[32:33]
	v_mov_b64_e32 v[68:69], v[32:33]
	v_mov_b64_e32 v[72:73], v[32:33]
	v_mov_b64_e32 v[76:77], v[32:33]
	v_mov_b64_e32 v[80:81], v[32:33]
	v_mov_b64_e32 v[84:85], v[32:33]
	v_mov_b64_e32 v[88:89], v[32:33]
	v_mov_b64_e32 v[92:93], v[32:33]
	v_mov_b64_e32 v[96:97], v[32:33]
	v_mov_b64_e32 v[100:101], v[32:33]
	v_mov_b64_e32 v[104:105], v[32:33]
	v_mov_b64_e32 v[108:109], v[32:33]
	v_mov_b64_e32 v[112:113], v[32:33]
	v_mov_b64_e32 v[116:117], v[32:33]
	v_mov_b64_e32 v[120:121], v[32:33]
	v_mov_b64_e32 v[124:125], v[32:33]
	v_mov_b64_e32 v[128:129], v[32:33]
	s_mov_b32 s38, 0
	s_barrier
	s_mov_b32 s50, 0
	s_branch .LBB0_933
.LBB0_932:
	s_cmp_eq_u32 s50, 0
	s_cbranch_scc1 .Lepib_yg_nb
	s_mov_b32 s50, 0
	s_barrier
.Lepib_yg_nb:
	s_andn2_b64 vcc, exec, s[8:9]
	s_mov_b32 s13, s39
	s_mov_b32 s10, s0
	s_mov_b32 s12, s2
	s_mov_b64 s[20:21], s[6:7]
	s_mov_b64 s[14:15], s[4:5]
	s_cbranch_vccz .LBB0_947

.LBB0_940:
	s_add_u32 s20, s14, 0x100
	s_addc_u32 s21, s15, 0
	s_add_i32 s40, 0, 0x10000
	v_add_u32_e32 v32, s40, v209
	ds_read_b128 v[132:135], v32
	ds_read_b128 v[140:143], v32 offset:2048
	ds_read_b128 v[136:139], v32 offset:1024
	ds_read_b128 v[144:147], v32 offset:3072
	s_cmp_eq_u32 s11, 12
	s_cselect_b32 s25, s17, s21
	s_cselect_b32 s24, s16, s20
	s_cselect_b32 s23, s19, s3
	s_cselect_b32 s22, s18, s1
	v_lshl_add_u64 v[34:35], s[14:15], 0, v[200:201]
	s_add_i32 m0, s30, 0xc000
	ds_read_b128 v[148:151], v211
	ds_read_b128 v[156:159], v211 offset:2048
	ds_read_b128 v[164:167], v211 offset:4096
	ds_read_b128 v[172:175], v211 offset:6144
	ds_read_b128 v[152:155], v211 offset:1024
	ds_read_b128 v[160:163], v211 offset:3072
	ds_read_b128 v[168:171], v211 offset:5120
	ds_read_b128 v[176:179], v211 offset:7168
	global_load_lds_dwordx4 v[34:35], off
	v_lshl_add_u64 v[34:35], s[14:15], 0, v[202:203]
	s_add_i32 m0, s30, 0xe000
	s_nop 0
	global_load_lds_dwordx4 v[34:35], off
	s_waitcnt lgkmcnt(8)
	s_barrier
	s_waitcnt lgkmcnt(7)
	s_setprio 1
	v_mfma_f32_16x16x32_f16 v[128:131], v[132:135], v[148:151], v[128:131]
	v_mfma_f32_16x16x32_f16 v[124:127], v[140:143], v[148:151], v[124:127]
	s_waitcnt lgkmcnt(6)
	v_mfma_f32_16x16x32_f16 v[120:123], v[132:135], v[156:159], v[120:123]
	v_mfma_f32_16x16x32_f16 v[116:119], v[140:143], v[156:159], v[116:119]
	s_waitcnt lgkmcnt(5)
	v_mfma_f32_16x16x32_f16 v[112:115], v[132:135], v[164:167], v[112:115]
	v_mfma_f32_16x16x32_f16 v[108:111], v[140:143], v[164:167], v[108:111]
	s_waitcnt lgkmcnt(4)
	v_mfma_f32_16x16x32_f16 v[104:107], v[132:135], v[172:175], v[104:107]
	v_mfma_f32_16x16x32_f16 v[100:103], v[140:143], v[172:175], v[100:103]
	s_waitcnt lgkmcnt(3)
	v_mfma_f32_16x16x32_f16 v[128:131], v[136:139], v[152:155], v[128:131]
	v_mfma_f32_16x16x32_f16 v[124:127], v[144:147], v[152:155], v[124:127]
	s_waitcnt lgkmcnt(2)
	v_mfma_f32_16x16x32_f16 v[120:123], v[136:139], v[160:163], v[120:123]
	v_mfma_f32_16x16x32_f16 v[116:119], v[144:147], v[160:163], v[116:119]
	s_waitcnt lgkmcnt(1)
	v_mfma_f32_16x16x32_f16 v[112:115], v[136:139], v[168:171], v[112:115]
	v_mfma_f32_16x16x32_f16 v[108:111], v[144:147], v[168:171], v[108:111]
	s_waitcnt lgkmcnt(0)
	v_mfma_f32_16x16x32_f16 v[104:107], v[136:139], v[176:179], v[104:107]
	v_mfma_f32_16x16x32_f16 v[100:103], v[144:147], v[176:179], v[100:103]
	s_setprio 0
	s_barrier
	s_add_i32 s41, 0, 0x14000
	s_add_i32 s14, s40, s29
	v_add_u32_e32 v32, s41, v209
	v_lshl_add_u64 v[204:205], s[22:23], 0, v[196:197]
	s_mov_b32 m0, s14
	ds_read_b128 v[180:183], v32
	ds_read_b128 v[188:191], v32 offset:2048
	ds_read_b128 v[184:187], v32 offset:1024
	ds_read_b128 v[192:195], v32 offset:3072
	global_load_lds_dwordx4 v[204:205], off
	v_lshl_add_u64 v[206:207], s[22:23], 0, v[198:199]
	s_add_i32 m0, s14, 0x2000
	s_nop 0
	global_load_lds_dwordx4 v[206:207], off
	s_barrier
	s_waitcnt lgkmcnt(2)
	s_setprio 1
	v_mfma_f32_16x16x32_f16 v[96:99], v[180:183], v[148:151], v[96:99]
	v_mfma_f32_16x16x32_f16 v[92:95], v[188:191], v[148:151], v[92:95]
	v_mfma_f32_16x16x32_f16 v[88:91], v[180:183], v[156:159], v[88:91]
	v_mfma_f32_16x16x32_f16 v[84:87], v[188:191], v[156:159], v[84:87]
	v_mfma_f32_16x16x32_f16 v[80:83], v[180:183], v[164:167], v[80:83]
	v_mfma_f32_16x16x32_f16 v[76:79], v[188:191], v[164:167], v[76:79]
	v_mfma_f32_16x16x32_f16 v[72:75], v[180:183], v[172:175], v[72:75]
	v_mfma_f32_16x16x32_f16 v[68:71], v[188:191], v[172:175], v[68:71]
	s_waitcnt lgkmcnt(0)
	v_mfma_f32_16x16x32_f16 v[96:99], v[184:187], v[152:155], v[96:99]
	v_mfma_f32_16x16x32_f16 v[92:95], v[192:195], v[152:155], v[92:95]
	v_mfma_f32_16x16x32_f16 v[88:91], v[184:187], v[160:163], v[88:91]
	v_mfma_f32_16x16x32_f16 v[84:87], v[192:195], v[160:163], v[84:87]
	v_mfma_f32_16x16x32_f16 v[80:83], v[184:187], v[168:171], v[80:83]
	v_mfma_f32_16x16x32_f16 v[76:79], v[192:195], v[168:171], v[76:79]
	v_mfma_f32_16x16x32_f16 v[72:75], v[184:187], v[176:179], v[72:75]
	v_mfma_f32_16x16x32_f16 v[68:71], v[192:195], v[176:179], v[68:71]
	s_setprio 0
	s_mov_b32 m0, s30
	v_lshl_add_u64 v[212:213], s[24:25], 0, v[196:197]
	s_barrier
	ds_read_b128 v[148:151], v211 offset:16384
	ds_read_b128 v[156:159], v211 offset:18432
	ds_read_b128 v[164:167], v211 offset:20480
	ds_read_b128 v[172:175], v211 offset:22528
	ds_read_b128 v[152:155], v211 offset:17408
	ds_read_b128 v[160:163], v211 offset:19456
	ds_read_b128 v[168:171], v211 offset:21504
	ds_read_b128 v[176:179], v211 offset:23552
	global_load_lds_dwordx4 v[212:213], off
	v_lshl_add_u64 v[214:215], s[24:25], 0, v[198:199]
	s_mov_b32 m0, s31
	s_nop 0
	global_load_lds_dwordx4 v[214:215], off
	s_barrier
	s_waitcnt lgkmcnt(7)
	s_setprio 1
	v_mfma_f32_16x16x32_f16 v[64:67], v[132:135], v[148:151], v[64:67]
	v_mfma_f32_16x16x32_f16 v[60:63], v[140:143], v[148:151], v[60:63]
	s_waitcnt lgkmcnt(6)
	v_mfma_f32_16x16x32_f16 v[56:59], v[132:135], v[156:159], v[56:59]
	v_mfma_f32_16x16x32_f16 v[52:55], v[140:143], v[156:159], v[52:55]
	s_waitcnt lgkmcnt(5)
	v_mfma_f32_16x16x32_f16 v[48:51], v[132:135], v[164:167], v[48:51]
	v_mfma_f32_16x16x32_f16 v[44:47], v[140:143], v[164:167], v[44:47]
	s_waitcnt lgkmcnt(4)
	v_mfma_f32_16x16x32_f16 v[40:43], v[132:135], v[172:175], v[40:43]
	v_mfma_f32_16x16x32_f16 v[34:37], v[140:143], v[172:175], v[36:39]
	s_waitcnt lgkmcnt(3)
	v_mfma_f32_16x16x32_f16 v[64:67], v[136:139], v[152:155], v[64:67]
	v_mfma_f32_16x16x32_f16 v[60:63], v[144:147], v[152:155], v[60:63]
	s_waitcnt lgkmcnt(2)
	v_mfma_f32_16x16x32_f16 v[56:59], v[136:139], v[160:163], v[56:59]
	v_mfma_f32_16x16x32_f16 v[52:55], v[144:147], v[160:163], v[52:55]
	s_waitcnt lgkmcnt(1)
	v_mfma_f32_16x16x32_f16 v[48:51], v[136:139], v[168:171], v[48:51]
	v_mfma_f32_16x16x32_f16 v[44:47], v[144:147], v[168:171], v[44:47]
	s_waitcnt lgkmcnt(0)
	v_mfma_f32_16x16x32_f16 v[40:43], v[136:139], v[176:179], v[40:43]
	v_mfma_f32_16x16x32_f16 v[34:37], v[144:147], v[176:179], v[34:37]
	s_setprio 0
	s_barrier
	s_add_u32 s14, s22, 0x40000
	s_addc_u32 s15, s23, 0
	s_add_i32 s40, s41, s29
	v_lshl_add_u64 v[38:39], s[14:15], 0, v[196:197]
	s_mov_b32 m0, s40
	s_nop 0
	global_load_lds_dwordx4 v[38:39], off
	v_lshl_add_u64 v[38:39], s[14:15], 0, v[198:199]
	s_add_i32 m0, s40, 0x2000
	s_nop 0
	global_load_lds_dwordx4 v[38:39], off
	s_waitcnt vmcnt(6)
	s_barrier
	s_setprio 1
	v_mfma_f32_16x16x32_f16 v[28:31], v[180:183], v[148:151], v[28:31]
	v_mfma_f32_16x16x32_f16 v[24:27], v[188:191], v[148:151], v[24:27]
	v_mfma_f32_16x16x32_f16 v[20:23], v[180:183], v[156:159], v[20:23]
	v_mfma_f32_16x16x32_f16 v[16:19], v[188:191], v[156:159], v[16:19]
	v_mfma_f32_16x16x32_f16 v[12:15], v[180:183], v[164:167], v[12:15]
	v_mfma_f32_16x16x32_f16 v[8:11], v[188:191], v[164:167], v[8:11]
	v_mfma_f32_16x16x32_f16 v[4:7], v[180:183], v[172:175], v[4:7]
	v_mfma_f32_16x16x32_f16 v[0:3], v[188:191], v[172:175], v[0:3]
	v_mfma_f32_16x16x32_f16 v[28:31], v[184:187], v[152:155], v[28:31]
	v_mfma_f32_16x16x32_f16 v[24:27], v[192:195], v[152:155], v[24:27]
	v_mfma_f32_16x16x32_f16 v[20:23], v[184:187], v[160:163], v[20:23]
	v_mfma_f32_16x16x32_f16 v[16:19], v[192:195], v[160:163], v[16:19]
	v_mfma_f32_16x16x32_f16 v[12:15], v[184:187], v[168:171], v[12:15]
	v_mfma_f32_16x16x32_f16 v[8:11], v[192:195], v[168:171], v[8:11]
	v_mfma_f32_16x16x32_f16 v[4:7], v[184:187], v[176:179], v[4:7]
	v_mfma_f32_16x16x32_f16 v[0:3], v[192:195], v[176:179], v[0:3]
	s_setprio 0
	s_add_i32 s40, 0, 0x18000
	v_add_u32_e32 v32, s40, v209
	s_barrier
	ds_read_b128 v[132:135], v32
	ds_read_b128 v[140:143], v32 offset:2048
	ds_read_b128 v[136:139], v32 offset:1024
	ds_read_b128 v[144:147], v32 offset:3072
	s_add_u32 s14, s24, 0x40000
	s_addc_u32 s15, s25, 0
	s_mov_b32 m0, s34
	v_lshl_add_u64 v[38:39], s[14:15], 0, v[196:197]
	ds_read_b128 v[148:151], v211 offset:32768
	ds_read_b128 v[156:159], v211 offset:34816
	ds_read_b128 v[164:167], v211 offset:36864
	ds_read_b128 v[172:175], v211 offset:38912
	ds_read_b128 v[152:155], v211 offset:33792
	ds_read_b128 v[160:163], v211 offset:35840
	ds_read_b128 v[168:171], v211 offset:37888
	ds_read_b128 v[176:179], v211 offset:39936
	global_load_lds_dwordx4 v[38:39], off
	v_lshl_add_u64 v[38:39], s[14:15], 0, v[198:199]
	s_mov_b32 m0, s35
	s_nop 0
	global_load_lds_dwordx4 v[38:39], off
	s_waitcnt lgkmcnt(8)
	s_barrier
	s_waitcnt lgkmcnt(7)
	s_setprio 1
	v_mfma_f32_16x16x32_f16 v[128:131], v[132:135], v[148:151], v[128:131]
	v_mfma_f32_16x16x32_f16 v[124:127], v[140:143], v[148:151], v[124:127]
	s_waitcnt lgkmcnt(6)
	v_mfma_f32_16x16x32_f16 v[120:123], v[132:135], v[156:159], v[120:123]
	v_mfma_f32_16x16x32_f16 v[116:119], v[140:143], v[156:159], v[116:119]
	s_waitcnt lgkmcnt(5)
	v_mfma_f32_16x16x32_f16 v[112:115], v[132:135], v[164:167], v[112:115]
	v_mfma_f32_16x16x32_f16 v[108:111], v[140:143], v[164:167], v[108:111]
	s_waitcnt lgkmcnt(4)
	v_mfma_f32_16x16x32_f16 v[104:107], v[132:135], v[172:175], v[104:107]
	v_mfma_f32_16x16x32_f16 v[100:103], v[140:143], v[172:175], v[100:103]
	s_waitcnt lgkmcnt(3)
	v_mfma_f32_16x16x32_f16 v[128:131], v[136:139], v[152:155], v[128:131]
	v_mfma_f32_16x16x32_f16 v[124:127], v[144:147], v[152:155], v[124:127]
	s_waitcnt lgkmcnt(2)
	v_mfma_f32_16x16x32_f16 v[120:123], v[136:139], v[160:163], v[120:123]
	v_mfma_f32_16x16x32_f16 v[116:119], v[144:147], v[160:163], v[116:119]
	s_waitcnt lgkmcnt(1)
	v_mfma_f32_16x16x32_f16 v[112:115], v[136:139], v[168:171], v[112:115]
	v_mfma_f32_16x16x32_f16 v[108:111], v[144:147], v[168:171], v[108:111]
	s_waitcnt lgkmcnt(0)
	v_mfma_f32_16x16x32_f16 v[104:107], v[136:139], v[176:179], v[104:107]
	v_mfma_f32_16x16x32_f16 v[100:103], v[144:147], v[176:179], v[100:103]
	s_setprio 0
	s_barrier
	s_add_i32 s24, 0, 0x1c000
	s_add_i32 s14, s40, s29
	v_add_u32_e32 v32, s24, v209
	v_lshl_add_u64 v[38:39], v[204:205], 0, s[84:85]
	s_mov_b32 m0, s14
	ds_read_b128 v[180:183], v32
	ds_read_b128 v[188:191], v32 offset:2048
	ds_read_b128 v[184:187], v32 offset:1024
	ds_read_b128 v[192:195], v32 offset:3072
	global_load_lds_dwordx4 v[38:39], off
	v_lshl_add_u64 v[38:39], v[206:207], 0, s[84:85]
	s_add_i32 m0, s14, 0x2000
	s_nop 0
	global_load_lds_dwordx4 v[38:39], off
	s_barrier
	s_waitcnt lgkmcnt(2)
	s_setprio 1
	v_mfma_f32_16x16x32_f16 v[96:99], v[180:183], v[148:151], v[96:99]
	v_mfma_f32_16x16x32_f16 v[92:95], v[188:191], v[148:151], v[92:95]
	v_mfma_f32_16x16x32_f16 v[88:91], v[180:183], v[156:159], v[88:91]
	v_mfma_f32_16x16x32_f16 v[84:87], v[188:191], v[156:159], v[84:87]
	v_mfma_f32_16x16x32_f16 v[80:83], v[180:183], v[164:167], v[80:83]
	v_mfma_f32_16x16x32_f16 v[76:79], v[188:191], v[164:167], v[76:79]
	v_mfma_f32_16x16x32_f16 v[72:75], v[180:183], v[172:175], v[72:75]
	v_mfma_f32_16x16x32_f16 v[68:71], v[188:191], v[172:175], v[68:71]
	s_waitcnt lgkmcnt(0)
	v_mfma_f32_16x16x32_f16 v[96:99], v[184:187], v[152:155], v[96:99]
	v_mfma_f32_16x16x32_f16 v[92:95], v[192:195], v[152:155], v[92:95]
	v_mfma_f32_16x16x32_f16 v[88:91], v[184:187], v[160:163], v[88:91]
	v_mfma_f32_16x16x32_f16 v[84:87], v[192:195], v[160:163], v[84:87]
	v_mfma_f32_16x16x32_f16 v[80:83], v[184:187], v[168:171], v[80:83]
	v_mfma_f32_16x16x32_f16 v[76:79], v[192:195], v[168:171], v[76:79]
	v_mfma_f32_16x16x32_f16 v[72:75], v[184:187], v[176:179], v[72:75]
	v_mfma_f32_16x16x32_f16 v[68:71], v[192:195], v[176:179], v[68:71]
	s_setprio 0
	s_mov_b32 m0, s36
	v_lshl_add_u64 v[38:39], v[212:213], 0, s[84:85]
	s_barrier
	ds_read_b128 v[148:151], v211 offset:49152
	ds_read_b128 v[156:159], v211 offset:51200
	ds_read_b128 v[164:167], v211 offset:53248
	ds_read_b128 v[172:175], v211 offset:55296
	ds_read_b128 v[152:155], v211 offset:50176
	ds_read_b128 v[160:163], v211 offset:52224
	ds_read_b128 v[168:171], v211 offset:54272
	ds_read_b128 v[176:179], v211 offset:56320
	global_load_lds_dwordx4 v[38:39], off
	v_lshl_add_u64 v[38:39], v[214:215], 0, s[84:85]
	s_mov_b32 m0, s37
	s_nop 0
	global_load_lds_dwordx4 v[38:39], off
	s_barrier
	s_waitcnt lgkmcnt(7)
	s_setprio 1
	v_mfma_f32_16x16x32_f16 v[64:67], v[132:135], v[148:151], v[64:67]
	v_mfma_f32_16x16x32_f16 v[60:63], v[140:143], v[148:151], v[60:63]
	s_waitcnt lgkmcnt(6)
	v_mfma_f32_16x16x32_f16 v[56:59], v[132:135], v[156:159], v[56:59]
	v_mfma_f32_16x16x32_f16 v[52:55], v[140:143], v[156:159], v[52:55]
	s_waitcnt lgkmcnt(5)
	v_mfma_f32_16x16x32_f16 v[48:51], v[132:135], v[164:167], v[48:51]
	v_mfma_f32_16x16x32_f16 v[44:47], v[140:143], v[164:167], v[44:47]
	s_waitcnt lgkmcnt(4)
	v_mfma_f32_16x16x32_f16 v[38:41], v[132:135], v[172:175], v[40:43]
	v_mfma_f32_16x16x32_f16 v[34:37], v[140:143], v[172:175], v[34:37]
	s_waitcnt lgkmcnt(3)
	v_mfma_f32_16x16x32_f16 v[64:67], v[136:139], v[152:155], v[64:67]
	v_mfma_f32_16x16x32_f16 v[60:63], v[144:147], v[152:155], v[60:63]
	s_waitcnt lgkmcnt(2)
	v_mfma_f32_16x16x32_f16 v[56:59], v[136:139], v[160:163], v[56:59]
	v_mfma_f32_16x16x32_f16 v[52:55], v[144:147], v[160:163], v[52:55]
	s_waitcnt lgkmcnt(1)
	v_mfma_f32_16x16x32_f16 v[48:51], v[136:139], v[168:171], v[48:51]
	v_mfma_f32_16x16x32_f16 v[44:47], v[144:147], v[168:171], v[44:47]
	s_waitcnt lgkmcnt(0)
	v_mfma_f32_16x16x32_f16 v[40:43], v[136:139], v[176:179], v[38:41]
	v_mfma_f32_16x16x32_f16 v[36:39], v[144:147], v[176:179], v[34:37]
	s_setprio 0
	s_barrier
	s_add_u32 s14, s22, 0x40080
	s_addc_u32 s15, s23, 0
	s_add_i32 s22, s24, s29
	v_lshl_add_u64 v[34:35], s[14:15], 0, v[196:197]
	s_mov_b32 m0, s22
	s_nop 0
	global_load_lds_dwordx4 v[34:35], off
	v_lshl_add_u64 v[34:35], s[14:15], 0, v[198:199]
	s_add_i32 m0, s22, 0x2000
	s_nop 0
	global_load_lds_dwordx4 v[34:35], off
	s_waitcnt vmcnt(6)
	s_barrier
	s_setprio 1
	v_mfma_f32_16x16x32_f16 v[28:31], v[180:183], v[148:151], v[28:31]
	v_mfma_f32_16x16x32_f16 v[24:27], v[188:191], v[148:151], v[24:27]
	v_mfma_f32_16x16x32_f16 v[20:23], v[180:183], v[156:159], v[20:23]
	v_mfma_f32_16x16x32_f16 v[16:19], v[188:191], v[156:159], v[16:19]
	v_mfma_f32_16x16x32_f16 v[12:15], v[180:183], v[164:167], v[12:15]
	v_mfma_f32_16x16x32_f16 v[8:11], v[188:191], v[164:167], v[8:11]
	v_mfma_f32_16x16x32_f16 v[4:7], v[180:183], v[172:175], v[4:7]
	v_mfma_f32_16x16x32_f16 v[0:3], v[188:191], v[172:175], v[0:3]
	v_mfma_f32_16x16x32_f16 v[28:31], v[184:187], v[152:155], v[28:31]
	v_mfma_f32_16x16x32_f16 v[24:27], v[192:195], v[152:155], v[24:27]
	v_mfma_f32_16x16x32_f16 v[20:23], v[184:187], v[160:163], v[20:23]
	v_mfma_f32_16x16x32_f16 v[16:19], v[192:195], v[160:163], v[16:19]
	v_mfma_f32_16x16x32_f16 v[12:15], v[184:187], v[168:171], v[12:15]
	v_mfma_f32_16x16x32_f16 v[8:11], v[192:195], v[168:171], v[8:11]
	v_mfma_f32_16x16x32_f16 v[4:7], v[184:187], v[176:179], v[4:7]
	v_mfma_f32_16x16x32_f16 v[0:3], v[192:195], v[176:179], v[0:3]
	s_setprio 0
	s_add_i32 s11, s11, 2
	s_add_u32 s1, s1, 0x100
	s_addc_u32 s3, s3, 0
	s_cmp_gt_u32 s11, 13
	s_mov_b64 s[14:15], s[20:21]
	s_cbranch_scc0 .Lepib_yg_bar
	v_readlane_b32 s51, v251, 36
	s_cmp_gt_u32 s51, 3
	s_cbranch_scc0 .Lepib_yg_barx
	s_mov_b32 s50, 1
	s_branch .Lepib_yg_exit

.Lepib_yg_exit:
	v_lshl_add_u32 v34, s12, 8, v208
	v_lshl_or_b32 v156, s10, 8, v210
	s_cmp_lg_u32 s13, 0
	s_cselect_b64 s[10:11], -1, 0
	s_cmp_eq_u32 s13, 0
	v_ashrrev_i32_e32 v157, 31, v156
	v_ashrrev_i32_e32 v35, 31, v34
	v_mad_i64_i32 v[158:159], s[12:13], v34, s33, 0
	v_or_b32_e32 v160, 16, v34
	v_or_b32_e32 v162, 32, v34
	v_or_b32_e32 v164, 48, v34
	s_cbranch_scc1 .LBB0_946
	v_lshl_add_u64 v[132:133], s[70:71], 0, v[158:159]
	v_lshlrev_b64 v[166:167], 1, v[156:157]
	v_lshl_add_u64 v[132:133], v[132:133], 0, v[166:167]
	s_mov_b64 s[16:17], 0x2800
	v_mov_b64_e32 v[168:169], s[70:71]
	s_movk_i32 s1, 0x2000
	v_lshl_add_u64 v[134:135], v[132:133], 0, s[16:17]
	v_mad_i64_i32 v[136:137], s[12:13], v160, s33, v[168:169]
	v_add_co_u32_e32 v132, vcc, s1, v132
	v_lshl_add_u64 v[136:137], v[136:137], 0, v[166:167]
	s_nop 0
	v_addc_co_u32_e32 v133, vcc, 0, v133, vcc
	v_lshl_add_u64 v[138:139], v[136:137], 0, s[16:17]
	v_mad_i64_i32 v[140:141], s[12:13], v162, s33, v[168:169]
	v_add_co_u32_e32 v136, vcc, s1, v136
	v_lshl_add_u64 v[140:141], v[140:141], 0, v[166:167]
	s_nop 0
	v_addc_co_u32_e32 v137, vcc, 0, v137, vcc
	v_mad_i64_i32 v[144:145], s[12:13], v164, s33, v[168:169]
	global_load_dwordx4 v[170:173], v[132:133], off offset:2048
	global_load_dwordx4 v[152:155], v[136:137], off offset:2048
	global_load_dwordx4 v[174:177], v[134:135], off offset:256
	global_load_dwordx4 v[148:151], v[138:139], off offset:256
	v_add_co_u32_e32 v132, vcc, s1, v140
	v_lshl_add_u64 v[144:145], v[144:145], 0, v[166:167]
	s_nop 0
	v_addc_co_u32_e32 v133, vcc, 0, v141, vcc
	v_add_co_u32_e32 v134, vcc, s1, v144
	v_lshl_add_u64 v[142:143], v[140:141], 0, s[16:17]
	s_nop 0
	v_addc_co_u32_e32 v135, vcc, 0, v145, vcc
	v_lshl_add_u64 v[178:179], v[144:145], 0, s[16:17]
	global_load_dwordx4 v[144:147], v[132:133], off offset:2048
	global_load_dwordx4 v[136:139], v[134:135], off offset:2048
	s_nop 0
	global_load_dwordx4 v[140:143], v[142:143], off offset:256
	s_nop 0
	global_load_dwordx4 v[132:135], v[178:179], off offset:256
	v_ashrrev_i32_e32 v161, 31, v160
	v_ashrrev_i32_e32 v163, 31, v162
	v_ashrrev_i32_e32 v165, 31, v164
	s_waitcnt vmcnt(0)
	v_cvt_f32_f16_e32 v32, v170
	v_cvt_f32_f16_sdwa v170, v170 dst_sel:DWORD dst_unused:UNUSED_PAD src0_sel:WORD_1
	v_lshlrev_b64 v[178:179], 11, v[34:35]
	v_readlane_b32 s14, v252, 9
	v_max_f32_e32 v32, 0xc1f00000, v32
	v_max_f32_e32 v35, 0xc1f00000, v170
	v_cvt_f32_f16_e32 v170, v171
	v_cvt_f32_f16_sdwa v171, v171 dst_sel:DWORD dst_unused:UNUSED_PAD src0_sel:WORD_1
	v_mul_f32_e32 v35, 0xbfb8aa3b, v35
	v_exp_f32_e32 v35, v35
	v_max_f32_e32 v170, 0xc1f00000, v170
	v_mul_f32_e32 v170, 0xbfb8aa3b, v170
	v_exp_f32_e32 v180, v170
	v_max_f32_e32 v170, 0xc1f00000, v171
	v_mul_f32_e32 v170, 0xbfb8aa3b, v170
	v_cvt_f32_f16_e32 v171, v172
	v_exp_f32_e32 v181, v170
	v_cvt_f32_f16_sdwa v170, v172 dst_sel:DWORD dst_unused:UNUSED_PAD src0_sel:WORD_1
	v_mul_f32_e32 v32, 0xbfb8aa3b, v32
	v_max_f32_e32 v171, 0xc1f00000, v171
	v_mul_f32_e32 v171, 0xbfb8aa3b, v171
	v_max_f32_e32 v170, 0xc1f00000, v170
	v_mul_f32_e32 v170, 0xbfb8aa3b, v170
	v_exp_f32_e32 v182, v171
	v_cvt_f32_f16_e32 v171, v173
	v_exp_f32_e32 v183, v170
	v_cvt_f32_f16_sdwa v170, v173 dst_sel:DWORD dst_unused:UNUSED_PAD src0_sel:WORD_1
	v_exp_f32_e32 v32, v32
	v_max_f32_e32 v171, 0xc1f00000, v171
	v_mul_f32_e32 v171, 0xbfb8aa3b, v171
	v_max_f32_e32 v170, 0xc1f00000, v170
	v_mul_f32_e32 v170, 0xbfb8aa3b, v170
	v_add_f32_e32 v35, 1.0, v35
	v_exp_f32_e32 v184, v171
	v_exp_f32_e32 v185, v170
	v_rcp_f32_e32 v170, v35
	v_add_f32_e32 v35, 1.0, v180
	v_rcp_f32_e32 v171, v35
	v_add_f32_e32 v35, 1.0, v181
	v_add_f32_e32 v32, 1.0, v32
	v_rcp_f32_e32 v172, v35
	v_add_f32_e32 v35, 1.0, v182
	v_rcp_f32_e32 v32, v32
	v_rcp_f32_e32 v173, v35
	v_add_f32_e32 v35, 1.0, v183
	v_rcp_f32_e32 v180, v35
	v_add_f32_e32 v35, 1.0, v184
	v_rcp_f32_e32 v181, v35
	v_mov_b32_e32 v182, v129
	v_mov_b32_e32 v183, v130
	v_pk_mul_f32 v[170:171], v[182:183], v[170:171]
	v_pk_mov_b32 v[182:183], v[130:131], v[124:125] op_sel:[1,0]
	v_add_f32_e32 v35, 1.0, v185
	v_fma_mixlo_f16 v32, v128, v32, 0
	v_cvt_pk_f16_f32 v171, v170, v171
	v_pk_mul_f32 v[172:173], v[182:183], v[172:173]
	v_rcp_f32_e32 v35, v35
	v_pack_b32_f16 v170, v32, v171
	v_cvt_pk_f16_f32 v32, v172, v173
	v_mov_b32_e32 v172, v125
	v_mov_b32_e32 v173, v126
	v_pk_mul_f32 v[172:173], v[172:173], v[180:181]
	v_readlane_b32 s15, v252, 10
	v_cvt_pk_f16_f32 v173, v172, v173
	v_alignbit_b32 v172, v173, v32, 16
	v_lshrrev_b32_e32 v173, 16, v173
	v_lshl_add_u64 v[178:179], s[14:15], 0, v[178:179]
	v_alignbit_b32 v171, v32, v171, 16
	v_fma_mixhi_f16 v173, v127, v35, 0
	v_lshl_add_u64 v[178:179], v[178:179], 0, v[166:167]
	global_store_dwordx4 v[178:179], v[170:173], off
	v_cvt_f32_f16_sdwa v35, v174 dst_sel:DWORD dst_unused:UNUSED_PAD src0_sel:WORD_1
	v_cvt_f32_f16_e32 v32, v174
	v_cvt_f32_f16_e32 v170, v175
	v_cvt_f32_f16_sdwa v171, v175 dst_sel:DWORD dst_unused:UNUSED_PAD src0_sel:WORD_1
	v_max_f32_e32 v35, 0xc1f00000, v35
	v_mul_f32_e32 v35, 0xbfb8aa3b, v35
	v_max_f32_e32 v170, 0xc1f00000, v170
	v_mul_f32_e32 v170, 0xbfb8aa3b, v170
	v_exp_f32_e32 v172, v170
	v_max_f32_e32 v170, 0xc1f00000, v171
	v_mul_f32_e32 v170, 0xbfb8aa3b, v170
	v_cvt_f32_f16_e32 v171, v176
	v_exp_f32_e32 v173, v170
	v_cvt_f32_f16_sdwa v170, v176 dst_sel:DWORD dst_unused:UNUSED_PAD src0_sel:WORD_1
	v_exp_f32_e32 v35, v35
	v_max_f32_e32 v171, 0xc1f00000, v171
	v_mul_f32_e32 v171, 0xbfb8aa3b, v171
	v_max_f32_e32 v170, 0xc1f00000, v170
	v_mul_f32_e32 v170, 0xbfb8aa3b, v170
	v_exp_f32_e32 v174, v171
	v_cvt_f32_f16_e32 v171, v177
	v_exp_f32_e32 v175, v170
	v_cvt_f32_f16_sdwa v170, v177 dst_sel:DWORD dst_unused:UNUSED_PAD src0_sel:WORD_1
	v_max_f32_e32 v32, 0xc1f00000, v32
	v_mul_f32_e32 v32, 0xbfb8aa3b, v32
	v_exp_f32_e32 v32, v32
	v_max_f32_e32 v171, 0xc1f00000, v171
	v_max_f32_e32 v170, 0xc1f00000, v170
	v_mul_f32_e32 v171, 0xbfb8aa3b, v171
	v_mul_f32_e32 v170, 0xbfb8aa3b, v170
	v_add_f32_e32 v35, 1.0, v35
	v_exp_f32_e32 v176, v171
	v_exp_f32_e32 v177, v170
	v_rcp_f32_e32 v170, v35
	v_add_f32_e32 v35, 1.0, v172
	v_rcp_f32_e32 v171, v35
	v_add_f32_e32 v35, 1.0, v173
	v_add_f32_e32 v32, 1.0, v32
	v_rcp_f32_e32 v172, v35
	v_add_f32_e32 v35, 1.0, v174
	v_rcp_f32_e32 v32, v32
	v_rcp_f32_e32 v173, v35
	v_add_f32_e32 v35, 1.0, v175
	v_rcp_f32_e32 v174, v35
	v_add_f32_e32 v35, 1.0, v176
	v_rcp_f32_e32 v175, v35
	v_add_f32_e32 v35, 1.0, v177
	v_mov_b32_e32 v176, v97
	v_mov_b32_e32 v177, v98
	v_pk_mul_f32 v[170:171], v[176:177], v[170:171]
	v_pk_mov_b32 v[176:177], v[98:99], v[92:93] op_sel:[1,0]
	v_fma_mixlo_f16 v32, v96, v32, 0
	v_cvt_pk_f16_f32 v171, v170, v171
	v_pk_mul_f32 v[172:173], v[176:177], v[172:173]
	v_rcp_f32_e32 v35, v35
	v_pack_b32_f16 v170, v32, v171
	v_cvt_pk_f16_f32 v32, v172, v173
	v_mov_b32_e32 v172, v93
	v_mov_b32_e32 v173, v94
	v_pk_mul_f32 v[172:173], v[172:173], v[174:175]
	v_alignbit_b32 v171, v32, v171, 16
	v_cvt_pk_f16_f32 v173, v172, v173
	v_alignbit_b32 v172, v173, v32, 16
	v_lshrrev_b32_e32 v173, 16, v173
	v_fma_mixhi_f16 v173, v95, v35, 0
	v_cvt_f32_f16_e32 v32, v152
	v_cvt_f32_f16_sdwa v35, v152 dst_sel:DWORD dst_unused:UNUSED_PAD src0_sel:WORD_1
	v_cvt_f32_f16_e32 v152, v153
	v_cvt_f32_f16_sdwa v153, v153 dst_sel:DWORD dst_unused:UNUSED_PAD src0_sel:WORD_1
	global_store_dwordx4 v[178:179], v[170:173], off offset:256
	v_max_f32_e32 v35, 0xc1f00000, v35
	v_max_f32_e32 v152, 0xc1f00000, v152
	v_mul_f32_e32 v152, 0xbfb8aa3b, v152
	v_lshlrev_b64 v[170:171], 11, v[160:161]
	v_exp_f32_e32 v161, v152
	v_max_f32_e32 v152, 0xc1f00000, v153
	v_mul_f32_e32 v152, 0xbfb8aa3b, v152
	v_cvt_f32_f16_e32 v153, v154
	v_exp_f32_e32 v172, v152
	v_cvt_f32_f16_sdwa v152, v154 dst_sel:DWORD dst_unused:UNUSED_PAD src0_sel:WORD_1
	v_mul_f32_e32 v35, 0xbfb8aa3b, v35
	v_max_f32_e32 v153, 0xc1f00000, v153
	v_mul_f32_e32 v153, 0xbfb8aa3b, v153
	v_max_f32_e32 v152, 0xc1f00000, v152
	v_mul_f32_e32 v152, 0xbfb8aa3b, v152
	v_exp_f32_e32 v173, v153
	v_cvt_f32_f16_e32 v153, v155
	v_exp_f32_e32 v174, v152
	v_cvt_f32_f16_sdwa v152, v155 dst_sel:DWORD dst_unused:UNUSED_PAD src0_sel:WORD_1
	v_exp_f32_e32 v35, v35
	v_max_f32_e32 v32, 0xc1f00000, v32
	v_mul_f32_e32 v32, 0xbfb8aa3b, v32
	v_exp_f32_e32 v32, v32
	v_max_f32_e32 v153, 0xc1f00000, v153
	v_max_f32_e32 v152, 0xc1f00000, v152
	v_mul_f32_e32 v153, 0xbfb8aa3b, v153
	v_mul_f32_e32 v152, 0xbfb8aa3b, v152
	v_add_f32_e32 v35, 1.0, v35
	v_exp_f32_e32 v175, v153
	v_exp_f32_e32 v176, v152
	v_rcp_f32_e32 v152, v35
	v_add_f32_e32 v35, 1.0, v161
	v_rcp_f32_e32 v153, v35
	v_add_f32_e32 v35, 1.0, v172
	v_add_f32_e32 v32, 1.0, v32
	v_rcp_f32_e32 v154, v35
	v_add_f32_e32 v35, 1.0, v173
	v_rcp_f32_e32 v32, v32
	v_rcp_f32_e32 v155, v35
	v_add_f32_e32 v35, 1.0, v174
	v_rcp_f32_e32 v172, v35
	v_add_f32_e32 v35, 1.0, v175
	v_rcp_f32_e32 v173, v35
	v_mov_b32_e32 v174, v121
	v_mov_b32_e32 v175, v122
	v_pk_mul_f32 v[152:153], v[174:175], v[152:153]
	v_pk_mov_b32 v[174:175], v[122:123], v[116:117] op_sel:[1,0]
	v_add_f32_e32 v35, 1.0, v176
	v_fma_mixlo_f16 v32, v120, v32, 0
	v_cvt_pk_f16_f32 v153, v152, v153
	v_pk_mul_f32 v[154:155], v[174:175], v[154:155]
	v_rcp_f32_e32 v35, v35
	v_pack_b32_f16 v152, v32, v153
	v_cvt_pk_f16_f32 v32, v154, v155
	v_mov_b32_e32 v154, v117
	v_mov_b32_e32 v155, v118
	v_pk_mul_f32 v[154:155], v[154:155], v[172:173]
	v_alignbit_b32 v153, v32, v153, 16
	v_cvt_pk_f16_f32 v155, v154, v155
	v_alignbit_b32 v154, v155, v32, 16
	v_lshrrev_b32_e32 v155, 16, v155
	v_fma_mixhi_f16 v155, v119, v35, 0
	v_cvt_f32_f16_e32 v32, v148
	v_cvt_f32_f16_sdwa v35, v148 dst_sel:DWORD dst_unused:UNUSED_PAD src0_sel:WORD_1
	v_cvt_f32_f16_e32 v148, v149
	v_cvt_f32_f16_sdwa v149, v149 dst_sel:DWORD dst_unused:UNUSED_PAD src0_sel:WORD_1
	v_lshl_add_u64 v[170:171], s[14:15], 0, v[170:171]
	v_lshl_add_u64 v[170:171], v[170:171], 0, v[166:167]
	v_max_f32_e32 v148, 0xc1f00000, v148
	v_mul_f32_e32 v148, 0xbfb8aa3b, v148
	global_store_dwordx4 v[170:171], v[152:155], off
	v_max_f32_e32 v35, 0xc1f00000, v35
	v_mul_f32_e32 v35, 0xbfb8aa3b, v35
	v_exp_f32_e32 v152, v148
	v_max_f32_e32 v148, 0xc1f00000, v149
	v_mul_f32_e32 v148, 0xbfb8aa3b, v148
	v_cvt_f32_f16_e32 v149, v150
	v_exp_f32_e32 v153, v148
	v_cvt_f32_f16_sdwa v148, v150 dst_sel:DWORD dst_unused:UNUSED_PAD src0_sel:WORD_1
	v_exp_f32_e32 v35, v35
	v_max_f32_e32 v149, 0xc1f00000, v149
	v_mul_f32_e32 v149, 0xbfb8aa3b, v149
	v_max_f32_e32 v148, 0xc1f00000, v148
	v_mul_f32_e32 v148, 0xbfb8aa3b, v148
	v_exp_f32_e32 v154, v149
	v_cvt_f32_f16_e32 v149, v151
	v_exp_f32_e32 v155, v148
	v_cvt_f32_f16_sdwa v148, v151 dst_sel:DWORD dst_unused:UNUSED_PAD src0_sel:WORD_1
	v_max_f32_e32 v32, 0xc1f00000, v32
	v_mul_f32_e32 v32, 0xbfb8aa3b, v32
	v_exp_f32_e32 v32, v32
	v_max_f32_e32 v149, 0xc1f00000, v149
	v_max_f32_e32 v148, 0xc1f00000, v148
	v_mul_f32_e32 v149, 0xbfb8aa3b, v149
	v_mul_f32_e32 v148, 0xbfb8aa3b, v148
	v_add_f32_e32 v35, 1.0, v35
	v_exp_f32_e32 v161, v149
	v_exp_f32_e32 v172, v148
	v_rcp_f32_e32 v148, v35
	v_add_f32_e32 v35, 1.0, v152
	v_rcp_f32_e32 v149, v35
	v_add_f32_e32 v35, 1.0, v153
	v_add_f32_e32 v32, 1.0, v32
	v_rcp_f32_e32 v150, v35
	v_add_f32_e32 v35, 1.0, v154
	v_rcp_f32_e32 v32, v32
	v_rcp_f32_e32 v151, v35
	v_add_f32_e32 v35, 1.0, v155
	v_rcp_f32_e32 v152, v35
	v_add_f32_e32 v35, 1.0, v161
	v_rcp_f32_e32 v153, v35
	v_mov_b32_e32 v154, v89
	v_mov_b32_e32 v155, v90
	v_pk_mul_f32 v[148:149], v[154:155], v[148:149]
	v_pk_mov_b32 v[154:155], v[90:91], v[84:85] op_sel:[1,0]
	v_add_f32_e32 v35, 1.0, v172
	v_fma_mixlo_f16 v32, v88, v32, 0
	v_cvt_pk_f16_f32 v149, v148, v149
	v_pk_mul_f32 v[150:151], v[154:155], v[150:151]
	v_rcp_f32_e32 v35, v35
	v_pack_b32_f16 v148, v32, v149
	v_cvt_pk_f16_f32 v32, v150, v151
	v_mov_b32_e32 v150, v85
	v_mov_b32_e32 v151, v86
	v_pk_mul_f32 v[150:151], v[150:151], v[152:153]
	v_alignbit_b32 v149, v32, v149, 16
	v_cvt_pk_f16_f32 v151, v150, v151
	v_alignbit_b32 v150, v151, v32, 16
	v_lshrrev_b32_e32 v151, 16, v151
	v_fma_mixhi_f16 v151, v87, v35, 0
	v_cvt_f32_f16_e32 v32, v144
	v_cvt_f32_f16_sdwa v35, v144 dst_sel:DWORD dst_unused:UNUSED_PAD src0_sel:WORD_1
	v_cvt_f32_f16_e32 v144, v145
	v_cvt_f32_f16_sdwa v145, v145 dst_sel:DWORD dst_unused:UNUSED_PAD src0_sel:WORD_1
	global_store_dwordx4 v[170:171], v[148:151], off offset:256
	v_max_f32_e32 v35, 0xc1f00000, v35
	v_max_f32_e32 v144, 0xc1f00000, v144
	v_mul_f32_e32 v144, 0xbfb8aa3b, v144
	v_exp_f32_e32 v150, v144
	v_max_f32_e32 v144, 0xc1f00000, v145
	v_mul_f32_e32 v144, 0xbfb8aa3b, v144
	v_cvt_f32_f16_e32 v145, v146
	v_exp_f32_e32 v151, v144
	v_cvt_f32_f16_sdwa v144, v146 dst_sel:DWORD dst_unused:UNUSED_PAD src0_sel:WORD_1
	v_mul_f32_e32 v35, 0xbfb8aa3b, v35
	v_max_f32_e32 v145, 0xc1f00000, v145
	v_mul_f32_e32 v145, 0xbfb8aa3b, v145
	v_max_f32_e32 v144, 0xc1f00000, v144
	v_mul_f32_e32 v144, 0xbfb8aa3b, v144
	v_exp_f32_e32 v152, v145
	v_cvt_f32_f16_e32 v145, v147
	v_exp_f32_e32 v153, v144
	v_cvt_f32_f16_sdwa v144, v147 dst_sel:DWORD dst_unused:UNUSED_PAD src0_sel:WORD_1
	v_exp_f32_e32 v35, v35
	v_max_f32_e32 v32, 0xc1f00000, v32
	v_mul_f32_e32 v32, 0xbfb8aa3b, v32
	v_exp_f32_e32 v32, v32
	v_max_f32_e32 v145, 0xc1f00000, v145
	v_max_f32_e32 v144, 0xc1f00000, v144
	v_mul_f32_e32 v145, 0xbfb8aa3b, v145
	v_mul_f32_e32 v144, 0xbfb8aa3b, v144
	v_add_f32_e32 v35, 1.0, v35
	v_exp_f32_e32 v154, v145
	v_exp_f32_e32 v155, v144
	v_rcp_f32_e32 v144, v35
	v_add_f32_e32 v35, 1.0, v150
	v_rcp_f32_e32 v145, v35
	v_add_f32_e32 v35, 1.0, v151
	v_add_f32_e32 v32, 1.0, v32
	v_rcp_f32_e32 v146, v35
	v_add_f32_e32 v35, 1.0, v152
	v_rcp_f32_e32 v32, v32
	v_rcp_f32_e32 v147, v35
	v_add_f32_e32 v35, 1.0, v153
	v_rcp_f32_e32 v150, v35
	v_add_f32_e32 v35, 1.0, v154
	v_rcp_f32_e32 v151, v35
	v_mov_b32_e32 v152, v113
	v_mov_b32_e32 v153, v114
	v_pk_mul_f32 v[144:145], v[152:153], v[144:145]
	v_pk_mov_b32 v[152:153], v[114:115], v[108:109] op_sel:[1,0]
	v_add_f32_e32 v35, 1.0, v155
	v_fma_mixlo_f16 v32, v112, v32, 0
	v_cvt_pk_f16_f32 v145, v144, v145
	v_pk_mul_f32 v[146:147], v[152:153], v[146:147]
	v_rcp_f32_e32 v35, v35
	v_pack_b32_f16 v144, v32, v145
	v_cvt_pk_f16_f32 v32, v146, v147
	v_mov_b32_e32 v146, v109
	v_mov_b32_e32 v147, v110
	v_pk_mul_f32 v[146:147], v[146:147], v[150:151]
	v_alignbit_b32 v145, v32, v145, 16
	v_cvt_pk_f16_f32 v147, v146, v147
	v_alignbit_b32 v146, v147, v32, 16
	v_lshrrev_b32_e32 v147, 16, v147
	v_fma_mixhi_f16 v147, v111, v35, 0
	v_cvt_f32_f16_e32 v32, v140
	v_cvt_f32_f16_sdwa v35, v140 dst_sel:DWORD dst_unused:UNUSED_PAD src0_sel:WORD_1
	v_cvt_f32_f16_e32 v140, v141
	v_cvt_f32_f16_sdwa v141, v141 dst_sel:DWORD dst_unused:UNUSED_PAD src0_sel:WORD_1
	v_lshlrev_b64 v[148:149], 11, v[162:163]
	v_lshl_add_u64 v[148:149], s[14:15], 0, v[148:149]
	v_max_f32_e32 v140, 0xc1f00000, v140
	v_lshl_add_u64 v[148:149], v[148:149], 0, v[166:167]
	v_mul_f32_e32 v140, 0xbfb8aa3b, v140
	global_store_dwordx4 v[148:149], v[144:147], off
	v_max_f32_e32 v35, 0xc1f00000, v35
	v_mul_f32_e32 v35, 0xbfb8aa3b, v35
	v_exp_f32_e32 v144, v140
	v_max_f32_e32 v140, 0xc1f00000, v141
	v_mul_f32_e32 v140, 0xbfb8aa3b, v140
	v_cvt_f32_f16_e32 v141, v142
	v_exp_f32_e32 v145, v140
	v_cvt_f32_f16_sdwa v140, v142 dst_sel:DWORD dst_unused:UNUSED_PAD src0_sel:WORD_1
	v_exp_f32_e32 v35, v35
	v_max_f32_e32 v141, 0xc1f00000, v141
	v_mul_f32_e32 v141, 0xbfb8aa3b, v141
	v_max_f32_e32 v140, 0xc1f00000, v140
	v_mul_f32_e32 v140, 0xbfb8aa3b, v140
	v_exp_f32_e32 v146, v141
	v_cvt_f32_f16_e32 v141, v143
	v_exp_f32_e32 v147, v140
	v_cvt_f32_f16_sdwa v140, v143 dst_sel:DWORD dst_unused:UNUSED_PAD src0_sel:WORD_1
	v_max_f32_e32 v32, 0xc1f00000, v32
	v_mul_f32_e32 v32, 0xbfb8aa3b, v32
	v_exp_f32_e32 v32, v32
	v_max_f32_e32 v141, 0xc1f00000, v141
	v_max_f32_e32 v140, 0xc1f00000, v140
	v_mul_f32_e32 v141, 0xbfb8aa3b, v141
	v_mul_f32_e32 v140, 0xbfb8aa3b, v140
	v_add_f32_e32 v35, 1.0, v35
	v_exp_f32_e32 v150, v141
	v_exp_f32_e32 v151, v140
	v_rcp_f32_e32 v140, v35
	v_add_f32_e32 v35, 1.0, v144
	v_rcp_f32_e32 v141, v35
	v_add_f32_e32 v35, 1.0, v145
	v_add_f32_e32 v32, 1.0, v32
	v_rcp_f32_e32 v142, v35
	v_add_f32_e32 v35, 1.0, v146
	v_rcp_f32_e32 v32, v32
	v_rcp_f32_e32 v143, v35
	v_add_f32_e32 v35, 1.0, v147
	v_rcp_f32_e32 v144, v35
	v_add_f32_e32 v35, 1.0, v150
	v_rcp_f32_e32 v145, v35
	v_mov_b32_e32 v146, v81
	v_mov_b32_e32 v147, v82
	v_pk_mul_f32 v[140:141], v[146:147], v[140:141]
	v_pk_mov_b32 v[146:147], v[82:83], v[76:77] op_sel:[1,0]
	v_add_f32_e32 v35, 1.0, v151
	v_fma_mixlo_f16 v32, v80, v32, 0
	v_cvt_pk_f16_f32 v141, v140, v141
	v_pk_mul_f32 v[142:143], v[146:147], v[142:143]
	v_rcp_f32_e32 v35, v35
	v_pack_b32_f16 v140, v32, v141
	v_cvt_pk_f16_f32 v32, v142, v143
	v_mov_b32_e32 v142, v77
	v_mov_b32_e32 v143, v78
	v_pk_mul_f32 v[142:143], v[142:143], v[144:145]
	v_alignbit_b32 v141, v32, v141, 16
	v_cvt_pk_f16_f32 v143, v142, v143
	v_alignbit_b32 v142, v143, v32, 16
	v_lshrrev_b32_e32 v143, 16, v143
	v_fma_mixhi_f16 v143, v79, v35, 0
	v_cvt_f32_f16_e32 v32, v136
	v_cvt_f32_f16_sdwa v35, v136 dst_sel:DWORD dst_unused:UNUSED_PAD src0_sel:WORD_1
	v_cvt_f32_f16_e32 v136, v137
	v_cvt_f32_f16_sdwa v137, v137 dst_sel:DWORD dst_unused:UNUSED_PAD src0_sel:WORD_1
	global_store_dwordx4 v[148:149], v[140:143], off offset:256
	v_max_f32_e32 v35, 0xc1f00000, v35
	v_max_f32_e32 v136, 0xc1f00000, v136
	v_mul_f32_e32 v136, 0xbfb8aa3b, v136
	v_exp_f32_e32 v142, v136
	v_max_f32_e32 v136, 0xc1f00000, v137
	v_mul_f32_e32 v136, 0xbfb8aa3b, v136
	v_cvt_f32_f16_e32 v137, v138
	v_exp_f32_e32 v143, v136
	v_cvt_f32_f16_sdwa v136, v138 dst_sel:DWORD dst_unused:UNUSED_PAD src0_sel:WORD_1
	v_mul_f32_e32 v35, 0xbfb8aa3b, v35
	v_max_f32_e32 v137, 0xc1f00000, v137
	v_mul_f32_e32 v137, 0xbfb8aa3b, v137
	v_max_f32_e32 v136, 0xc1f00000, v136
	v_mul_f32_e32 v136, 0xbfb8aa3b, v136
	v_exp_f32_e32 v144, v137
	v_cvt_f32_f16_e32 v137, v139
	v_exp_f32_e32 v145, v136
	v_cvt_f32_f16_sdwa v136, v139 dst_sel:DWORD dst_unused:UNUSED_PAD src0_sel:WORD_1
	v_exp_f32_e32 v35, v35
	v_max_f32_e32 v32, 0xc1f00000, v32
	v_mul_f32_e32 v32, 0xbfb8aa3b, v32
	v_exp_f32_e32 v32, v32
	v_max_f32_e32 v137, 0xc1f00000, v137
	v_max_f32_e32 v136, 0xc1f00000, v136
	v_mul_f32_e32 v137, 0xbfb8aa3b, v137
	v_mul_f32_e32 v136, 0xbfb8aa3b, v136
	v_add_f32_e32 v35, 1.0, v35
	v_exp_f32_e32 v146, v137
	v_exp_f32_e32 v147, v136
	v_rcp_f32_e32 v136, v35
	v_add_f32_e32 v35, 1.0, v142
	v_rcp_f32_e32 v137, v35
	v_add_f32_e32 v35, 1.0, v143
	v_add_f32_e32 v32, 1.0, v32
	v_rcp_f32_e32 v138, v35
	v_add_f32_e32 v35, 1.0, v144
	v_rcp_f32_e32 v32, v32
	v_rcp_f32_e32 v139, v35
	v_add_f32_e32 v35, 1.0, v145
	v_rcp_f32_e32 v142, v35
	v_add_f32_e32 v35, 1.0, v146
	v_rcp_f32_e32 v143, v35
	v_mov_b32_e32 v144, v105
	v_mov_b32_e32 v145, v106
	v_pk_mul_f32 v[136:137], v[144:145], v[136:137]
	v_pk_mov_b32 v[144:145], v[106:107], v[100:101] op_sel:[1,0]
	v_add_f32_e32 v35, 1.0, v147
	v_fma_mixlo_f16 v32, v104, v32, 0
	v_cvt_pk_f16_f32 v137, v136, v137
	v_pk_mul_f32 v[138:139], v[144:145], v[138:139]
	v_rcp_f32_e32 v35, v35
	v_pack_b32_f16 v136, v32, v137
	v_cvt_pk_f16_f32 v32, v138, v139
	v_mov_b32_e32 v138, v101
	v_mov_b32_e32 v139, v102
	v_pk_mul_f32 v[138:139], v[138:139], v[142:143]
	v_alignbit_b32 v137, v32, v137, 16
	v_cvt_pk_f16_f32 v139, v138, v139
	v_alignbit_b32 v138, v139, v32, 16
	v_lshrrev_b32_e32 v139, 16, v139
	v_fma_mixhi_f16 v139, v103, v35, 0
	v_cvt_f32_f16_e32 v32, v132
	v_cvt_f32_f16_sdwa v35, v132 dst_sel:DWORD dst_unused:UNUSED_PAD src0_sel:WORD_1
	v_cvt_f32_f16_e32 v132, v133
	v_cvt_f32_f16_sdwa v133, v133 dst_sel:DWORD dst_unused:UNUSED_PAD src0_sel:WORD_1
	v_lshlrev_b64 v[140:141], 11, v[164:165]
	v_lshl_add_u64 v[140:141], s[14:15], 0, v[140:141]
	v_max_f32_e32 v132, 0xc1f00000, v132
	v_lshl_add_u64 v[140:141], v[140:141], 0, v[166:167]
	v_mul_f32_e32 v132, 0xbfb8aa3b, v132
	global_store_dwordx4 v[140:141], v[136:139], off
	v_max_f32_e32 v35, 0xc1f00000, v35
	v_mul_f32_e32 v35, 0xbfb8aa3b, v35
	v_exp_f32_e32 v136, v132
	v_max_f32_e32 v132, 0xc1f00000, v133
	v_mul_f32_e32 v132, 0xbfb8aa3b, v132
	v_cvt_f32_f16_e32 v133, v134
	v_exp_f32_e32 v137, v132
	v_cvt_f32_f16_sdwa v132, v134 dst_sel:DWORD dst_unused:UNUSED_PAD src0_sel:WORD_1
	v_exp_f32_e32 v35, v35
	v_max_f32_e32 v133, 0xc1f00000, v133
	v_mul_f32_e32 v133, 0xbfb8aa3b, v133
	v_max_f32_e32 v132, 0xc1f00000, v132
	v_mul_f32_e32 v132, 0xbfb8aa3b, v132
	v_exp_f32_e32 v138, v133
	v_cvt_f32_f16_e32 v133, v135
	v_exp_f32_e32 v139, v132
	v_cvt_f32_f16_sdwa v132, v135 dst_sel:DWORD dst_unused:UNUSED_PAD src0_sel:WORD_1
	v_max_f32_e32 v32, 0xc1f00000, v32
	v_mul_f32_e32 v32, 0xbfb8aa3b, v32
	v_exp_f32_e32 v32, v32
	v_max_f32_e32 v133, 0xc1f00000, v133
	v_max_f32_e32 v132, 0xc1f00000, v132
	v_mul_f32_e32 v133, 0xbfb8aa3b, v133
	v_mul_f32_e32 v132, 0xbfb8aa3b, v132
	v_add_f32_e32 v35, 1.0, v35
	v_exp_f32_e32 v142, v133
	v_exp_f32_e32 v143, v132
	v_rcp_f32_e32 v132, v35
	v_add_f32_e32 v35, 1.0, v136
	v_rcp_f32_e32 v133, v35
	v_add_f32_e32 v35, 1.0, v137
	v_add_f32_e32 v32, 1.0, v32
	v_rcp_f32_e32 v134, v35
	v_add_f32_e32 v35, 1.0, v138
	v_rcp_f32_e32 v32, v32
	v_rcp_f32_e32 v135, v35
	v_add_f32_e32 v35, 1.0, v139
	v_rcp_f32_e32 v136, v35
	v_add_f32_e32 v35, 1.0, v142
	v_rcp_f32_e32 v137, v35
	v_mov_b32_e32 v138, v73
	v_mov_b32_e32 v139, v74
	v_pk_mul_f32 v[132:133], v[138:139], v[132:133]
	v_pk_mov_b32 v[138:139], v[74:75], v[68:69] op_sel:[1,0]
	v_add_f32_e32 v35, 1.0, v143
	v_fma_mixlo_f16 v32, v72, v32, 0
	v_cvt_pk_f16_f32 v133, v132, v133
	v_pk_mul_f32 v[134:135], v[138:139], v[134:135]
	v_rcp_f32_e32 v35, v35
	v_pack_b32_f16 v132, v32, v133
	v_cvt_pk_f16_f32 v32, v134, v135
	v_mov_b32_e32 v134, v69
	v_mov_b32_e32 v135, v70
	v_pk_mul_f32 v[134:135], v[134:135], v[136:137]
	v_alignbit_b32 v133, v32, v133, 16
	v_cvt_pk_f16_f32 v135, v134, v135
	v_alignbit_b32 v134, v135, v32, 16
	v_lshrrev_b32_e32 v135, 16, v135
	v_fma_mixhi_f16 v135, v71, v35, 0
	global_store_dwordx4 v[140:141], v[132:135], off offset:256
	v_add_u32_e32 v184, 0x80, v34
	s_nop 0
	v_mad_i64_i32 v[132:133], s[12:13], v184, s33, v[168:169]
	v_lshl_add_u64 v[132:133], v[132:133], 0, v[166:167]
	v_add_u32_e32 v174, 0x90, v34
	v_lshl_add_u64 v[134:135], v[132:133], 0, s[16:17]
	v_mad_i64_i32 v[136:137], s[12:13], v174, s33, v[168:169]
	v_add_co_u32_e32 v132, vcc, s1, v132
	v_lshl_add_u64 v[136:137], v[136:137], 0, v[166:167]
	v_add_u32_e32 v172, 0xa0, v34
	v_addc_co_u32_e32 v133, vcc, 0, v133, vcc
	v_lshl_add_u64 v[138:139], v[136:137], 0, s[16:17]
	v_mad_i64_i32 v[140:141], s[12:13], v172, s33, v[168:169]
	v_add_co_u32_e32 v136, vcc, s1, v136
	v_lshl_add_u64 v[140:141], v[140:141], 0, v[166:167]
	v_add_u32_e32 v170, 0xb0, v34
	v_addc_co_u32_e32 v137, vcc, 0, v137, vcc
	v_mad_i64_i32 v[144:145], s[12:13], v170, s33, v[168:169]
	global_load_dwordx4 v[176:179], v[132:133], off offset:2048
	global_load_dwordx4 v[152:155], v[136:137], off offset:2048
	global_load_dwordx4 v[180:183], v[134:135], off offset:256
	global_load_dwordx4 v[148:151], v[138:139], off offset:256
	v_add_co_u32_e32 v132, vcc, s1, v140
	v_lshl_add_u64 v[144:145], v[144:145], 0, v[166:167]
	s_nop 0
	v_addc_co_u32_e32 v133, vcc, 0, v141, vcc
	v_add_co_u32_e32 v134, vcc, s1, v144
	v_lshl_add_u64 v[142:143], v[140:141], 0, s[16:17]
	s_nop 0
	v_addc_co_u32_e32 v135, vcc, 0, v145, vcc
	v_lshl_add_u64 v[168:169], v[144:145], 0, s[16:17]
	global_load_dwordx4 v[144:147], v[132:133], off offset:2048
	global_load_dwordx4 v[136:139], v[134:135], off offset:2048
	s_nop 0
	global_load_dwordx4 v[140:143], v[142:143], off offset:256
	s_nop 0
	global_load_dwordx4 v[132:135], v[168:169], off offset:256
	v_ashrrev_i32_e32 v185, 31, v184
	v_ashrrev_i32_e32 v175, 31, v174
	v_ashrrev_i32_e32 v173, 31, v172
	v_ashrrev_i32_e32 v171, 31, v170
	s_waitcnt vmcnt(0)
	v_cvt_f32_f16_e32 v32, v176
	v_cvt_f32_f16_sdwa v35, v176 dst_sel:DWORD dst_unused:UNUSED_PAD src0_sel:WORD_1
	v_cvt_f32_f16_sdwa v176, v178 dst_sel:DWORD dst_unused:UNUSED_PAD src0_sel:WORD_1
	v_cvt_f32_f16_e32 v161, v177
	v_cvt_f32_f16_sdwa v163, v177 dst_sel:DWORD dst_unused:UNUSED_PAD src0_sel:WORD_1
	v_cvt_f32_f16_e32 v165, v178
	v_max_f32_e32 v176, 0xc1f00000, v176
	v_max_f32_e32 v35, 0xc1f00000, v35
	v_mul_f32_e32 v176, 0xbfb8aa3b, v176
	v_lshlrev_b64 v[168:169], 11, v[184:185]
	v_mul_f32_e32 v35, 0xbfb8aa3b, v35
	v_max_f32_e32 v161, 0xc1f00000, v161
	v_cvt_f32_f16_e32 v177, v179
	v_exp_f32_e32 v184, v176
	v_cvt_f32_f16_sdwa v176, v179 dst_sel:DWORD dst_unused:UNUSED_PAD src0_sel:WORD_1
	v_exp_f32_e32 v35, v35
	v_mul_f32_e32 v161, 0xbfb8aa3b, v161
	v_max_f32_e32 v163, 0xc1f00000, v163
	v_max_f32_e32 v32, 0xc1f00000, v32
	v_exp_f32_e32 v161, v161
	v_mul_f32_e32 v163, 0xbfb8aa3b, v163
	v_max_f32_e32 v165, 0xc1f00000, v165
	v_mul_f32_e32 v32, 0xbfb8aa3b, v32
	v_exp_f32_e32 v163, v163
	v_mul_f32_e32 v165, 0xbfb8aa3b, v165
	v_exp_f32_e32 v32, v32
	v_exp_f32_e32 v165, v165
	v_max_f32_e32 v177, 0xc1f00000, v177
	v_max_f32_e32 v176, 0xc1f00000, v176
	v_mul_f32_e32 v177, 0xbfb8aa3b, v177
	v_mul_f32_e32 v176, 0xbfb8aa3b, v176
	v_add_f32_e32 v35, 1.0, v35
	v_exp_f32_e32 v185, v177
	v_exp_f32_e32 v186, v176
	v_rcp_f32_e32 v176, v35
	v_add_f32_e32 v35, 1.0, v161
	v_rcp_f32_e32 v177, v35
	v_add_f32_e32 v35, 1.0, v163
	v_add_f32_e32 v32, 1.0, v32
	v_rcp_f32_e32 v178, v35
	v_add_f32_e32 v35, 1.0, v165
	v_rcp_f32_e32 v32, v32
	v_rcp_f32_e32 v179, v35
	v_add_f32_e32 v35, 1.0, v184
	v_rcp_f32_e32 v184, v35
	v_add_f32_e32 v35, 1.0, v185
	v_rcp_f32_e32 v185, v35
	v_add_f32_e32 v35, 1.0, v186
	v_mov_b32_e32 v186, v65
	v_mov_b32_e32 v187, v66
	v_pk_mul_f32 v[176:177], v[186:187], v[176:177]
	v_pk_mov_b32 v[186:187], v[66:67], v[60:61] op_sel:[1,0]
	v_fma_mixlo_f16 v32, v64, v32, 0
	v_cvt_pk_f16_f32 v161, v176, v177
	v_pk_mul_f32 v[178:179], v[186:187], v[178:179]
	v_rcp_f32_e32 v35, v35
	v_pack_b32_f16 v176, v32, v161
	v_cvt_pk_f16_f32 v32, v178, v179
	v_mov_b32_e32 v178, v61
	v_mov_b32_e32 v179, v62
	v_pk_mul_f32 v[178:179], v[178:179], v[184:185]
	v_alignbit_b32 v177, v32, v161, 16
	v_cvt_pk_f16_f32 v161, v178, v179
	v_lshrrev_b32_e32 v179, 16, v161
	v_lshl_add_u64 v[168:169], s[14:15], 0, v[168:169]
	v_alignbit_b32 v178, v161, v32, 16
	v_fma_mixhi_f16 v179, v63, v35, 0
	v_lshl_add_u64 v[168:169], v[168:169], 0, v[166:167]
	global_store_dwordx4 v[168:169], v[176:179], off
	v_cvt_f32_f16_sdwa v35, v180 dst_sel:DWORD dst_unused:UNUSED_PAD src0_sel:WORD_1
	v_cvt_f32_f16_e32 v161, v181
	v_cvt_f32_f16_sdwa v176, v182 dst_sel:DWORD dst_unused:UNUSED_PAD src0_sel:WORD_1
	v_cvt_f32_f16_sdwa v163, v181 dst_sel:DWORD dst_unused:UNUSED_PAD src0_sel:WORD_1
	v_cvt_f32_f16_e32 v32, v180
	v_cvt_f32_f16_e32 v165, v182
	v_max_f32_e32 v176, 0xc1f00000, v176
	v_max_f32_e32 v35, 0xc1f00000, v35
	v_mul_f32_e32 v176, 0xbfb8aa3b, v176
	v_mul_f32_e32 v35, 0xbfb8aa3b, v35
	v_max_f32_e32 v161, 0xc1f00000, v161
	v_cvt_f32_f16_e32 v177, v183
	v_exp_f32_e32 v180, v176
	v_cvt_f32_f16_sdwa v176, v183 dst_sel:DWORD dst_unused:UNUSED_PAD src0_sel:WORD_1
	v_exp_f32_e32 v35, v35
	v_mul_f32_e32 v161, 0xbfb8aa3b, v161
	v_max_f32_e32 v163, 0xc1f00000, v163
	v_max_f32_e32 v32, 0xc1f00000, v32
	v_exp_f32_e32 v161, v161
	v_mul_f32_e32 v163, 0xbfb8aa3b, v163
	v_max_f32_e32 v165, 0xc1f00000, v165
	v_mul_f32_e32 v32, 0xbfb8aa3b, v32
	v_exp_f32_e32 v163, v163
	v_mul_f32_e32 v165, 0xbfb8aa3b, v165
	v_exp_f32_e32 v32, v32
	v_exp_f32_e32 v165, v165
	v_max_f32_e32 v177, 0xc1f00000, v177
	v_max_f32_e32 v176, 0xc1f00000, v176
	v_mul_f32_e32 v177, 0xbfb8aa3b, v177
	v_mul_f32_e32 v176, 0xbfb8aa3b, v176
	v_add_f32_e32 v35, 1.0, v35
	v_exp_f32_e32 v181, v177
	v_exp_f32_e32 v182, v176
	v_rcp_f32_e32 v176, v35
	v_add_f32_e32 v35, 1.0, v161
	v_rcp_f32_e32 v177, v35
	v_add_f32_e32 v35, 1.0, v163
	v_add_f32_e32 v32, 1.0, v32
	v_rcp_f32_e32 v178, v35
	v_add_f32_e32 v35, 1.0, v165
	v_rcp_f32_e32 v32, v32
	v_rcp_f32_e32 v179, v35
	v_add_f32_e32 v35, 1.0, v180
	v_rcp_f32_e32 v180, v35
	v_add_f32_e32 v35, 1.0, v181
	v_rcp_f32_e32 v181, v35
	v_add_f32_e32 v35, 1.0, v182
	v_mov_b32_e32 v182, v29
	v_mov_b32_e32 v183, v30
	v_pk_mul_f32 v[176:177], v[182:183], v[176:177]
	v_pk_mov_b32 v[182:183], v[30:31], v[24:25] op_sel:[1,0]
	v_fma_mixlo_f16 v32, v28, v32, 0
	v_cvt_pk_f16_f32 v161, v176, v177
	v_pk_mul_f32 v[178:179], v[182:183], v[178:179]
	v_rcp_f32_e32 v35, v35
	v_pack_b32_f16 v176, v32, v161
	v_cvt_pk_f16_f32 v32, v178, v179
	v_mov_b32_e32 v178, v25
	v_mov_b32_e32 v179, v26
	v_pk_mul_f32 v[178:179], v[178:179], v[180:181]
	v_alignbit_b32 v177, v32, v161, 16
	v_cvt_pk_f16_f32 v161, v178, v179
	v_lshrrev_b32_e32 v179, 16, v161
	v_alignbit_b32 v178, v161, v32, 16
	v_fma_mixhi_f16 v179, v27, v35, 0
	v_cvt_f32_f16_e32 v32, v152
	v_cvt_f32_f16_sdwa v35, v152 dst_sel:DWORD dst_unused:UNUSED_PAD src0_sel:WORD_1
	v_cvt_f32_f16_e32 v152, v153
	v_cvt_f32_f16_sdwa v153, v153 dst_sel:DWORD dst_unused:UNUSED_PAD src0_sel:WORD_1
	global_store_dwordx4 v[168:169], v[176:179], off offset:256
	v_max_f32_e32 v35, 0xc1f00000, v35
	v_max_f32_e32 v152, 0xc1f00000, v152
	v_mul_f32_e32 v152, 0xbfb8aa3b, v152
	v_exp_f32_e32 v161, v152
	v_max_f32_e32 v152, 0xc1f00000, v153
	v_mul_f32_e32 v152, 0xbfb8aa3b, v152
	v_cvt_f32_f16_e32 v153, v154
	v_exp_f32_e32 v163, v152
	v_cvt_f32_f16_sdwa v152, v154 dst_sel:DWORD dst_unused:UNUSED_PAD src0_sel:WORD_1
	v_lshlrev_b64 v[168:169], 11, v[174:175]
	v_max_f32_e32 v153, 0xc1f00000, v153
	v_mul_f32_e32 v153, 0xbfb8aa3b, v153
	v_max_f32_e32 v152, 0xc1f00000, v152
	v_mul_f32_e32 v152, 0xbfb8aa3b, v152
	v_mul_f32_e32 v35, 0xbfb8aa3b, v35
	v_exp_f32_e32 v165, v153
	v_cvt_f32_f16_e32 v153, v155
	v_exp_f32_e32 v174, v152
	v_cvt_f32_f16_sdwa v152, v155 dst_sel:DWORD dst_unused:UNUSED_PAD src0_sel:WORD_1
	v_exp_f32_e32 v35, v35
	v_max_f32_e32 v32, 0xc1f00000, v32
	v_mul_f32_e32 v32, 0xbfb8aa3b, v32
	v_exp_f32_e32 v32, v32
	v_max_f32_e32 v153, 0xc1f00000, v153
	v_max_f32_e32 v152, 0xc1f00000, v152
	v_mul_f32_e32 v153, 0xbfb8aa3b, v153
	v_mul_f32_e32 v152, 0xbfb8aa3b, v152
	v_add_f32_e32 v35, 1.0, v35
	v_exp_f32_e32 v175, v153
	v_exp_f32_e32 v176, v152
	v_rcp_f32_e32 v152, v35
	v_add_f32_e32 v35, 1.0, v161
	v_rcp_f32_e32 v153, v35
	v_add_f32_e32 v35, 1.0, v163
	v_add_f32_e32 v32, 1.0, v32
	v_rcp_f32_e32 v154, v35
	v_add_f32_e32 v35, 1.0, v165
	v_rcp_f32_e32 v32, v32
	v_rcp_f32_e32 v155, v35
	v_add_f32_e32 v35, 1.0, v174
	v_rcp_f32_e32 v174, v35
	v_add_f32_e32 v35, 1.0, v175
	v_rcp_f32_e32 v175, v35
	v_add_f32_e32 v35, 1.0, v176
	v_mov_b32_e32 v176, v57
	v_mov_b32_e32 v177, v58
	v_pk_mul_f32 v[152:153], v[176:177], v[152:153]
	v_pk_mov_b32 v[176:177], v[58:59], v[52:53] op_sel:[1,0]
	v_fma_mixlo_f16 v32, v56, v32, 0
	v_cvt_pk_f16_f32 v153, v152, v153
	v_pk_mul_f32 v[154:155], v[176:177], v[154:155]
	v_rcp_f32_e32 v35, v35
	v_pack_b32_f16 v152, v32, v153
	v_cvt_pk_f16_f32 v32, v154, v155
	v_mov_b32_e32 v154, v53
	v_mov_b32_e32 v155, v54
	v_pk_mul_f32 v[154:155], v[154:155], v[174:175]
	v_alignbit_b32 v153, v32, v153, 16
	v_cvt_pk_f16_f32 v155, v154, v155
	v_alignbit_b32 v154, v155, v32, 16
	v_lshrrev_b32_e32 v155, 16, v155
	v_fma_mixhi_f16 v155, v55, v35, 0
	v_cvt_f32_f16_e32 v32, v148
	v_cvt_f32_f16_sdwa v35, v148 dst_sel:DWORD dst_unused:UNUSED_PAD src0_sel:WORD_1
	v_cvt_f32_f16_e32 v148, v149
	v_cvt_f32_f16_sdwa v149, v149 dst_sel:DWORD dst_unused:UNUSED_PAD src0_sel:WORD_1
	v_lshl_add_u64 v[168:169], s[14:15], 0, v[168:169]
	v_lshl_add_u64 v[168:169], v[168:169], 0, v[166:167]
	v_max_f32_e32 v148, 0xc1f00000, v148
	v_mul_f32_e32 v148, 0xbfb8aa3b, v148
	global_store_dwordx4 v[168:169], v[152:155], off
	v_max_f32_e32 v35, 0xc1f00000, v35
	v_mul_f32_e32 v35, 0xbfb8aa3b, v35
	v_exp_f32_e32 v152, v148
	v_max_f32_e32 v148, 0xc1f00000, v149
	v_mul_f32_e32 v148, 0xbfb8aa3b, v148
	v_cvt_f32_f16_e32 v149, v150
	v_exp_f32_e32 v153, v148
	v_cvt_f32_f16_sdwa v148, v150 dst_sel:DWORD dst_unused:UNUSED_PAD src0_sel:WORD_1
	v_exp_f32_e32 v35, v35
	v_max_f32_e32 v149, 0xc1f00000, v149
	v_mul_f32_e32 v149, 0xbfb8aa3b, v149
	v_max_f32_e32 v148, 0xc1f00000, v148
	v_mul_f32_e32 v148, 0xbfb8aa3b, v148
	v_exp_f32_e32 v154, v149
	v_cvt_f32_f16_e32 v149, v151
	v_exp_f32_e32 v155, v148
	v_cvt_f32_f16_sdwa v148, v151 dst_sel:DWORD dst_unused:UNUSED_PAD src0_sel:WORD_1
	v_max_f32_e32 v32, 0xc1f00000, v32
	v_mul_f32_e32 v32, 0xbfb8aa3b, v32
	v_exp_f32_e32 v32, v32
	v_max_f32_e32 v149, 0xc1f00000, v149
	v_max_f32_e32 v148, 0xc1f00000, v148
	v_mul_f32_e32 v149, 0xbfb8aa3b, v149
	v_mul_f32_e32 v148, 0xbfb8aa3b, v148
	v_add_f32_e32 v35, 1.0, v35
	v_exp_f32_e32 v161, v149
	v_exp_f32_e32 v163, v148
	v_rcp_f32_e32 v148, v35
	v_add_f32_e32 v35, 1.0, v152
	v_rcp_f32_e32 v149, v35
	v_add_f32_e32 v35, 1.0, v153
	v_add_f32_e32 v32, 1.0, v32
	v_rcp_f32_e32 v150, v35
	v_add_f32_e32 v35, 1.0, v154
	v_rcp_f32_e32 v32, v32
	v_rcp_f32_e32 v151, v35
	v_add_f32_e32 v35, 1.0, v155
	v_rcp_f32_e32 v152, v35
	v_add_f32_e32 v35, 1.0, v161
	v_rcp_f32_e32 v153, v35
	v_mov_b32_e32 v154, v21
	v_mov_b32_e32 v155, v22
	v_pk_mul_f32 v[148:149], v[154:155], v[148:149]
	v_pk_mov_b32 v[154:155], v[22:23], v[16:17] op_sel:[1,0]
	v_add_f32_e32 v35, 1.0, v163
	v_fma_mixlo_f16 v32, v20, v32, 0
	v_cvt_pk_f16_f32 v149, v148, v149
	v_pk_mul_f32 v[150:151], v[154:155], v[150:151]
	v_rcp_f32_e32 v35, v35
	v_pack_b32_f16 v148, v32, v149
	v_cvt_pk_f16_f32 v32, v150, v151
	v_mov_b32_e32 v150, v17
	v_mov_b32_e32 v151, v18
	v_pk_mul_f32 v[150:151], v[150:151], v[152:153]
	v_alignbit_b32 v149, v32, v149, 16
	v_cvt_pk_f16_f32 v151, v150, v151
	v_alignbit_b32 v150, v151, v32, 16
	v_lshrrev_b32_e32 v151, 16, v151
	v_fma_mixhi_f16 v151, v19, v35, 0
	v_cvt_f32_f16_e32 v32, v144
	v_cvt_f32_f16_sdwa v35, v144 dst_sel:DWORD dst_unused:UNUSED_PAD src0_sel:WORD_1
	v_cvt_f32_f16_e32 v144, v145
	v_cvt_f32_f16_sdwa v145, v145 dst_sel:DWORD dst_unused:UNUSED_PAD src0_sel:WORD_1
	global_store_dwordx4 v[168:169], v[148:151], off offset:256
	v_max_f32_e32 v35, 0xc1f00000, v35
	v_max_f32_e32 v144, 0xc1f00000, v144
	v_mul_f32_e32 v144, 0xbfb8aa3b, v144
	v_exp_f32_e32 v150, v144
	v_max_f32_e32 v144, 0xc1f00000, v145
	v_mul_f32_e32 v144, 0xbfb8aa3b, v144
	v_cvt_f32_f16_e32 v145, v146
	v_exp_f32_e32 v151, v144
	v_cvt_f32_f16_sdwa v144, v146 dst_sel:DWORD dst_unused:UNUSED_PAD src0_sel:WORD_1
	v_mul_f32_e32 v35, 0xbfb8aa3b, v35
	v_max_f32_e32 v145, 0xc1f00000, v145
	v_mul_f32_e32 v145, 0xbfb8aa3b, v145
	v_max_f32_e32 v144, 0xc1f00000, v144
	v_mul_f32_e32 v144, 0xbfb8aa3b, v144
	v_exp_f32_e32 v152, v145
	v_cvt_f32_f16_e32 v145, v147
	v_exp_f32_e32 v153, v144
	v_cvt_f32_f16_sdwa v144, v147 dst_sel:DWORD dst_unused:UNUSED_PAD src0_sel:WORD_1
	v_exp_f32_e32 v35, v35
	v_max_f32_e32 v32, 0xc1f00000, v32
	v_mul_f32_e32 v32, 0xbfb8aa3b, v32
	v_exp_f32_e32 v32, v32
	v_max_f32_e32 v145, 0xc1f00000, v145
	v_max_f32_e32 v144, 0xc1f00000, v144
	v_mul_f32_e32 v145, 0xbfb8aa3b, v145
	v_mul_f32_e32 v144, 0xbfb8aa3b, v144
	v_add_f32_e32 v35, 1.0, v35
	v_exp_f32_e32 v154, v145
	v_exp_f32_e32 v155, v144
	v_rcp_f32_e32 v144, v35
	v_add_f32_e32 v35, 1.0, v150
	v_rcp_f32_e32 v145, v35
	v_add_f32_e32 v35, 1.0, v151
	v_add_f32_e32 v32, 1.0, v32
	v_rcp_f32_e32 v146, v35
	v_add_f32_e32 v35, 1.0, v152
	v_rcp_f32_e32 v32, v32
	v_rcp_f32_e32 v147, v35
	v_add_f32_e32 v35, 1.0, v153
	v_rcp_f32_e32 v150, v35
	v_add_f32_e32 v35, 1.0, v154
	v_rcp_f32_e32 v151, v35
	v_mov_b32_e32 v152, v49
	v_mov_b32_e32 v153, v50
	v_pk_mul_f32 v[144:145], v[152:153], v[144:145]
	v_pk_mov_b32 v[152:153], v[50:51], v[44:45] op_sel:[1,0]
	v_add_f32_e32 v35, 1.0, v155
	v_fma_mixlo_f16 v32, v48, v32, 0
	v_cvt_pk_f16_f32 v145, v144, v145
	v_pk_mul_f32 v[146:147], v[152:153], v[146:147]
	v_rcp_f32_e32 v35, v35
	v_pack_b32_f16 v144, v32, v145
	v_cvt_pk_f16_f32 v32, v146, v147
	v_mov_b32_e32 v146, v45
	v_mov_b32_e32 v147, v46
	v_pk_mul_f32 v[146:147], v[146:147], v[150:151]
	v_alignbit_b32 v145, v32, v145, 16
	v_cvt_pk_f16_f32 v147, v146, v147
	v_alignbit_b32 v146, v147, v32, 16
	v_lshrrev_b32_e32 v147, 16, v147
	v_fma_mixhi_f16 v147, v47, v35, 0
	v_cvt_f32_f16_e32 v32, v140
	v_cvt_f32_f16_sdwa v35, v140 dst_sel:DWORD dst_unused:UNUSED_PAD src0_sel:WORD_1
	v_cvt_f32_f16_e32 v140, v141
	v_cvt_f32_f16_sdwa v141, v141 dst_sel:DWORD dst_unused:UNUSED_PAD src0_sel:WORD_1
	v_lshlrev_b64 v[148:149], 11, v[172:173]
	v_lshl_add_u64 v[148:149], s[14:15], 0, v[148:149]
	v_max_f32_e32 v140, 0xc1f00000, v140
	v_lshl_add_u64 v[148:149], v[148:149], 0, v[166:167]
	v_mul_f32_e32 v140, 0xbfb8aa3b, v140
	global_store_dwordx4 v[148:149], v[144:147], off
	v_max_f32_e32 v35, 0xc1f00000, v35
	v_mul_f32_e32 v35, 0xbfb8aa3b, v35
	v_exp_f32_e32 v144, v140
	v_max_f32_e32 v140, 0xc1f00000, v141
	v_mul_f32_e32 v140, 0xbfb8aa3b, v140
	v_cvt_f32_f16_e32 v141, v142
	v_exp_f32_e32 v145, v140
	v_cvt_f32_f16_sdwa v140, v142 dst_sel:DWORD dst_unused:UNUSED_PAD src0_sel:WORD_1
	v_exp_f32_e32 v35, v35
	v_max_f32_e32 v141, 0xc1f00000, v141
	v_mul_f32_e32 v141, 0xbfb8aa3b, v141
	v_max_f32_e32 v140, 0xc1f00000, v140
	v_mul_f32_e32 v140, 0xbfb8aa3b, v140
	v_exp_f32_e32 v146, v141
	v_cvt_f32_f16_e32 v141, v143
	v_exp_f32_e32 v147, v140
	v_cvt_f32_f16_sdwa v140, v143 dst_sel:DWORD dst_unused:UNUSED_PAD src0_sel:WORD_1
	v_max_f32_e32 v32, 0xc1f00000, v32
	v_mul_f32_e32 v32, 0xbfb8aa3b, v32
	v_exp_f32_e32 v32, v32
	v_max_f32_e32 v141, 0xc1f00000, v141
	v_max_f32_e32 v140, 0xc1f00000, v140
	v_mul_f32_e32 v141, 0xbfb8aa3b, v141
	v_mul_f32_e32 v140, 0xbfb8aa3b, v140
	v_add_f32_e32 v35, 1.0, v35
	v_exp_f32_e32 v150, v141
	v_exp_f32_e32 v151, v140
	v_rcp_f32_e32 v140, v35
	v_add_f32_e32 v35, 1.0, v144
	v_rcp_f32_e32 v141, v35
	v_add_f32_e32 v35, 1.0, v145
	v_add_f32_e32 v32, 1.0, v32
	v_rcp_f32_e32 v142, v35
	v_add_f32_e32 v35, 1.0, v146
	v_rcp_f32_e32 v32, v32
	v_rcp_f32_e32 v143, v35
	v_add_f32_e32 v35, 1.0, v147
	v_rcp_f32_e32 v144, v35
	v_add_f32_e32 v35, 1.0, v150
	v_rcp_f32_e32 v145, v35
	v_mov_b32_e32 v146, v13
	v_mov_b32_e32 v147, v14
	v_pk_mul_f32 v[140:141], v[146:147], v[140:141]
	v_pk_mov_b32 v[146:147], v[14:15], v[8:9] op_sel:[1,0]
	v_add_f32_e32 v35, 1.0, v151
	v_fma_mixlo_f16 v32, v12, v32, 0
	v_cvt_pk_f16_f32 v141, v140, v141
	v_pk_mul_f32 v[142:143], v[146:147], v[142:143]
	v_rcp_f32_e32 v35, v35
	v_pack_b32_f16 v140, v32, v141
	v_cvt_pk_f16_f32 v32, v142, v143
	v_mov_b32_e32 v142, v9
	v_mov_b32_e32 v143, v10
	v_pk_mul_f32 v[142:143], v[142:143], v[144:145]
	v_alignbit_b32 v141, v32, v141, 16
	v_cvt_pk_f16_f32 v143, v142, v143
	v_alignbit_b32 v142, v143, v32, 16
	v_lshrrev_b32_e32 v143, 16, v143
	v_fma_mixhi_f16 v143, v11, v35, 0
	v_cvt_f32_f16_e32 v32, v136
	v_cvt_f32_f16_sdwa v35, v136 dst_sel:DWORD dst_unused:UNUSED_PAD src0_sel:WORD_1
	v_cvt_f32_f16_e32 v136, v137
	v_cvt_f32_f16_sdwa v137, v137 dst_sel:DWORD dst_unused:UNUSED_PAD src0_sel:WORD_1
	global_store_dwordx4 v[148:149], v[140:143], off offset:256
	v_max_f32_e32 v35, 0xc1f00000, v35
	v_max_f32_e32 v136, 0xc1f00000, v136
	v_mul_f32_e32 v136, 0xbfb8aa3b, v136
	v_exp_f32_e32 v142, v136
	v_max_f32_e32 v136, 0xc1f00000, v137
	v_mul_f32_e32 v136, 0xbfb8aa3b, v136
	v_cvt_f32_f16_e32 v137, v138
	v_exp_f32_e32 v143, v136
	v_cvt_f32_f16_sdwa v136, v138 dst_sel:DWORD dst_unused:UNUSED_PAD src0_sel:WORD_1
	v_mul_f32_e32 v35, 0xbfb8aa3b, v35
	v_max_f32_e32 v137, 0xc1f00000, v137
	v_mul_f32_e32 v137, 0xbfb8aa3b, v137
	v_max_f32_e32 v136, 0xc1f00000, v136
	v_mul_f32_e32 v136, 0xbfb8aa3b, v136
	v_exp_f32_e32 v144, v137
	v_cvt_f32_f16_e32 v137, v139
	v_exp_f32_e32 v145, v136
	v_cvt_f32_f16_sdwa v136, v139 dst_sel:DWORD dst_unused:UNUSED_PAD src0_sel:WORD_1
	v_exp_f32_e32 v35, v35
	v_max_f32_e32 v32, 0xc1f00000, v32
	v_mul_f32_e32 v32, 0xbfb8aa3b, v32
	v_exp_f32_e32 v32, v32
	v_max_f32_e32 v137, 0xc1f00000, v137
	v_max_f32_e32 v136, 0xc1f00000, v136
	v_mul_f32_e32 v137, 0xbfb8aa3b, v137
	v_mul_f32_e32 v136, 0xbfb8aa3b, v136
	v_add_f32_e32 v35, 1.0, v35
	v_exp_f32_e32 v146, v137
	v_exp_f32_e32 v147, v136
	v_rcp_f32_e32 v136, v35
	v_add_f32_e32 v35, 1.0, v142
	v_rcp_f32_e32 v137, v35
	v_add_f32_e32 v35, 1.0, v143
	v_add_f32_e32 v32, 1.0, v32
	v_rcp_f32_e32 v138, v35
	v_add_f32_e32 v35, 1.0, v144
	v_rcp_f32_e32 v32, v32
	v_rcp_f32_e32 v139, v35
	v_add_f32_e32 v35, 1.0, v145
	v_rcp_f32_e32 v142, v35
	v_add_f32_e32 v35, 1.0, v146
	v_rcp_f32_e32 v143, v35
	v_mov_b32_e32 v144, v41
	v_mov_b32_e32 v145, v42
	v_pk_mul_f32 v[136:137], v[144:145], v[136:137]
	v_pk_mov_b32 v[144:145], v[42:43], v[36:37] op_sel:[1,0]
	v_add_f32_e32 v35, 1.0, v147
	v_fma_mixlo_f16 v32, v40, v32, 0
	v_cvt_pk_f16_f32 v137, v136, v137
	v_pk_mul_f32 v[138:139], v[144:145], v[138:139]
	v_rcp_f32_e32 v35, v35
	v_pack_b32_f16 v136, v32, v137
	v_cvt_pk_f16_f32 v32, v138, v139
	v_mov_b32_e32 v138, v37
	v_mov_b32_e32 v139, v38
	v_pk_mul_f32 v[138:139], v[138:139], v[142:143]
	v_alignbit_b32 v137, v32, v137, 16
	v_cvt_pk_f16_f32 v139, v138, v139
	v_alignbit_b32 v138, v139, v32, 16
	v_lshrrev_b32_e32 v139, 16, v139
	v_fma_mixhi_f16 v139, v39, v35, 0
	v_cvt_f32_f16_e32 v32, v132
	v_cvt_f32_f16_sdwa v35, v132 dst_sel:DWORD dst_unused:UNUSED_PAD src0_sel:WORD_1
	v_cvt_f32_f16_e32 v132, v133
	v_cvt_f32_f16_sdwa v133, v133 dst_sel:DWORD dst_unused:UNUSED_PAD src0_sel:WORD_1
	v_lshlrev_b64 v[140:141], 11, v[170:171]
	v_lshl_add_u64 v[140:141], s[14:15], 0, v[140:141]
	v_max_f32_e32 v132, 0xc1f00000, v132
	v_lshl_add_u64 v[140:141], v[140:141], 0, v[166:167]
	v_mul_f32_e32 v132, 0xbfb8aa3b, v132
	global_store_dwordx4 v[140:141], v[136:139], off
	v_max_f32_e32 v35, 0xc1f00000, v35
	v_mul_f32_e32 v35, 0xbfb8aa3b, v35
	v_exp_f32_e32 v136, v132
	v_max_f32_e32 v132, 0xc1f00000, v133
	v_mul_f32_e32 v132, 0xbfb8aa3b, v132
	v_cvt_f32_f16_e32 v133, v134
	v_exp_f32_e32 v137, v132
	v_cvt_f32_f16_sdwa v132, v134 dst_sel:DWORD dst_unused:UNUSED_PAD src0_sel:WORD_1
	v_exp_f32_e32 v35, v35
	v_max_f32_e32 v133, 0xc1f00000, v133
	v_mul_f32_e32 v133, 0xbfb8aa3b, v133
	v_max_f32_e32 v132, 0xc1f00000, v132
	v_mul_f32_e32 v132, 0xbfb8aa3b, v132
	v_exp_f32_e32 v138, v133
	v_cvt_f32_f16_e32 v133, v135
	v_exp_f32_e32 v139, v132
	v_cvt_f32_f16_sdwa v132, v135 dst_sel:DWORD dst_unused:UNUSED_PAD src0_sel:WORD_1
	v_max_f32_e32 v32, 0xc1f00000, v32
	v_mul_f32_e32 v32, 0xbfb8aa3b, v32
	v_exp_f32_e32 v32, v32
	v_max_f32_e32 v133, 0xc1f00000, v133
	v_max_f32_e32 v132, 0xc1f00000, v132
	v_mul_f32_e32 v133, 0xbfb8aa3b, v133
	v_mul_f32_e32 v132, 0xbfb8aa3b, v132
	v_add_f32_e32 v35, 1.0, v35
	v_exp_f32_e32 v142, v133
	v_exp_f32_e32 v143, v132
	v_rcp_f32_e32 v132, v35
	v_add_f32_e32 v35, 1.0, v136
	v_rcp_f32_e32 v133, v35
	v_add_f32_e32 v35, 1.0, v137
	v_add_f32_e32 v32, 1.0, v32
	v_rcp_f32_e32 v134, v35
	v_add_f32_e32 v35, 1.0, v138
	v_rcp_f32_e32 v32, v32
	v_rcp_f32_e32 v135, v35
	v_add_f32_e32 v35, 1.0, v139
	v_rcp_f32_e32 v136, v35
	v_add_f32_e32 v35, 1.0, v142
	v_rcp_f32_e32 v137, v35
	v_mov_b32_e32 v138, v5
	v_mov_b32_e32 v139, v6
	v_pk_mul_f32 v[132:133], v[138:139], v[132:133]
	v_pk_mov_b32 v[138:139], v[6:7], v[0:1] op_sel:[1,0]
	v_add_f32_e32 v35, 1.0, v143
	v_fma_mixlo_f16 v32, v4, v32, 0
	v_cvt_pk_f16_f32 v133, v132, v133
	v_pk_mul_f32 v[134:135], v[138:139], v[134:135]
	v_rcp_f32_e32 v35, v35
	v_pack_b32_f16 v132, v32, v133
	v_cvt_pk_f16_f32 v32, v134, v135
	v_mov_b32_e32 v134, v1
	v_mov_b32_e32 v135, v2
	v_pk_mul_f32 v[134:135], v[134:135], v[136:137]
	v_alignbit_b32 v133, v32, v133, 16
	v_cvt_pk_f16_f32 v135, v134, v135
	v_alignbit_b32 v134, v135, v32, 16
	v_lshrrev_b32_e32 v135, 16, v135
	v_fma_mixhi_f16 v135, v3, v35, 0
	global_store_dwordx4 v[140:141], v[132:135], off offset:256
	s_cbranch_execnz .LBB0_944

.LBB0_950:
	s_mov_b32 s50, 0
	v_readlane_b32 s0, v251, 36
	s_cmp_lg_u32 s0, 0
	s_cbranch_scc1 .Lrts_skip
	v_readlane_b32 s1, v255, 48
	s_cmp_lg_u32 s1, 2
	s_cbranch_scc1 .Lrts_known
	s_and_b32 s0, s91, 63
	s_lshl_b32 s0, s0, 2
	s_add_i32 s0, s0, 15104
	v_readlane_b32 s2, v251, 32
	v_readlane_b32 s3, v251, 33
	s_add_u32 s2, s2, s0
	s_addc_u32 s3, s3, 0
	v_mov_b32_e32 v1, 0
	global_load_dword v2, v1, s[2:3] sc1
	s_waitcnt vmcnt(0)
	v_readfirstlane_b32 s4, v2
	global_load_dword v2, v1, s[2:3] offset:256 sc1
	s_waitcnt vmcnt(0)
	v_readfirstlane_b32 s5, v2
	s_cmp_lg_u32 s4, s5
	s_cselect_b32 s1, 0, 1
	global_load_dword v2, v1, s[2:3] offset:512 sc1
	s_waitcnt vmcnt(0)
	v_readfirstlane_b32 s5, v2
	s_cmp_lg_u32 s4, s5
	s_cselect_b32 s1, 0, s1
	global_load_dword v2, v1, s[2:3] offset:768 sc1
	s_waitcnt vmcnt(0)
	v_readfirstlane_b32 s5, v2
	s_cmp_lg_u32 s4, s5
	s_cselect_b32 s1, 0, s1
	s_cmp_eq_u32 s4, 0
	s_cselect_b32 s1, 0, s1
	v_writelane_b32 v255, s1, 48

.LBB0_958:
	s_add_u32 s12, s10, 0x100
	s_addc_u32 s13, s11, 0
	s_add_i32 s38, 0, 0x10000
	v_add_u32_e32 v142, s38, v196
	ds_read_b128 v[122:125], v142
	ds_read_b128 v[138:141], v142 offset:2048
	ds_read_b128 v[130:133], v142 offset:1024
	ds_read_b128 v[142:145], v142 offset:3072
	s_cmp_eq_u32 s37, 12
	s_cselect_b32 s17, s7, s13
	s_cselect_b32 s16, s6, s12
	s_cselect_b32 s15, s9, s36
	s_cselect_b32 s14, s8, s35
	v_lshl_add_u64 v[230:231], s[10:11], 0, v[188:189]
	s_add_i32 m0, s21, 0xc000
	ds_read_b128 v[146:149], v198
	ds_read_b128 v[192:195], v198 offset:2048
	ds_read_b128 v[204:207], v198 offset:4096
	ds_read_b128 v[212:215], v198 offset:6144
	ds_read_b128 v[150:153], v198 offset:1024
	ds_read_b128 v[200:203], v198 offset:3072
	ds_read_b128 v[208:211], v198 offset:5120
	ds_read_b128 v[216:219], v198 offset:7168
	global_load_lds_dwordx4 v[230:231], off
	v_lshl_add_u64 v[230:231], s[10:11], 0, v[190:191]
	s_add_i32 m0, s21, 0xe000
	s_nop 0
	global_load_lds_dwordx4 v[230:231], off
	s_waitcnt lgkmcnt(8)
	s_barrier
	s_waitcnt lgkmcnt(7)
	s_setprio 1
	v_mfma_f32_16x16x32_f16 v[134:137], v[122:125], v[146:149], v[134:137]
	v_mfma_f32_16x16x32_f16 v[126:129], v[138:141], v[146:149], v[126:129]
	s_waitcnt lgkmcnt(6)
	v_mfma_f32_16x16x32_f16 v[110:113], v[122:125], v[192:195], v[110:113]
	v_mfma_f32_16x16x32_f16 v[106:109], v[138:141], v[192:195], v[106:109]
	s_waitcnt lgkmcnt(5)
	v_mfma_f32_16x16x32_f16 v[94:97], v[122:125], v[204:207], v[94:97]
	v_mfma_f32_16x16x32_f16 v[90:93], v[138:141], v[204:207], v[90:93]
	s_waitcnt lgkmcnt(4)
	v_mfma_f32_16x16x32_f16 v[78:81], v[122:125], v[212:215], v[78:81]
	v_mfma_f32_16x16x32_f16 v[74:77], v[138:141], v[212:215], v[74:77]
	s_waitcnt lgkmcnt(3)
	v_mfma_f32_16x16x32_f16 v[134:137], v[130:133], v[150:153], v[134:137]
	v_mfma_f32_16x16x32_f16 v[126:129], v[142:145], v[150:153], v[126:129]
	s_waitcnt lgkmcnt(2)
	v_mfma_f32_16x16x32_f16 v[110:113], v[130:133], v[200:203], v[110:113]
	v_mfma_f32_16x16x32_f16 v[106:109], v[142:145], v[200:203], v[106:109]
	s_waitcnt lgkmcnt(1)
	v_mfma_f32_16x16x32_f16 v[94:97], v[130:133], v[208:211], v[94:97]
	v_mfma_f32_16x16x32_f16 v[90:93], v[142:145], v[208:211], v[90:93]
	s_waitcnt lgkmcnt(0)
	v_mfma_f32_16x16x32_f16 v[78:81], v[130:133], v[216:219], v[78:81]
	v_mfma_f32_16x16x32_f16 v[74:77], v[142:145], v[216:219], v[74:77]
	s_setprio 0
	s_barrier
	s_add_i32 s39, 0, 0x14000
	s_add_i32 s10, s38, s20
	v_add_u32_e32 v199, s39, v196
	v_lshl_add_u64 v[246:247], s[14:15], 0, v[32:33]
	s_mov_b32 m0, s10
	ds_read_b128 v[230:233], v199
	ds_read_b128 v[238:241], v199 offset:2048
	ds_read_b128 v[234:237], v199 offset:1024
	ds_read_b128 v[242:245], v199 offset:3072
	global_load_lds_dwordx4 v[246:247], off
	v_lshl_add_u64 v[248:249], s[14:15], 0, v[154:155]
	s_add_i32 m0, s10, 0x2000
	s_nop 0
	global_load_lds_dwordx4 v[248:249], off
	s_barrier
	s_waitcnt lgkmcnt(2)
	s_setprio 1
	v_mfma_f32_16x16x32_f16 v[118:121], v[230:233], v[146:149], v[118:121]
	v_mfma_f32_16x16x32_f16 v[114:117], v[238:241], v[146:149], v[114:117]
	v_mfma_f32_16x16x32_f16 v[102:105], v[230:233], v[192:195], v[102:105]
	v_mfma_f32_16x16x32_f16 v[98:101], v[238:241], v[192:195], v[98:101]
	v_mfma_f32_16x16x32_f16 v[86:89], v[230:233], v[204:207], v[86:89]
	v_mfma_f32_16x16x32_f16 v[82:85], v[238:241], v[204:207], v[82:85]
	v_mfma_f32_16x16x32_f16 v[70:73], v[230:233], v[212:215], v[70:73]
	v_mfma_f32_16x16x32_f16 v[66:69], v[238:241], v[212:215], v[66:69]
	s_waitcnt lgkmcnt(0)
	v_mfma_f32_16x16x32_f16 v[118:121], v[234:237], v[150:153], v[118:121]
	v_mfma_f32_16x16x32_f16 v[114:117], v[242:245], v[150:153], v[114:117]
	v_mfma_f32_16x16x32_f16 v[102:105], v[234:237], v[200:203], v[102:105]
	v_mfma_f32_16x16x32_f16 v[98:101], v[242:245], v[200:203], v[98:101]
	v_mfma_f32_16x16x32_f16 v[86:89], v[234:237], v[208:211], v[86:89]
	v_mfma_f32_16x16x32_f16 v[82:85], v[242:245], v[208:211], v[82:85]
	v_mfma_f32_16x16x32_f16 v[70:73], v[234:237], v[216:219], v[70:73]
	v_mfma_f32_16x16x32_f16 v[66:69], v[242:245], v[216:219], v[66:69]
	s_setprio 0
	s_mov_b32 m0, s21
	v_lshl_add_u64 v[228:229], s[16:17], 0, v[32:33]
	s_barrier
	ds_read_b128 v[146:149], v198 offset:16384
	ds_read_b128 v[192:195], v198 offset:18432
	ds_read_b128 v[204:207], v198 offset:20480
	ds_read_b128 v[212:215], v198 offset:22528
	ds_read_b128 v[150:153], v198 offset:17408
	ds_read_b128 v[200:203], v198 offset:19456
	ds_read_b128 v[208:211], v198 offset:21504
	ds_read_b128 v[216:219], v198 offset:23552
	global_load_lds_dwordx4 v[228:229], off
	v_lshl_add_u64 v[222:223], s[16:17], 0, v[154:155]
	s_mov_b32 m0, s22
	s_nop 0
	global_load_lds_dwordx4 v[222:223], off
	s_barrier
	s_waitcnt lgkmcnt(7)
	s_setprio 1
	v_mfma_f32_16x16x32_f16 v[62:65], v[122:125], v[146:149], v[62:65]
	v_mfma_f32_16x16x32_f16 v[58:61], v[138:141], v[146:149], v[58:61]
	s_waitcnt lgkmcnt(6)
	v_mfma_f32_16x16x32_f16 v[46:49], v[122:125], v[192:195], v[46:49]
	v_mfma_f32_16x16x32_f16 v[42:45], v[138:141], v[192:195], v[42:45]
	s_waitcnt lgkmcnt(5)
	v_mfma_f32_16x16x32_f16 v[28:31], v[122:125], v[204:207], v[28:31]
	v_mfma_f32_16x16x32_f16 v[24:27], v[138:141], v[204:207], v[24:27]
	s_waitcnt lgkmcnt(4)
	v_mfma_f32_16x16x32_f16 v[12:15], v[122:125], v[212:215], v[12:15]
	v_mfma_f32_16x16x32_f16 v[8:11], v[138:141], v[212:215], v[8:11]
	s_waitcnt lgkmcnt(3)
	v_mfma_f32_16x16x32_f16 v[62:65], v[130:133], v[150:153], v[62:65]
	v_mfma_f32_16x16x32_f16 v[58:61], v[142:145], v[150:153], v[58:61]
	s_waitcnt lgkmcnt(2)
	v_mfma_f32_16x16x32_f16 v[46:49], v[130:133], v[200:203], v[46:49]
	v_mfma_f32_16x16x32_f16 v[42:45], v[142:145], v[200:203], v[42:45]
	s_waitcnt lgkmcnt(1)
	v_mfma_f32_16x16x32_f16 v[28:31], v[130:133], v[208:211], v[28:31]
	v_mfma_f32_16x16x32_f16 v[24:27], v[142:145], v[208:211], v[24:27]
	s_waitcnt lgkmcnt(0)
	v_mfma_f32_16x16x32_f16 v[12:15], v[130:133], v[216:219], v[12:15]
	v_mfma_f32_16x16x32_f16 v[8:11], v[142:145], v[216:219], v[8:11]
	s_setprio 0
	s_barrier
	s_add_u32 s10, s14, 0x40000
	s_addc_u32 s11, s15, 0
	s_add_i32 s38, s39, s20
	v_lshl_add_u64 v[122:123], s[10:11], 0, v[32:33]
	s_mov_b32 m0, s38
	s_nop 0
	global_load_lds_dwordx4 v[122:123], off
	v_lshl_add_u64 v[122:123], s[10:11], 0, v[154:155]
	s_add_i32 m0, s38, 0x2000
	s_nop 0
	global_load_lds_dwordx4 v[122:123], off
	s_waitcnt vmcnt(6)
	s_barrier
	s_setprio 1
	v_mfma_f32_16x16x32_f16 v[54:57], v[230:233], v[146:149], v[54:57]
	v_mfma_f32_16x16x32_f16 v[50:53], v[238:241], v[146:149], v[50:53]
	v_mfma_f32_16x16x32_f16 v[38:41], v[230:233], v[192:195], v[38:41]
	v_mfma_f32_16x16x32_f16 v[34:37], v[238:241], v[192:195], v[34:37]
	v_mfma_f32_16x16x32_f16 v[20:23], v[230:233], v[204:207], v[20:23]
	v_mfma_f32_16x16x32_f16 v[16:19], v[238:241], v[204:207], v[16:19]
	v_mfma_f32_16x16x32_f16 v[4:7], v[230:233], v[212:215], v[4:7]
	v_mfma_f32_16x16x32_f16 v[0:3], v[238:241], v[212:215], v[0:3]
	v_mfma_f32_16x16x32_f16 v[54:57], v[234:237], v[150:153], v[54:57]
	v_mfma_f32_16x16x32_f16 v[50:53], v[242:245], v[150:153], v[50:53]
	v_mfma_f32_16x16x32_f16 v[38:41], v[234:237], v[200:203], v[38:41]
	v_mfma_f32_16x16x32_f16 v[34:37], v[242:245], v[200:203], v[34:37]
	v_mfma_f32_16x16x32_f16 v[20:23], v[234:237], v[208:211], v[20:23]
	v_mfma_f32_16x16x32_f16 v[16:19], v[242:245], v[208:211], v[16:19]
	v_mfma_f32_16x16x32_f16 v[4:7], v[234:237], v[216:219], v[4:7]
	v_mfma_f32_16x16x32_f16 v[0:3], v[242:245], v[216:219], v[0:3]
	s_setprio 0
	s_add_i32 s38, 0, 0x18000
	v_add_u32_e32 v142, s38, v196
	s_barrier
	ds_read_b128 v[122:125], v142
	ds_read_b128 v[138:141], v142 offset:2048
	ds_read_b128 v[130:133], v142 offset:1024
	ds_read_b128 v[142:145], v142 offset:3072
	s_add_u32 s10, s16, 0x40000
	s_addc_u32 s11, s17, 0
	s_mov_b32 m0, s23
	v_lshl_add_u64 v[230:231], s[10:11], 0, v[32:33]
	ds_read_b128 v[146:149], v198 offset:32768
	ds_read_b128 v[192:195], v198 offset:34816
	ds_read_b128 v[204:207], v198 offset:36864
	ds_read_b128 v[212:215], v198 offset:38912
	ds_read_b128 v[150:153], v198 offset:33792
	ds_read_b128 v[200:203], v198 offset:35840
	ds_read_b128 v[208:211], v198 offset:37888
	ds_read_b128 v[216:219], v198 offset:39936
	global_load_lds_dwordx4 v[230:231], off
	v_lshl_add_u64 v[230:231], s[10:11], 0, v[154:155]
	s_mov_b32 m0, s24
	s_nop 0
	global_load_lds_dwordx4 v[230:231], off
	s_waitcnt lgkmcnt(8)
	s_barrier
	s_waitcnt lgkmcnt(7)
	s_setprio 1
	v_mfma_f32_16x16x32_f16 v[134:137], v[122:125], v[146:149], v[134:137]
	v_mfma_f32_16x16x32_f16 v[126:129], v[138:141], v[146:149], v[126:129]
	s_waitcnt lgkmcnt(6)
	v_mfma_f32_16x16x32_f16 v[110:113], v[122:125], v[192:195], v[110:113]
	v_mfma_f32_16x16x32_f16 v[106:109], v[138:141], v[192:195], v[106:109]
	s_waitcnt lgkmcnt(5)
	v_mfma_f32_16x16x32_f16 v[94:97], v[122:125], v[204:207], v[94:97]
	v_mfma_f32_16x16x32_f16 v[90:93], v[138:141], v[204:207], v[90:93]
	s_waitcnt lgkmcnt(4)
	v_mfma_f32_16x16x32_f16 v[78:81], v[122:125], v[212:215], v[78:81]
	v_mfma_f32_16x16x32_f16 v[74:77], v[138:141], v[212:215], v[74:77]
	s_waitcnt lgkmcnt(3)
	v_mfma_f32_16x16x32_f16 v[134:137], v[130:133], v[150:153], v[134:137]
	v_mfma_f32_16x16x32_f16 v[126:129], v[142:145], v[150:153], v[126:129]
	s_waitcnt lgkmcnt(2)
	v_mfma_f32_16x16x32_f16 v[110:113], v[130:133], v[200:203], v[110:113]
	v_mfma_f32_16x16x32_f16 v[106:109], v[142:145], v[200:203], v[106:109]
	s_waitcnt lgkmcnt(1)
	v_mfma_f32_16x16x32_f16 v[94:97], v[130:133], v[208:211], v[94:97]
	v_mfma_f32_16x16x32_f16 v[90:93], v[142:145], v[208:211], v[90:93]
	s_waitcnt lgkmcnt(0)
	v_mfma_f32_16x16x32_f16 v[78:81], v[130:133], v[216:219], v[78:81]
	v_mfma_f32_16x16x32_f16 v[74:77], v[142:145], v[216:219], v[74:77]
	s_setprio 0
	s_barrier
	s_add_i32 s16, 0, 0x1c000
	s_add_i32 s10, s38, s20
	v_add_u32_e32 v199, s16, v196
	v_lshl_add_u64 v[246:247], v[246:247], 0, s[84:85]
	s_mov_b32 m0, s10
	ds_read_b128 v[230:233], v199
	ds_read_b128 v[238:241], v199 offset:2048
	ds_read_b128 v[234:237], v199 offset:1024
	ds_read_b128 v[242:245], v199 offset:3072
	global_load_lds_dwordx4 v[246:247], off
	v_lshl_add_u64 v[246:247], v[248:249], 0, s[84:85]
	s_add_i32 m0, s10, 0x2000
	s_nop 0
	global_load_lds_dwordx4 v[246:247], off
	s_barrier
	s_waitcnt lgkmcnt(2)
	s_setprio 1
	v_mfma_f32_16x16x32_f16 v[118:121], v[230:233], v[146:149], v[118:121]
	v_mfma_f32_16x16x32_f16 v[114:117], v[238:241], v[146:149], v[114:117]
	v_mfma_f32_16x16x32_f16 v[102:105], v[230:233], v[192:195], v[102:105]
	v_mfma_f32_16x16x32_f16 v[98:101], v[238:241], v[192:195], v[98:101]
	v_mfma_f32_16x16x32_f16 v[86:89], v[230:233], v[204:207], v[86:89]
	v_mfma_f32_16x16x32_f16 v[82:85], v[238:241], v[204:207], v[82:85]
	v_mfma_f32_16x16x32_f16 v[70:73], v[230:233], v[212:215], v[70:73]
	v_mfma_f32_16x16x32_f16 v[66:69], v[238:241], v[212:215], v[66:69]
	s_waitcnt lgkmcnt(0)
	v_mfma_f32_16x16x32_f16 v[118:121], v[234:237], v[150:153], v[118:121]
	v_mfma_f32_16x16x32_f16 v[114:117], v[242:245], v[150:153], v[114:117]
	v_mfma_f32_16x16x32_f16 v[102:105], v[234:237], v[200:203], v[102:105]
	v_mfma_f32_16x16x32_f16 v[98:101], v[242:245], v[200:203], v[98:101]
	v_mfma_f32_16x16x32_f16 v[86:89], v[234:237], v[208:211], v[86:89]
	v_mfma_f32_16x16x32_f16 v[82:85], v[242:245], v[208:211], v[82:85]
	v_mfma_f32_16x16x32_f16 v[70:73], v[234:237], v[216:219], v[70:73]
	v_mfma_f32_16x16x32_f16 v[66:69], v[242:245], v[216:219], v[66:69]
	s_setprio 0
	s_mov_b32 m0, s25
	v_lshl_add_u64 v[228:229], v[228:229], 0, s[84:85]
	s_barrier
	ds_read_b128 v[146:149], v198 offset:49152
	ds_read_b128 v[192:195], v198 offset:51200
	ds_read_b128 v[204:207], v198 offset:53248
	ds_read_b128 v[212:215], v198 offset:55296
	ds_read_b128 v[150:153], v198 offset:50176
	ds_read_b128 v[200:203], v198 offset:52224
	ds_read_b128 v[208:211], v198 offset:54272
	ds_read_b128 v[216:219], v198 offset:56320
	global_load_lds_dwordx4 v[228:229], off
	v_lshl_add_u64 v[222:223], v[222:223], 0, s[84:85]
	s_mov_b32 m0, s27
	s_nop 0
	global_load_lds_dwordx4 v[222:223], off
	s_barrier
	s_waitcnt lgkmcnt(7)
	s_setprio 1
	v_mfma_f32_16x16x32_f16 v[62:65], v[122:125], v[146:149], v[62:65]
	v_mfma_f32_16x16x32_f16 v[58:61], v[138:141], v[146:149], v[58:61]
	s_waitcnt lgkmcnt(6)
	v_mfma_f32_16x16x32_f16 v[46:49], v[122:125], v[192:195], v[46:49]
	v_mfma_f32_16x16x32_f16 v[42:45], v[138:141], v[192:195], v[42:45]
	s_waitcnt lgkmcnt(5)
	v_mfma_f32_16x16x32_f16 v[28:31], v[122:125], v[204:207], v[28:31]
	v_mfma_f32_16x16x32_f16 v[24:27], v[138:141], v[204:207], v[24:27]
	s_waitcnt lgkmcnt(4)
	v_mfma_f32_16x16x32_f16 v[12:15], v[122:125], v[212:215], v[12:15]
	v_mfma_f32_16x16x32_f16 v[8:11], v[138:141], v[212:215], v[8:11]
	s_waitcnt lgkmcnt(3)
	v_mfma_f32_16x16x32_f16 v[62:65], v[130:133], v[150:153], v[62:65]
	v_mfma_f32_16x16x32_f16 v[58:61], v[142:145], v[150:153], v[58:61]
	s_waitcnt lgkmcnt(2)
	v_mfma_f32_16x16x32_f16 v[46:49], v[130:133], v[200:203], v[46:49]
	v_mfma_f32_16x16x32_f16 v[42:45], v[142:145], v[200:203], v[42:45]
	s_waitcnt lgkmcnt(1)
	v_mfma_f32_16x16x32_f16 v[28:31], v[130:133], v[208:211], v[28:31]
	v_mfma_f32_16x16x32_f16 v[24:27], v[142:145], v[208:211], v[24:27]
	s_waitcnt lgkmcnt(0)
	v_mfma_f32_16x16x32_f16 v[12:15], v[130:133], v[216:219], v[12:15]
	v_mfma_f32_16x16x32_f16 v[8:11], v[142:145], v[216:219], v[8:11]
	s_setprio 0
	s_barrier
	s_add_u32 s10, s14, 0x40080
	s_addc_u32 s11, s15, 0
	s_add_i32 s14, s16, s20
	v_lshl_add_u64 v[122:123], s[10:11], 0, v[32:33]
	s_mov_b32 m0, s14
	s_nop 0
	global_load_lds_dwordx4 v[122:123], off
	v_lshl_add_u64 v[122:123], s[10:11], 0, v[154:155]
	s_add_i32 m0, s14, 0x2000
	s_nop 0
	global_load_lds_dwordx4 v[122:123], off
	s_waitcnt vmcnt(6)
	s_barrier
	s_setprio 1
	v_mfma_f32_16x16x32_f16 v[54:57], v[230:233], v[146:149], v[54:57]
	v_mfma_f32_16x16x32_f16 v[50:53], v[238:241], v[146:149], v[50:53]
	v_mfma_f32_16x16x32_f16 v[38:41], v[230:233], v[192:195], v[38:41]
	v_mfma_f32_16x16x32_f16 v[34:37], v[238:241], v[192:195], v[34:37]
	v_mfma_f32_16x16x32_f16 v[20:23], v[230:233], v[204:207], v[20:23]
	v_mfma_f32_16x16x32_f16 v[16:19], v[238:241], v[204:207], v[16:19]
	v_mfma_f32_16x16x32_f16 v[4:7], v[230:233], v[212:215], v[4:7]
	v_mfma_f32_16x16x32_f16 v[0:3], v[238:241], v[212:215], v[0:3]
	v_mfma_f32_16x16x32_f16 v[54:57], v[234:237], v[150:153], v[54:57]
	v_mfma_f32_16x16x32_f16 v[50:53], v[242:245], v[150:153], v[50:53]
	v_mfma_f32_16x16x32_f16 v[38:41], v[234:237], v[200:203], v[38:41]
	v_mfma_f32_16x16x32_f16 v[34:37], v[242:245], v[200:203], v[34:37]
	v_mfma_f32_16x16x32_f16 v[20:23], v[234:237], v[208:211], v[20:23]
	v_mfma_f32_16x16x32_f16 v[16:19], v[242:245], v[208:211], v[16:19]
	v_mfma_f32_16x16x32_f16 v[4:7], v[234:237], v[216:219], v[4:7]
	v_mfma_f32_16x16x32_f16 v[0:3], v[242:245], v[216:219], v[0:3]
	s_setprio 0
	s_add_i32 s37, s37, 2
	s_add_u32 s35, s35, 0x100
	s_addc_u32 s36, s36, 0
	s_cmp_gt_u32 s37, 13
	s_mov_b64 s[10:11], s[12:13]
	s_cbranch_scc0 .Lepib_ygc_bar
	v_readlane_b32 s51, v251, 36
	s_cmp_gt_u32 s51, 3
	s_cbranch_scc0 .Lepib_ygc_barx
	s_mov_b32 s50, 1
	s_branch .Lepib_ygc_exit

.Lepib_ygc_exit:
.Lpeelx2:
	s_cmp_eq_u32 s34, 2
	s_movk_i32 s6, 0x2800
	v_lshl_or_b32 v122, s31, 8, v197
	s_cselect_b32 s6, 0x2000, s6
	s_mov_b32 s7, 0x23a3c000
	s_cselect_b32 s8, s7, 0x23abc000
	s_add_u32 s6, s70, s6
	v_ashrrev_i32_e32 v123, 31, v122
	s_addc_u32 s7, s71, 0
	v_lshlrev_b64 v[192:193], 1, v[122:123]
	v_lshl_add_u64 v[194:195], s[6:7], 0, v[192:193]
	v_lshl_add_u64 v[122:123], v[194:195], 0, v[156:157]
	v_lshl_add_u64 v[124:125], v[194:195], 0, v[158:159]
	v_lshl_add_u64 v[130:131], v[194:195], 0, v[160:161]
	v_lshl_add_u64 v[208:209], v[194:195], 0, v[162:163]
	global_load_dwordx4 v[200:203], v[122:123], off
	global_load_dwordx4 v[204:207], v[122:123], off offset:256
	global_load_dwordx4 v[150:153], v[124:125], off
	global_load_dwordx4 v[146:149], v[124:125], off offset:256
	global_load_dwordx4 v[142:145], v[130:131], off
	global_load_dwordx4 v[138:141], v[130:131], off offset:256
	s_nop 0
	global_load_dwordx4 v[130:133], v[208:209], off
	global_load_dwordx4 v[122:125], v[208:209], off offset:256
	v_readlane_b32 s36, v252, 26
	v_readlane_b32 s42, v252, 32
	v_readlane_b32 s43, v252, 33
	s_add_u32 s6, s42, s8
	s_addc_u32 s7, s43, 0
	v_readlane_b32 s37, v252, 27
	v_readlane_b32 s38, v252, 28
	v_readlane_b32 s39, v252, 29
	v_readlane_b32 s40, v252, 30
	v_readlane_b32 s41, v252, 31
	v_lshl_add_u64 v[192:193], s[6:7], 0, v[192:193]
	s_waitcnt vmcnt(0)
	v_cvt_f32_f16_e32 v199, v200
	v_cvt_f32_f16_sdwa v200, v200 dst_sel:DWORD dst_unused:UNUSED_PAD src0_sel:WORD_1
	v_cvt_f32_f16_e32 v210, v201
	v_lshl_add_u64 v[208:209], v[192:193], 0, v[164:165]
	v_max_f32_e32 v199, 0xc1f00000, v199
	v_mul_f32_e32 v199, 0xbfb8aa3b, v199
	v_exp_f32_e32 v199, v199
	v_max_f32_e32 v200, 0xc1f00000, v200
	v_max_f32_e32 v210, 0xc1f00000, v210
	v_mul_f32_e32 v200, 0xbfb8aa3b, v200
	v_add_f32_e32 v199, 1.0, v199
	v_rcp_f32_e32 v199, v199
	v_exp_f32_e32 v200, v200
	v_mul_f32_e32 v210, 0xbfb8aa3b, v210
	v_exp_f32_e32 v211, v210
	v_fma_mixlo_f16 v199, v134, v199, 0
	v_add_f32_e32 v134, 1.0, v200
	v_rcp_f32_e32 v210, v134
	v_add_f32_e32 v134, 1.0, v211
	v_cvt_f32_f16_sdwa v200, v201 dst_sel:DWORD dst_unused:UNUSED_PAD src0_sel:WORD_1
	v_rcp_f32_e32 v211, v134
	v_mov_b32_e32 v134, v135
	v_mov_b32_e32 v135, v136
	v_cvt_f32_f16_e32 v136, v202
	v_max_f32_e32 v200, 0xc1f00000, v200
	v_mul_f32_e32 v200, 0xbfb8aa3b, v200
	v_exp_f32_e32 v200, v200
	v_max_f32_e32 v136, 0xc1f00000, v136
	v_mul_f32_e32 v136, 0xbfb8aa3b, v136
	v_exp_f32_e32 v136, v136
	v_pk_mul_f32 v[134:135], v[134:135], v[210:211]
	s_nop 0
	v_cvt_pk_f16_f32 v135, v134, v135
	v_add_f32_e32 v134, 1.0, v200
	v_rcp_f32_e32 v200, v134
	v_add_f32_e32 v134, 1.0, v136
	v_rcp_f32_e32 v201, v134
	v_pk_mov_b32 v[136:137], v[136:137], v[126:127] op_sel:[1,0]
	v_cvt_f32_f16_sdwa v126, v202 dst_sel:DWORD dst_unused:UNUSED_PAD src0_sel:WORD_1
	v_pack_b32_f16 v134, v199, v135
	v_pk_mul_f32 v[136:137], v[136:137], v[200:201]
	v_cvt_f32_f16_sdwa v200, v203 dst_sel:DWORD dst_unused:UNUSED_PAD src0_sel:WORD_1
	v_cvt_pk_f16_f32 v199, v136, v137
	v_cvt_f32_f16_e32 v136, v203
	v_max_f32_e32 v126, 0xc1f00000, v126
	v_mul_f32_e32 v126, 0xbfb8aa3b, v126
	v_exp_f32_e32 v126, v126
	v_max_f32_e32 v136, 0xc1f00000, v136
	v_mul_f32_e32 v136, 0xbfb8aa3b, v136
	v_exp_f32_e32 v137, v136
	v_add_f32_e32 v126, 1.0, v126
	v_rcp_f32_e32 v136, v126
	v_alignbit_b32 v135, v199, v135, 16
	v_add_f32_e32 v126, 1.0, v137
	v_rcp_f32_e32 v137, v126
	v_mov_b32_e32 v126, v127
	v_mov_b32_e32 v127, v128
	v_cvt_f32_f16_e32 v128, v204
	v_pk_mul_f32 v[126:127], v[126:127], v[136:137]
	s_nop 0
	v_cvt_pk_f16_f32 v126, v126, v127
	v_max_f32_e32 v127, 0xc1f00000, v200
	v_mul_f32_e32 v127, 0xbfb8aa3b, v127
	v_exp_f32_e32 v127, v127
	v_alignbit_b32 v136, v126, v199, 16
	v_lshrrev_b32_e32 v137, 16, v126
	v_add_f32_e32 v126, 1.0, v127
	v_rcp_f32_e32 v126, v126
	v_max_f32_e32 v127, 0xc1f00000, v128
	v_mul_f32_e32 v127, 0xbfb8aa3b, v127
	v_exp_f32_e32 v127, v127
	v_fma_mixhi_f16 v137, v129, v126, 0
	v_cvt_f32_f16_sdwa v126, v204 dst_sel:DWORD dst_unused:UNUSED_PAD src0_sel:WORD_1
	v_cvt_f32_f16_e32 v128, v205
	v_add_f32_e32 v127, 1.0, v127
	v_rcp_f32_e32 v127, v127
	v_max_f32_e32 v126, 0xc1f00000, v126
	v_mul_f32_e32 v126, 0xbfb8aa3b, v126
	v_max_f32_e32 v128, 0xc1f00000, v128
	v_exp_f32_e32 v126, v126
	v_mul_f32_e32 v128, 0xbfb8aa3b, v128
	v_exp_f32_e32 v128, v128
	v_fma_mixlo_f16 v129, v118, v127, 0
	v_add_f32_e32 v118, 1.0, v126
	v_rcp_f32_e32 v126, v118
	v_add_f32_e32 v118, 1.0, v128
	v_rcp_f32_e32 v127, v118
	v_cvt_f32_f16_sdwa v128, v205 dst_sel:DWORD dst_unused:UNUSED_PAD src0_sel:WORD_1
	v_mov_b32_e32 v118, v119
	v_mov_b32_e32 v119, v120
	v_cvt_f32_f16_e32 v120, v206
	v_max_f32_e32 v128, 0xc1f00000, v128
	v_mul_f32_e32 v128, 0xbfb8aa3b, v128
	v_exp_f32_e32 v128, v128
	v_max_f32_e32 v120, 0xc1f00000, v120
	v_mul_f32_e32 v120, 0xbfb8aa3b, v120
	v_exp_f32_e32 v120, v120
	v_pk_mul_f32 v[118:119], v[118:119], v[126:127]
	v_add_f32_e32 v126, 1.0, v128
	v_rcp_f32_e32 v126, v126
	v_add_f32_e32 v120, 1.0, v120
	v_rcp_f32_e32 v127, v120
	v_pk_mov_b32 v[120:121], v[120:121], v[114:115] op_sel:[1,0]
	v_cvt_f32_f16_sdwa v114, v206 dst_sel:DWORD dst_unused:UNUSED_PAD src0_sel:WORD_1
	v_cvt_pk_f16_f32 v119, v118, v119
	v_pk_mul_f32 v[120:121], v[120:121], v[126:127]
	v_cvt_f32_f16_sdwa v127, v207 dst_sel:DWORD dst_unused:UNUSED_PAD src0_sel:WORD_1
	v_cvt_pk_f16_f32 v126, v120, v121
	v_cvt_f32_f16_e32 v120, v207
	v_max_f32_e32 v114, 0xc1f00000, v114
	v_mul_f32_e32 v114, 0xbfb8aa3b, v114
	v_exp_f32_e32 v114, v114
	v_max_f32_e32 v120, 0xc1f00000, v120
	v_mul_f32_e32 v120, 0xbfb8aa3b, v120
	v_exp_f32_e32 v121, v120
	v_add_f32_e32 v114, 1.0, v114
	v_rcp_f32_e32 v120, v114
	v_pack_b32_f16 v118, v129, v119
	v_add_f32_e32 v114, 1.0, v121
	v_rcp_f32_e32 v121, v114
	v_mov_b32_e32 v114, v115
	v_max_f32_e32 v115, 0xc1f00000, v127
	v_mul_f32_e32 v115, 0xbfb8aa3b, v115
	v_exp_f32_e32 v127, v115
	v_mov_b32_e32 v115, v116
	v_pk_mul_f32 v[114:115], v[114:115], v[120:121]
	v_cvt_f32_f16_e32 v116, v150
	v_cvt_pk_f16_f32 v114, v114, v115
	v_add_f32_e32 v115, 1.0, v127
	v_rcp_f32_e32 v115, v115
	v_alignbit_b32 v120, v114, v126, 16
	v_lshrrev_b32_e32 v121, 16, v114
	v_max_f32_e32 v114, 0xc1f00000, v116
	v_alignbit_b32 v119, v126, v119, 16
	v_fma_mixhi_f16 v121, v117, v115, 0
	v_mul_f32_e32 v114, 0xbfb8aa3b, v114
	v_cvt_f32_f16_sdwa v117, v150 dst_sel:DWORD dst_unused:UNUSED_PAD src0_sel:WORD_1
	v_exp_f32_e32 v116, v114
	global_store_dwordx4 v[208:209], v[118:121], off offset:256
	v_lshl_add_u64 v[114:115], v[192:193], 0, v[166:167]
	v_max_f32_e32 v117, 0xc1f00000, v117
	v_cvt_f32_f16_e32 v118, v151
	v_add_f32_e32 v116, 1.0, v116
	v_mul_f32_e32 v117, 0xbfb8aa3b, v117
	v_rcp_f32_e32 v116, v116
	v_max_f32_e32 v118, 0xc1f00000, v118
	v_exp_f32_e32 v117, v117
	v_mul_f32_e32 v118, 0xbfb8aa3b, v118
	v_exp_f32_e32 v118, v118
	v_fma_mixlo_f16 v119, v110, v116, 0
	v_add_f32_e32 v110, 1.0, v117
	v_rcp_f32_e32 v116, v110
	v_add_f32_e32 v110, 1.0, v118
	v_rcp_f32_e32 v117, v110
	v_cvt_f32_f16_sdwa v118, v151 dst_sel:DWORD dst_unused:UNUSED_PAD src0_sel:WORD_1
	v_mov_b32_e32 v110, v111
	v_mov_b32_e32 v111, v112
	v_cvt_f32_f16_e32 v112, v152
	v_pk_mul_f32 v[110:111], v[110:111], v[116:117]
	v_max_f32_e32 v116, 0xc1f00000, v118
	v_mul_f32_e32 v116, 0xbfb8aa3b, v116
	v_max_f32_e32 v112, 0xc1f00000, v112
	v_exp_f32_e32 v116, v116
	v_mul_f32_e32 v112, 0xbfb8aa3b, v112
	v_exp_f32_e32 v112, v112
	v_cvt_pk_f16_f32 v111, v110, v111
	v_add_f32_e32 v110, 1.0, v116
	v_rcp_f32_e32 v116, v110
	v_add_f32_e32 v110, 1.0, v112
	v_rcp_f32_e32 v117, v110
	v_pk_mov_b32 v[112:113], v[112:113], v[106:107] op_sel:[1,0]
	v_cvt_f32_f16_sdwa v106, v152 dst_sel:DWORD dst_unused:UNUSED_PAD src0_sel:WORD_1
	v_pack_b32_f16 v110, v119, v111
	v_pk_mul_f32 v[112:113], v[112:113], v[116:117]
	v_cvt_f32_f16_sdwa v117, v153 dst_sel:DWORD dst_unused:UNUSED_PAD src0_sel:WORD_1
	v_cvt_pk_f16_f32 v116, v112, v113
	v_cvt_f32_f16_e32 v112, v153
	v_max_f32_e32 v106, 0xc1f00000, v106
	v_mul_f32_e32 v106, 0xbfb8aa3b, v106
	v_exp_f32_e32 v106, v106
	v_max_f32_e32 v112, 0xc1f00000, v112
	v_mul_f32_e32 v112, 0xbfb8aa3b, v112
	v_exp_f32_e32 v113, v112
	v_add_f32_e32 v106, 1.0, v106
	v_rcp_f32_e32 v112, v106
	v_alignbit_b32 v111, v116, v111, 16
	v_add_f32_e32 v106, 1.0, v113
	v_rcp_f32_e32 v113, v106
	v_mov_b32_e32 v106, v107
	v_mov_b32_e32 v107, v108
	v_cvt_f32_f16_e32 v108, v146
	v_pk_mul_f32 v[106:107], v[106:107], v[112:113]
	global_store_dwordx4 v[208:209], v[134:137], off
	v_cvt_pk_f16_f32 v106, v106, v107
	v_max_f32_e32 v107, 0xc1f00000, v117
	v_mul_f32_e32 v107, 0xbfb8aa3b, v107
	v_exp_f32_e32 v107, v107
	v_alignbit_b32 v112, v106, v116, 16
	v_lshrrev_b32_e32 v113, 16, v106
	v_add_f32_e32 v106, 1.0, v107
	v_rcp_f32_e32 v106, v106
	v_max_f32_e32 v107, 0xc1f00000, v108
	v_mul_f32_e32 v107, 0xbfb8aa3b, v107
	v_exp_f32_e32 v107, v107
	v_fma_mixhi_f16 v113, v109, v106, 0
	v_cvt_f32_f16_sdwa v106, v146 dst_sel:DWORD dst_unused:UNUSED_PAD src0_sel:WORD_1
	v_cvt_f32_f16_e32 v108, v147
	v_add_f32_e32 v107, 1.0, v107
	v_rcp_f32_e32 v107, v107
	v_max_f32_e32 v106, 0xc1f00000, v106
	v_mul_f32_e32 v106, 0xbfb8aa3b, v106
	v_max_f32_e32 v108, 0xc1f00000, v108
	v_exp_f32_e32 v106, v106
	v_mul_f32_e32 v108, 0xbfb8aa3b, v108
	v_exp_f32_e32 v108, v108
	v_fma_mixlo_f16 v109, v102, v107, 0
	v_add_f32_e32 v102, 1.0, v106
	v_rcp_f32_e32 v106, v102
	v_add_f32_e32 v102, 1.0, v108
	v_rcp_f32_e32 v107, v102
	v_cvt_f32_f16_sdwa v108, v147 dst_sel:DWORD dst_unused:UNUSED_PAD src0_sel:WORD_1
	v_mov_b32_e32 v102, v103
	v_mov_b32_e32 v103, v104
	v_cvt_f32_f16_e32 v104, v148
	v_max_f32_e32 v108, 0xc1f00000, v108
	v_mul_f32_e32 v108, 0xbfb8aa3b, v108
	v_exp_f32_e32 v108, v108
	v_max_f32_e32 v104, 0xc1f00000, v104
	v_mul_f32_e32 v104, 0xbfb8aa3b, v104
	v_exp_f32_e32 v104, v104
	v_pk_mul_f32 v[102:103], v[102:103], v[106:107]
	v_add_f32_e32 v106, 1.0, v108
	v_rcp_f32_e32 v106, v106
	v_add_f32_e32 v104, 1.0, v104
	v_rcp_f32_e32 v107, v104
	v_pk_mov_b32 v[104:105], v[104:105], v[98:99] op_sel:[1,0]
	v_cvt_f32_f16_sdwa v98, v148 dst_sel:DWORD dst_unused:UNUSED_PAD src0_sel:WORD_1
	v_cvt_pk_f16_f32 v103, v102, v103
	v_pk_mul_f32 v[104:105], v[104:105], v[106:107]
	v_cvt_f32_f16_sdwa v107, v149 dst_sel:DWORD dst_unused:UNUSED_PAD src0_sel:WORD_1
	v_cvt_pk_f16_f32 v106, v104, v105
	v_cvt_f32_f16_e32 v104, v149
	v_max_f32_e32 v98, 0xc1f00000, v98
	v_mul_f32_e32 v98, 0xbfb8aa3b, v98
	v_exp_f32_e32 v98, v98
	v_max_f32_e32 v104, 0xc1f00000, v104
	v_mul_f32_e32 v104, 0xbfb8aa3b, v104
	v_exp_f32_e32 v105, v104
	v_add_f32_e32 v98, 1.0, v98
	v_rcp_f32_e32 v104, v98
	v_pack_b32_f16 v102, v109, v103
	v_add_f32_e32 v98, 1.0, v105
	v_rcp_f32_e32 v105, v98
	v_mov_b32_e32 v98, v99
	v_max_f32_e32 v99, 0xc1f00000, v107
	v_mul_f32_e32 v99, 0xbfb8aa3b, v99
	v_exp_f32_e32 v107, v99
	v_mov_b32_e32 v99, v100
	v_pk_mul_f32 v[98:99], v[98:99], v[104:105]
	v_cvt_f32_f16_e32 v100, v142
	v_cvt_pk_f16_f32 v98, v98, v99
	v_add_f32_e32 v99, 1.0, v107
	v_rcp_f32_e32 v99, v99
	v_alignbit_b32 v104, v98, v106, 16
	v_lshrrev_b32_e32 v105, 16, v98
	v_max_f32_e32 v98, 0xc1f00000, v100
	v_alignbit_b32 v103, v106, v103, 16
	v_fma_mixhi_f16 v105, v101, v99, 0
	v_mul_f32_e32 v98, 0xbfb8aa3b, v98
	v_cvt_f32_f16_sdwa v101, v142 dst_sel:DWORD dst_unused:UNUSED_PAD src0_sel:WORD_1
	v_exp_f32_e32 v100, v98
	global_store_dwordx4 v[114:115], v[102:105], off offset:256
	v_lshl_add_u64 v[98:99], v[192:193], 0, v[168:169]
	v_max_f32_e32 v101, 0xc1f00000, v101
	v_cvt_f32_f16_e32 v102, v143
	v_add_f32_e32 v100, 1.0, v100
	v_mul_f32_e32 v101, 0xbfb8aa3b, v101
	v_rcp_f32_e32 v100, v100
	v_max_f32_e32 v102, 0xc1f00000, v102
	v_exp_f32_e32 v101, v101
	v_mul_f32_e32 v102, 0xbfb8aa3b, v102
	v_exp_f32_e32 v102, v102
	v_fma_mixlo_f16 v103, v94, v100, 0
	v_add_f32_e32 v94, 1.0, v101
	v_rcp_f32_e32 v100, v94
	v_add_f32_e32 v94, 1.0, v102
	v_rcp_f32_e32 v101, v94
	v_cvt_f32_f16_sdwa v102, v143 dst_sel:DWORD dst_unused:UNUSED_PAD src0_sel:WORD_1
	v_mov_b32_e32 v94, v95
	v_mov_b32_e32 v95, v96
	v_cvt_f32_f16_e32 v96, v144
	v_pk_mul_f32 v[94:95], v[94:95], v[100:101]
	v_max_f32_e32 v100, 0xc1f00000, v102
	v_mul_f32_e32 v100, 0xbfb8aa3b, v100
	v_max_f32_e32 v96, 0xc1f00000, v96
	v_exp_f32_e32 v100, v100
	v_mul_f32_e32 v96, 0xbfb8aa3b, v96
	v_exp_f32_e32 v96, v96
	v_cvt_pk_f16_f32 v95, v94, v95
	v_add_f32_e32 v94, 1.0, v100
	v_rcp_f32_e32 v100, v94
	v_add_f32_e32 v94, 1.0, v96
	v_rcp_f32_e32 v101, v94
	v_pk_mov_b32 v[96:97], v[96:97], v[90:91] op_sel:[1,0]
	v_cvt_f32_f16_sdwa v90, v144 dst_sel:DWORD dst_unused:UNUSED_PAD src0_sel:WORD_1
	v_pack_b32_f16 v94, v103, v95
	v_pk_mul_f32 v[96:97], v[96:97], v[100:101]
	v_cvt_f32_f16_sdwa v101, v145 dst_sel:DWORD dst_unused:UNUSED_PAD src0_sel:WORD_1
	v_cvt_pk_f16_f32 v100, v96, v97
	v_cvt_f32_f16_e32 v96, v145
	v_max_f32_e32 v90, 0xc1f00000, v90
	v_mul_f32_e32 v90, 0xbfb8aa3b, v90
	v_exp_f32_e32 v90, v90
	v_max_f32_e32 v96, 0xc1f00000, v96
	v_mul_f32_e32 v96, 0xbfb8aa3b, v96
	v_exp_f32_e32 v97, v96
	v_add_f32_e32 v90, 1.0, v90
	v_rcp_f32_e32 v96, v90
	v_alignbit_b32 v95, v100, v95, 16
	v_add_f32_e32 v90, 1.0, v97
	v_rcp_f32_e32 v97, v90
	v_mov_b32_e32 v90, v91
	v_mov_b32_e32 v91, v92
	v_cvt_f32_f16_e32 v92, v138
	v_pk_mul_f32 v[90:91], v[90:91], v[96:97]
	global_store_dwordx4 v[114:115], v[110:113], off
	v_cvt_pk_f16_f32 v90, v90, v91
	v_max_f32_e32 v91, 0xc1f00000, v101
	v_mul_f32_e32 v91, 0xbfb8aa3b, v91
	v_exp_f32_e32 v91, v91
	v_alignbit_b32 v96, v90, v100, 16
	v_lshrrev_b32_e32 v97, 16, v90
	v_add_f32_e32 v90, 1.0, v91
	v_rcp_f32_e32 v90, v90
	v_max_f32_e32 v91, 0xc1f00000, v92
	v_mul_f32_e32 v91, 0xbfb8aa3b, v91
	v_exp_f32_e32 v91, v91
	v_fma_mixhi_f16 v97, v93, v90, 0
	v_cvt_f32_f16_sdwa v90, v138 dst_sel:DWORD dst_unused:UNUSED_PAD src0_sel:WORD_1
	v_cvt_f32_f16_e32 v92, v139
	v_add_f32_e32 v91, 1.0, v91
	v_rcp_f32_e32 v91, v91
	v_max_f32_e32 v90, 0xc1f00000, v90
	v_mul_f32_e32 v90, 0xbfb8aa3b, v90
	v_max_f32_e32 v92, 0xc1f00000, v92
	v_exp_f32_e32 v90, v90
	v_mul_f32_e32 v92, 0xbfb8aa3b, v92
	v_exp_f32_e32 v92, v92
	v_fma_mixlo_f16 v93, v86, v91, 0
	v_add_f32_e32 v86, 1.0, v90
	v_rcp_f32_e32 v90, v86
	v_add_f32_e32 v86, 1.0, v92
	v_rcp_f32_e32 v91, v86
	v_cvt_f32_f16_sdwa v92, v139 dst_sel:DWORD dst_unused:UNUSED_PAD src0_sel:WORD_1
	v_mov_b32_e32 v86, v87
	v_mov_b32_e32 v87, v88
	v_cvt_f32_f16_e32 v88, v140
	v_max_f32_e32 v92, 0xc1f00000, v92
	v_mul_f32_e32 v92, 0xbfb8aa3b, v92
	v_exp_f32_e32 v92, v92
	v_max_f32_e32 v88, 0xc1f00000, v88
	v_mul_f32_e32 v88, 0xbfb8aa3b, v88
	v_exp_f32_e32 v88, v88
	v_pk_mul_f32 v[86:87], v[86:87], v[90:91]
	v_add_f32_e32 v90, 1.0, v92
	v_rcp_f32_e32 v90, v90
	v_add_f32_e32 v88, 1.0, v88
	v_rcp_f32_e32 v91, v88
	v_pk_mov_b32 v[88:89], v[88:89], v[82:83] op_sel:[1,0]
	v_cvt_f32_f16_sdwa v82, v140 dst_sel:DWORD dst_unused:UNUSED_PAD src0_sel:WORD_1
	v_cvt_pk_f16_f32 v87, v86, v87
	v_pk_mul_f32 v[88:89], v[88:89], v[90:91]
	v_cvt_f32_f16_sdwa v91, v141 dst_sel:DWORD dst_unused:UNUSED_PAD src0_sel:WORD_1
	v_cvt_pk_f16_f32 v90, v88, v89
	v_cvt_f32_f16_e32 v88, v141
	v_max_f32_e32 v82, 0xc1f00000, v82
	v_mul_f32_e32 v82, 0xbfb8aa3b, v82
	v_exp_f32_e32 v82, v82
	v_max_f32_e32 v88, 0xc1f00000, v88
	v_mul_f32_e32 v88, 0xbfb8aa3b, v88
	v_exp_f32_e32 v89, v88
	v_add_f32_e32 v82, 1.0, v82
	v_rcp_f32_e32 v88, v82
	v_pack_b32_f16 v86, v93, v87
	v_add_f32_e32 v82, 1.0, v89
	v_rcp_f32_e32 v89, v82
	v_mov_b32_e32 v82, v83
	v_max_f32_e32 v83, 0xc1f00000, v91
	v_mul_f32_e32 v83, 0xbfb8aa3b, v83
	v_exp_f32_e32 v91, v83
	v_mov_b32_e32 v83, v84
	v_pk_mul_f32 v[82:83], v[82:83], v[88:89]
	v_cvt_f32_f16_e32 v84, v130
	v_cvt_pk_f16_f32 v82, v82, v83
	v_add_f32_e32 v83, 1.0, v91
	v_rcp_f32_e32 v83, v83
	v_alignbit_b32 v88, v82, v90, 16
	v_lshrrev_b32_e32 v89, 16, v82
	v_max_f32_e32 v82, 0xc1f00000, v84
	v_alignbit_b32 v87, v90, v87, 16
	v_fma_mixhi_f16 v89, v85, v83, 0
	v_mul_f32_e32 v82, 0xbfb8aa3b, v82
	v_cvt_f32_f16_sdwa v85, v130 dst_sel:DWORD dst_unused:UNUSED_PAD src0_sel:WORD_1
	v_exp_f32_e32 v84, v82
	global_store_dwordx4 v[98:99], v[86:89], off offset:256
	v_lshl_add_u64 v[82:83], v[192:193], 0, v[170:171]
	v_max_f32_e32 v85, 0xc1f00000, v85
	v_cvt_f32_f16_e32 v86, v131
	v_add_f32_e32 v84, 1.0, v84
	v_mul_f32_e32 v85, 0xbfb8aa3b, v85
	v_rcp_f32_e32 v84, v84
	v_max_f32_e32 v86, 0xc1f00000, v86
	v_exp_f32_e32 v85, v85
	v_mul_f32_e32 v86, 0xbfb8aa3b, v86
	v_exp_f32_e32 v86, v86
	v_fma_mixlo_f16 v87, v78, v84, 0
	v_add_f32_e32 v78, 1.0, v85
	v_rcp_f32_e32 v84, v78
	v_add_f32_e32 v78, 1.0, v86
	v_rcp_f32_e32 v85, v78
	v_cvt_f32_f16_sdwa v86, v131 dst_sel:DWORD dst_unused:UNUSED_PAD src0_sel:WORD_1
	v_mov_b32_e32 v78, v79
	v_mov_b32_e32 v79, v80
	v_cvt_f32_f16_e32 v80, v132
	v_pk_mul_f32 v[78:79], v[78:79], v[84:85]
	v_max_f32_e32 v84, 0xc1f00000, v86
	v_mul_f32_e32 v84, 0xbfb8aa3b, v84
	v_max_f32_e32 v80, 0xc1f00000, v80
	v_exp_f32_e32 v84, v84
	v_mul_f32_e32 v80, 0xbfb8aa3b, v80
	v_exp_f32_e32 v80, v80
	v_cvt_pk_f16_f32 v79, v78, v79
	v_add_f32_e32 v78, 1.0, v84
	v_rcp_f32_e32 v84, v78
	v_add_f32_e32 v78, 1.0, v80
	v_rcp_f32_e32 v85, v78
	v_pk_mov_b32 v[80:81], v[80:81], v[74:75] op_sel:[1,0]
	v_cvt_f32_f16_sdwa v74, v132 dst_sel:DWORD dst_unused:UNUSED_PAD src0_sel:WORD_1
	v_pack_b32_f16 v78, v87, v79
	v_pk_mul_f32 v[80:81], v[80:81], v[84:85]
	v_cvt_f32_f16_sdwa v85, v133 dst_sel:DWORD dst_unused:UNUSED_PAD src0_sel:WORD_1
	v_cvt_pk_f16_f32 v84, v80, v81
	v_cvt_f32_f16_e32 v80, v133
	v_max_f32_e32 v74, 0xc1f00000, v74
	v_mul_f32_e32 v74, 0xbfb8aa3b, v74
	v_exp_f32_e32 v74, v74
	v_max_f32_e32 v80, 0xc1f00000, v80
	v_mul_f32_e32 v80, 0xbfb8aa3b, v80
	v_exp_f32_e32 v81, v80
	v_add_f32_e32 v74, 1.0, v74
	v_rcp_f32_e32 v80, v74
	v_alignbit_b32 v79, v84, v79, 16
	v_add_f32_e32 v74, 1.0, v81
	v_rcp_f32_e32 v81, v74
	v_mov_b32_e32 v74, v75
	v_mov_b32_e32 v75, v76
	v_cvt_f32_f16_e32 v76, v122
	v_pk_mul_f32 v[74:75], v[74:75], v[80:81]
	global_store_dwordx4 v[98:99], v[94:97], off
	v_cvt_pk_f16_f32 v74, v74, v75
	v_max_f32_e32 v75, 0xc1f00000, v85
	v_mul_f32_e32 v75, 0xbfb8aa3b, v75
	v_exp_f32_e32 v75, v75
	v_alignbit_b32 v80, v74, v84, 16
	v_lshrrev_b32_e32 v81, 16, v74
	v_add_f32_e32 v74, 1.0, v75
	v_rcp_f32_e32 v74, v74
	v_max_f32_e32 v75, 0xc1f00000, v76
	v_mul_f32_e32 v75, 0xbfb8aa3b, v75
	v_exp_f32_e32 v75, v75
	v_fma_mixhi_f16 v81, v77, v74, 0
	v_cvt_f32_f16_sdwa v74, v122 dst_sel:DWORD dst_unused:UNUSED_PAD src0_sel:WORD_1
	v_cvt_f32_f16_e32 v76, v123
	v_add_f32_e32 v75, 1.0, v75
	v_rcp_f32_e32 v75, v75
	v_max_f32_e32 v74, 0xc1f00000, v74
	v_mul_f32_e32 v74, 0xbfb8aa3b, v74
	v_max_f32_e32 v76, 0xc1f00000, v76
	v_exp_f32_e32 v74, v74
	v_mul_f32_e32 v76, 0xbfb8aa3b, v76
	v_exp_f32_e32 v76, v76
	v_fma_mixlo_f16 v77, v70, v75, 0
	v_add_f32_e32 v70, 1.0, v74
	v_rcp_f32_e32 v74, v70
	v_add_f32_e32 v70, 1.0, v76
	v_rcp_f32_e32 v75, v70
	v_cvt_f32_f16_sdwa v76, v123 dst_sel:DWORD dst_unused:UNUSED_PAD src0_sel:WORD_1
	v_mov_b32_e32 v70, v71
	v_mov_b32_e32 v71, v72
	v_cvt_f32_f16_e32 v72, v124
	v_max_f32_e32 v76, 0xc1f00000, v76
	v_mul_f32_e32 v76, 0xbfb8aa3b, v76
	v_exp_f32_e32 v76, v76
	v_max_f32_e32 v72, 0xc1f00000, v72
	v_mul_f32_e32 v72, 0xbfb8aa3b, v72
	v_exp_f32_e32 v72, v72
	v_pk_mul_f32 v[70:71], v[70:71], v[74:75]
	v_add_f32_e32 v74, 1.0, v76
	v_rcp_f32_e32 v74, v74
	v_add_f32_e32 v72, 1.0, v72
	v_rcp_f32_e32 v75, v72
	v_pk_mov_b32 v[72:73], v[72:73], v[66:67] op_sel:[1,0]
	v_cvt_f32_f16_sdwa v66, v124 dst_sel:DWORD dst_unused:UNUSED_PAD src0_sel:WORD_1
	v_cvt_pk_f16_f32 v71, v70, v71
	v_pk_mul_f32 v[72:73], v[72:73], v[74:75]
	v_cvt_f32_f16_sdwa v75, v125 dst_sel:DWORD dst_unused:UNUSED_PAD src0_sel:WORD_1
	v_cvt_pk_f16_f32 v74, v72, v73
	v_cvt_f32_f16_e32 v72, v125
	v_max_f32_e32 v66, 0xc1f00000, v66
	v_mul_f32_e32 v66, 0xbfb8aa3b, v66
	v_exp_f32_e32 v66, v66
	v_max_f32_e32 v72, 0xc1f00000, v72
	v_mul_f32_e32 v72, 0xbfb8aa3b, v72
	v_exp_f32_e32 v73, v72
	v_add_f32_e32 v66, 1.0, v66
	v_rcp_f32_e32 v72, v66
	v_pack_b32_f16 v70, v77, v71
	v_add_f32_e32 v66, 1.0, v73
	v_rcp_f32_e32 v73, v66
	v_max_f32_e32 v66, 0xc1f00000, v75
	v_mul_f32_e32 v66, 0xbfb8aa3b, v66
	v_exp_f32_e32 v75, v66
	v_mov_b32_e32 v66, v67
	v_mov_b32_e32 v67, v68
	v_pk_mul_f32 v[66:67], v[66:67], v[72:73]
	v_add_f32_e32 v68, 1.0, v75
	v_rcp_f32_e32 v68, v68
	v_cvt_pk_f16_f32 v66, v66, v67
	v_lshrrev_b32_e32 v73, 16, v66
	v_alignbit_b32 v71, v74, v71, 16
	v_alignbit_b32 v72, v66, v74, 16
	v_fma_mixhi_f16 v73, v69, v68, 0
	global_store_dwordx4 v[82:83], v[78:81], off
	global_store_dwordx4 v[82:83], v[70:73], off offset:256
	v_lshl_add_u64 v[66:67], v[194:195], 0, v[172:173]
	v_lshl_add_u64 v[68:69], v[194:195], 0, v[174:175]
	v_lshl_add_u64 v[70:71], v[194:195], 0, v[176:177]
	v_lshl_add_u64 v[98:99], v[194:195], 0, v[178:179]
	global_load_dwordx4 v[90:93], v[66:67], off
	global_load_dwordx4 v[94:97], v[66:67], off offset:256
	global_load_dwordx4 v[86:89], v[68:69], off
	global_load_dwordx4 v[82:85], v[68:69], off offset:256
	global_load_dwordx4 v[78:81], v[70:71], off
	global_load_dwordx4 v[74:77], v[70:71], off offset:256
	s_nop 0
	global_load_dwordx4 v[70:73], v[98:99], off
	global_load_dwordx4 v[66:69], v[98:99], off offset:256
	s_waitcnt vmcnt(0)
	v_cvt_f32_f16_e32 v100, v90
	v_cvt_f32_f16_sdwa v90, v90 dst_sel:DWORD dst_unused:UNUSED_PAD src0_sel:WORD_1
	v_cvt_f32_f16_e32 v101, v91
	v_lshl_add_u64 v[98:99], v[192:193], 0, v[180:181]
	v_max_f32_e32 v100, 0xc1f00000, v100
	v_mul_f32_e32 v100, 0xbfb8aa3b, v100
	v_exp_f32_e32 v100, v100
	v_max_f32_e32 v90, 0xc1f00000, v90
	v_max_f32_e32 v101, 0xc1f00000, v101
	v_mul_f32_e32 v90, 0xbfb8aa3b, v90
	v_add_f32_e32 v100, 1.0, v100
	v_rcp_f32_e32 v100, v100
	v_exp_f32_e32 v90, v90
	v_mul_f32_e32 v101, 0xbfb8aa3b, v101
	v_exp_f32_e32 v101, v101
	v_fma_mixlo_f16 v102, v62, v100, 0
	v_add_f32_e32 v62, 1.0, v90
	v_rcp_f32_e32 v100, v62
	v_add_f32_e32 v62, 1.0, v101
	v_cvt_f32_f16_sdwa v90, v91 dst_sel:DWORD dst_unused:UNUSED_PAD src0_sel:WORD_1
	v_rcp_f32_e32 v101, v62
	v_mov_b32_e32 v62, v63
	v_mov_b32_e32 v63, v64
	v_cvt_f32_f16_e32 v64, v92
	v_max_f32_e32 v90, 0xc1f00000, v90
	v_mul_f32_e32 v90, 0xbfb8aa3b, v90
	v_exp_f32_e32 v90, v90
	v_max_f32_e32 v64, 0xc1f00000, v64
	v_mul_f32_e32 v64, 0xbfb8aa3b, v64
	v_exp_f32_e32 v64, v64
	v_pk_mul_f32 v[62:63], v[62:63], v[100:101]
	s_nop 0
	v_cvt_pk_f16_f32 v63, v62, v63
	v_add_f32_e32 v62, 1.0, v90
	v_rcp_f32_e32 v90, v62
	v_add_f32_e32 v62, 1.0, v64
	v_rcp_f32_e32 v91, v62
	v_pk_mov_b32 v[64:65], v[64:65], v[58:59] op_sel:[1,0]
	v_cvt_f32_f16_sdwa v58, v92 dst_sel:DWORD dst_unused:UNUSED_PAD src0_sel:WORD_1
	v_pack_b32_f16 v62, v102, v63
	v_pk_mul_f32 v[64:65], v[64:65], v[90:91]
	v_cvt_f32_f16_sdwa v91, v93 dst_sel:DWORD dst_unused:UNUSED_PAD src0_sel:WORD_1
	v_cvt_pk_f16_f32 v90, v64, v65
	v_cvt_f32_f16_e32 v64, v93
	v_max_f32_e32 v58, 0xc1f00000, v58
	v_mul_f32_e32 v58, 0xbfb8aa3b, v58
	v_exp_f32_e32 v58, v58
	v_max_f32_e32 v64, 0xc1f00000, v64
	v_mul_f32_e32 v64, 0xbfb8aa3b, v64
	v_exp_f32_e32 v65, v64
	v_add_f32_e32 v58, 1.0, v58
	v_rcp_f32_e32 v64, v58
	v_alignbit_b32 v63, v90, v63, 16
	v_add_f32_e32 v58, 1.0, v65
	v_rcp_f32_e32 v65, v58
	v_mov_b32_e32 v58, v59
	v_mov_b32_e32 v59, v60
	v_cvt_f32_f16_e32 v60, v94
	v_pk_mul_f32 v[58:59], v[58:59], v[64:65]
	s_nop 0
	v_cvt_pk_f16_f32 v58, v58, v59
	v_max_f32_e32 v59, 0xc1f00000, v91
	v_mul_f32_e32 v59, 0xbfb8aa3b, v59
	v_exp_f32_e32 v59, v59
	v_alignbit_b32 v64, v58, v90, 16
	v_lshrrev_b32_e32 v65, 16, v58
	v_add_f32_e32 v58, 1.0, v59
	v_rcp_f32_e32 v58, v58
	v_max_f32_e32 v59, 0xc1f00000, v60
	v_mul_f32_e32 v59, 0xbfb8aa3b, v59
	v_exp_f32_e32 v59, v59
	v_fma_mixhi_f16 v65, v61, v58, 0
	v_cvt_f32_f16_sdwa v58, v94 dst_sel:DWORD dst_unused:UNUSED_PAD src0_sel:WORD_1
	v_cvt_f32_f16_e32 v60, v95
	v_add_f32_e32 v59, 1.0, v59
	v_rcp_f32_e32 v59, v59
	v_max_f32_e32 v58, 0xc1f00000, v58
	v_mul_f32_e32 v58, 0xbfb8aa3b, v58
	v_max_f32_e32 v60, 0xc1f00000, v60
	v_exp_f32_e32 v58, v58
	v_mul_f32_e32 v60, 0xbfb8aa3b, v60
	v_exp_f32_e32 v60, v60
	v_fma_mixlo_f16 v61, v54, v59, 0
	v_add_f32_e32 v54, 1.0, v58
	v_rcp_f32_e32 v58, v54
	v_add_f32_e32 v54, 1.0, v60
	v_rcp_f32_e32 v59, v54
	v_cvt_f32_f16_sdwa v60, v95 dst_sel:DWORD dst_unused:UNUSED_PAD src0_sel:WORD_1
	v_mov_b32_e32 v54, v55
	v_mov_b32_e32 v55, v56
	v_cvt_f32_f16_e32 v56, v96
	v_max_f32_e32 v60, 0xc1f00000, v60
	v_mul_f32_e32 v60, 0xbfb8aa3b, v60
	v_exp_f32_e32 v60, v60
	v_max_f32_e32 v56, 0xc1f00000, v56
	v_mul_f32_e32 v56, 0xbfb8aa3b, v56
	v_exp_f32_e32 v56, v56
	v_pk_mul_f32 v[54:55], v[54:55], v[58:59]
	v_add_f32_e32 v58, 1.0, v60
	v_rcp_f32_e32 v58, v58
	v_add_f32_e32 v56, 1.0, v56
	v_rcp_f32_e32 v59, v56
	v_pk_mov_b32 v[56:57], v[56:57], v[50:51] op_sel:[1,0]
	v_cvt_f32_f16_sdwa v50, v96 dst_sel:DWORD dst_unused:UNUSED_PAD src0_sel:WORD_1
	v_cvt_pk_f16_f32 v55, v54, v55
	v_pk_mul_f32 v[56:57], v[56:57], v[58:59]
	v_cvt_f32_f16_sdwa v59, v97 dst_sel:DWORD dst_unused:UNUSED_PAD src0_sel:WORD_1
	v_cvt_pk_f16_f32 v58, v56, v57
	v_cvt_f32_f16_e32 v56, v97
	v_max_f32_e32 v50, 0xc1f00000, v50
	v_mul_f32_e32 v50, 0xbfb8aa3b, v50
	v_exp_f32_e32 v50, v50
	v_max_f32_e32 v56, 0xc1f00000, v56
	v_mul_f32_e32 v56, 0xbfb8aa3b, v56
	v_exp_f32_e32 v57, v56
	v_add_f32_e32 v50, 1.0, v50
	v_rcp_f32_e32 v56, v50
	v_pack_b32_f16 v54, v61, v55
	v_add_f32_e32 v50, 1.0, v57
	v_rcp_f32_e32 v57, v50
	v_mov_b32_e32 v50, v51
	v_max_f32_e32 v51, 0xc1f00000, v59
	v_mul_f32_e32 v51, 0xbfb8aa3b, v51
	v_exp_f32_e32 v59, v51
	v_mov_b32_e32 v51, v52
	v_pk_mul_f32 v[50:51], v[50:51], v[56:57]
	v_cvt_f32_f16_e32 v52, v86
	v_cvt_pk_f16_f32 v50, v50, v51
	v_add_f32_e32 v51, 1.0, v59
	v_rcp_f32_e32 v51, v51
	v_alignbit_b32 v56, v50, v58, 16
	v_lshrrev_b32_e32 v57, 16, v50
	v_max_f32_e32 v50, 0xc1f00000, v52
	v_alignbit_b32 v55, v58, v55, 16
	v_fma_mixhi_f16 v57, v53, v51, 0
	v_mul_f32_e32 v50, 0xbfb8aa3b, v50
	v_cvt_f32_f16_sdwa v53, v86 dst_sel:DWORD dst_unused:UNUSED_PAD src0_sel:WORD_1
	v_exp_f32_e32 v52, v50
	global_store_dwordx4 v[98:99], v[54:57], off offset:256
	v_lshl_add_u64 v[50:51], v[192:193], 0, v[182:183]
	v_max_f32_e32 v53, 0xc1f00000, v53
	v_cvt_f32_f16_e32 v54, v87
	v_add_f32_e32 v52, 1.0, v52
	v_mul_f32_e32 v53, 0xbfb8aa3b, v53
	v_rcp_f32_e32 v52, v52
	v_max_f32_e32 v54, 0xc1f00000, v54
	v_exp_f32_e32 v53, v53
	v_mul_f32_e32 v54, 0xbfb8aa3b, v54
	v_exp_f32_e32 v54, v54
	v_fma_mixlo_f16 v55, v46, v52, 0
	v_add_f32_e32 v46, 1.0, v53
	v_rcp_f32_e32 v52, v46
	v_add_f32_e32 v46, 1.0, v54
	v_rcp_f32_e32 v53, v46
	v_cvt_f32_f16_sdwa v54, v87 dst_sel:DWORD dst_unused:UNUSED_PAD src0_sel:WORD_1
	v_mov_b32_e32 v46, v47
	v_mov_b32_e32 v47, v48
	v_cvt_f32_f16_e32 v48, v88
	v_pk_mul_f32 v[46:47], v[46:47], v[52:53]
	v_max_f32_e32 v52, 0xc1f00000, v54
	v_mul_f32_e32 v52, 0xbfb8aa3b, v52
	v_max_f32_e32 v48, 0xc1f00000, v48
	v_exp_f32_e32 v52, v52
	v_mul_f32_e32 v48, 0xbfb8aa3b, v48
	v_exp_f32_e32 v48, v48
	v_cvt_pk_f16_f32 v47, v46, v47
	v_add_f32_e32 v46, 1.0, v52
	v_rcp_f32_e32 v52, v46
	v_add_f32_e32 v46, 1.0, v48
	v_rcp_f32_e32 v53, v46
	v_pk_mov_b32 v[48:49], v[48:49], v[42:43] op_sel:[1,0]
	v_cvt_f32_f16_sdwa v42, v88 dst_sel:DWORD dst_unused:UNUSED_PAD src0_sel:WORD_1
	v_pack_b32_f16 v46, v55, v47
	v_pk_mul_f32 v[48:49], v[48:49], v[52:53]
	v_cvt_f32_f16_sdwa v53, v89 dst_sel:DWORD dst_unused:UNUSED_PAD src0_sel:WORD_1
	v_cvt_pk_f16_f32 v52, v48, v49
	v_cvt_f32_f16_e32 v48, v89
	v_max_f32_e32 v42, 0xc1f00000, v42
	v_mul_f32_e32 v42, 0xbfb8aa3b, v42
	v_exp_f32_e32 v42, v42
	v_max_f32_e32 v48, 0xc1f00000, v48
	v_mul_f32_e32 v48, 0xbfb8aa3b, v48
	v_exp_f32_e32 v49, v48
	v_add_f32_e32 v42, 1.0, v42
	v_rcp_f32_e32 v48, v42
	v_alignbit_b32 v47, v52, v47, 16
	v_add_f32_e32 v42, 1.0, v49
	v_rcp_f32_e32 v49, v42
	v_mov_b32_e32 v42, v43
	v_mov_b32_e32 v43, v44
	v_cvt_f32_f16_e32 v44, v82
	v_pk_mul_f32 v[42:43], v[42:43], v[48:49]
	global_store_dwordx4 v[98:99], v[62:65], off
	v_cvt_pk_f16_f32 v42, v42, v43
	v_max_f32_e32 v43, 0xc1f00000, v53
	v_mul_f32_e32 v43, 0xbfb8aa3b, v43
	v_exp_f32_e32 v43, v43
	v_alignbit_b32 v48, v42, v52, 16
	v_lshrrev_b32_e32 v49, 16, v42
	v_add_f32_e32 v42, 1.0, v43
	v_rcp_f32_e32 v42, v42
	v_max_f32_e32 v43, 0xc1f00000, v44
	v_mul_f32_e32 v43, 0xbfb8aa3b, v43
	v_exp_f32_e32 v43, v43
	v_fma_mixhi_f16 v49, v45, v42, 0
	v_cvt_f32_f16_sdwa v42, v82 dst_sel:DWORD dst_unused:UNUSED_PAD src0_sel:WORD_1
	v_cvt_f32_f16_e32 v44, v83
	v_add_f32_e32 v43, 1.0, v43
	v_rcp_f32_e32 v43, v43
	v_max_f32_e32 v42, 0xc1f00000, v42
	v_mul_f32_e32 v42, 0xbfb8aa3b, v42
	v_max_f32_e32 v44, 0xc1f00000, v44
	v_exp_f32_e32 v42, v42
	v_mul_f32_e32 v44, 0xbfb8aa3b, v44
	v_exp_f32_e32 v44, v44
	v_fma_mixlo_f16 v45, v38, v43, 0
	v_add_f32_e32 v38, 1.0, v42
	v_rcp_f32_e32 v42, v38
	v_add_f32_e32 v38, 1.0, v44
	v_rcp_f32_e32 v43, v38
	v_cvt_f32_f16_sdwa v44, v83 dst_sel:DWORD dst_unused:UNUSED_PAD src0_sel:WORD_1
	v_mov_b32_e32 v38, v39
	v_mov_b32_e32 v39, v40
	v_cvt_f32_f16_e32 v40, v84
	v_max_f32_e32 v44, 0xc1f00000, v44
	v_mul_f32_e32 v44, 0xbfb8aa3b, v44
	v_exp_f32_e32 v44, v44
	v_max_f32_e32 v40, 0xc1f00000, v40
	v_mul_f32_e32 v40, 0xbfb8aa3b, v40
	v_exp_f32_e32 v40, v40
	v_pk_mul_f32 v[38:39], v[38:39], v[42:43]
	v_add_f32_e32 v42, 1.0, v44
	v_rcp_f32_e32 v42, v42
	v_add_f32_e32 v40, 1.0, v40
	v_rcp_f32_e32 v43, v40
	v_pk_mov_b32 v[40:41], v[40:41], v[34:35] op_sel:[1,0]
	v_cvt_f32_f16_sdwa v34, v84 dst_sel:DWORD dst_unused:UNUSED_PAD src0_sel:WORD_1
	v_cvt_pk_f16_f32 v39, v38, v39
	v_pk_mul_f32 v[40:41], v[40:41], v[42:43]
	v_cvt_f32_f16_sdwa v43, v85 dst_sel:DWORD dst_unused:UNUSED_PAD src0_sel:WORD_1
	v_cvt_pk_f16_f32 v42, v40, v41
	v_cvt_f32_f16_e32 v40, v85
	v_max_f32_e32 v34, 0xc1f00000, v34
	v_mul_f32_e32 v34, 0xbfb8aa3b, v34
	v_exp_f32_e32 v34, v34
	v_max_f32_e32 v40, 0xc1f00000, v40
	v_mul_f32_e32 v40, 0xbfb8aa3b, v40
	v_exp_f32_e32 v41, v40
	v_add_f32_e32 v34, 1.0, v34
	v_rcp_f32_e32 v40, v34
	v_pack_b32_f16 v38, v45, v39
	v_add_f32_e32 v34, 1.0, v41
	v_rcp_f32_e32 v41, v34
	v_mov_b32_e32 v34, v35
	v_max_f32_e32 v35, 0xc1f00000, v43
	v_mul_f32_e32 v35, 0xbfb8aa3b, v35
	v_exp_f32_e32 v43, v35
	v_mov_b32_e32 v35, v36
	v_pk_mul_f32 v[34:35], v[34:35], v[40:41]
	v_cvt_f32_f16_e32 v36, v78
	v_cvt_pk_f16_f32 v34, v34, v35
	v_add_f32_e32 v35, 1.0, v43
	v_rcp_f32_e32 v35, v35
	v_alignbit_b32 v40, v34, v42, 16
	v_lshrrev_b32_e32 v41, 16, v34
	v_max_f32_e32 v34, 0xc1f00000, v36
	v_alignbit_b32 v39, v42, v39, 16
	v_fma_mixhi_f16 v41, v37, v35, 0
	v_mul_f32_e32 v34, 0xbfb8aa3b, v34
	v_cvt_f32_f16_sdwa v37, v78 dst_sel:DWORD dst_unused:UNUSED_PAD src0_sel:WORD_1
	v_exp_f32_e32 v36, v34
	global_store_dwordx4 v[50:51], v[38:41], off offset:256
	v_lshl_add_u64 v[34:35], v[192:193], 0, v[184:185]
	v_max_f32_e32 v37, 0xc1f00000, v37
	v_cvt_f32_f16_e32 v38, v79
	v_add_f32_e32 v36, 1.0, v36
	v_mul_f32_e32 v37, 0xbfb8aa3b, v37
	v_rcp_f32_e32 v36, v36
	v_max_f32_e32 v38, 0xc1f00000, v38
	v_exp_f32_e32 v37, v37
	v_mul_f32_e32 v38, 0xbfb8aa3b, v38
	v_exp_f32_e32 v38, v38
	v_fma_mixlo_f16 v39, v28, v36, 0
	v_add_f32_e32 v28, 1.0, v37
	v_rcp_f32_e32 v36, v28
	v_add_f32_e32 v28, 1.0, v38
	v_rcp_f32_e32 v37, v28
	v_cvt_f32_f16_sdwa v38, v79 dst_sel:DWORD dst_unused:UNUSED_PAD src0_sel:WORD_1
	v_mov_b32_e32 v28, v29
	v_mov_b32_e32 v29, v30
	v_cvt_f32_f16_e32 v30, v80
	v_pk_mul_f32 v[28:29], v[28:29], v[36:37]
	v_max_f32_e32 v36, 0xc1f00000, v38
	v_mul_f32_e32 v36, 0xbfb8aa3b, v36
	v_max_f32_e32 v30, 0xc1f00000, v30
	v_exp_f32_e32 v36, v36
	v_mul_f32_e32 v30, 0xbfb8aa3b, v30
	v_exp_f32_e32 v30, v30
	v_cvt_pk_f16_f32 v29, v28, v29
	v_add_f32_e32 v28, 1.0, v36
	v_rcp_f32_e32 v36, v28
	v_add_f32_e32 v28, 1.0, v30
	v_rcp_f32_e32 v37, v28
	v_pk_mov_b32 v[30:31], v[30:31], v[24:25] op_sel:[1,0]
	v_cvt_f32_f16_sdwa v24, v80 dst_sel:DWORD dst_unused:UNUSED_PAD src0_sel:WORD_1
	v_pack_b32_f16 v28, v39, v29
	v_pk_mul_f32 v[30:31], v[30:31], v[36:37]
	v_cvt_f32_f16_sdwa v37, v81 dst_sel:DWORD dst_unused:UNUSED_PAD src0_sel:WORD_1
	v_cvt_pk_f16_f32 v36, v30, v31
	v_cvt_f32_f16_e32 v30, v81
	v_max_f32_e32 v24, 0xc1f00000, v24
	v_mul_f32_e32 v24, 0xbfb8aa3b, v24
	v_exp_f32_e32 v24, v24
	v_max_f32_e32 v30, 0xc1f00000, v30
	v_mul_f32_e32 v30, 0xbfb8aa3b, v30
	v_exp_f32_e32 v31, v30
	v_add_f32_e32 v24, 1.0, v24
	v_rcp_f32_e32 v30, v24
	v_alignbit_b32 v29, v36, v29, 16
	v_add_f32_e32 v24, 1.0, v31
	v_rcp_f32_e32 v31, v24
	v_mov_b32_e32 v24, v25
	v_mov_b32_e32 v25, v26
	v_cvt_f32_f16_e32 v26, v74
	v_pk_mul_f32 v[24:25], v[24:25], v[30:31]
	global_store_dwordx4 v[50:51], v[46:49], off
	v_cvt_pk_f16_f32 v24, v24, v25
	v_max_f32_e32 v25, 0xc1f00000, v37
	v_mul_f32_e32 v25, 0xbfb8aa3b, v25
	v_exp_f32_e32 v25, v25
	v_alignbit_b32 v30, v24, v36, 16
	v_lshrrev_b32_e32 v31, 16, v24
	v_add_f32_e32 v24, 1.0, v25
	v_rcp_f32_e32 v24, v24
	v_max_f32_e32 v25, 0xc1f00000, v26
	v_mul_f32_e32 v25, 0xbfb8aa3b, v25
	v_exp_f32_e32 v25, v25
	v_fma_mixhi_f16 v31, v27, v24, 0
	v_cvt_f32_f16_sdwa v24, v74 dst_sel:DWORD dst_unused:UNUSED_PAD src0_sel:WORD_1
	v_cvt_f32_f16_e32 v26, v75
	v_add_f32_e32 v25, 1.0, v25
	v_rcp_f32_e32 v25, v25
	v_max_f32_e32 v24, 0xc1f00000, v24
	v_mul_f32_e32 v24, 0xbfb8aa3b, v24
	v_max_f32_e32 v26, 0xc1f00000, v26
	v_exp_f32_e32 v24, v24
	v_mul_f32_e32 v26, 0xbfb8aa3b, v26
	v_exp_f32_e32 v26, v26
	v_fma_mixlo_f16 v27, v20, v25, 0
	v_add_f32_e32 v20, 1.0, v24
	v_rcp_f32_e32 v24, v20
	v_add_f32_e32 v20, 1.0, v26
	v_rcp_f32_e32 v25, v20
	v_cvt_f32_f16_sdwa v26, v75 dst_sel:DWORD dst_unused:UNUSED_PAD src0_sel:WORD_1
	v_mov_b32_e32 v20, v21
	v_mov_b32_e32 v21, v22
	v_cvt_f32_f16_e32 v22, v76
	v_max_f32_e32 v26, 0xc1f00000, v26
	v_mul_f32_e32 v26, 0xbfb8aa3b, v26
	v_exp_f32_e32 v26, v26
	v_max_f32_e32 v22, 0xc1f00000, v22
	v_mul_f32_e32 v22, 0xbfb8aa3b, v22
	v_exp_f32_e32 v22, v22
	v_pk_mul_f32 v[20:21], v[20:21], v[24:25]
	v_add_f32_e32 v24, 1.0, v26
	v_rcp_f32_e32 v24, v24
	v_add_f32_e32 v22, 1.0, v22
	v_rcp_f32_e32 v25, v22
	v_pk_mov_b32 v[22:23], v[22:23], v[16:17] op_sel:[1,0]
	v_cvt_f32_f16_sdwa v16, v76 dst_sel:DWORD dst_unused:UNUSED_PAD src0_sel:WORD_1
	v_cvt_pk_f16_f32 v21, v20, v21
	v_pk_mul_f32 v[22:23], v[22:23], v[24:25]
	v_cvt_f32_f16_sdwa v25, v77 dst_sel:DWORD dst_unused:UNUSED_PAD src0_sel:WORD_1
	v_cvt_pk_f16_f32 v24, v22, v23
	v_cvt_f32_f16_e32 v22, v77
	v_max_f32_e32 v16, 0xc1f00000, v16
	v_mul_f32_e32 v16, 0xbfb8aa3b, v16
	v_exp_f32_e32 v16, v16
	v_max_f32_e32 v22, 0xc1f00000, v22
	v_mul_f32_e32 v22, 0xbfb8aa3b, v22
	v_exp_f32_e32 v23, v22
	v_add_f32_e32 v16, 1.0, v16
	v_rcp_f32_e32 v22, v16
	v_pack_b32_f16 v20, v27, v21
	v_add_f32_e32 v16, 1.0, v23
	v_rcp_f32_e32 v23, v16
	v_mov_b32_e32 v16, v17
	v_max_f32_e32 v17, 0xc1f00000, v25
	v_mul_f32_e32 v17, 0xbfb8aa3b, v17
	v_exp_f32_e32 v25, v17
	v_mov_b32_e32 v17, v18
	v_pk_mul_f32 v[16:17], v[16:17], v[22:23]
	v_cvt_f32_f16_e32 v18, v70
	v_cvt_pk_f16_f32 v16, v16, v17
	v_add_f32_e32 v17, 1.0, v25
	v_rcp_f32_e32 v17, v17
	v_alignbit_b32 v22, v16, v24, 16
	v_lshrrev_b32_e32 v23, 16, v16
	v_max_f32_e32 v16, 0xc1f00000, v18
	v_alignbit_b32 v21, v24, v21, 16
	v_fma_mixhi_f16 v23, v19, v17, 0
	v_mul_f32_e32 v16, 0xbfb8aa3b, v16
	v_cvt_f32_f16_sdwa v19, v70 dst_sel:DWORD dst_unused:UNUSED_PAD src0_sel:WORD_1
	v_exp_f32_e32 v18, v16
	global_store_dwordx4 v[34:35], v[20:23], off offset:256
	v_lshl_add_u64 v[16:17], v[192:193], 0, v[186:187]
	v_max_f32_e32 v19, 0xc1f00000, v19
	v_cvt_f32_f16_e32 v20, v71
	v_add_f32_e32 v18, 1.0, v18
	v_mul_f32_e32 v19, 0xbfb8aa3b, v19
	v_rcp_f32_e32 v18, v18
	v_max_f32_e32 v20, 0xc1f00000, v20
	v_exp_f32_e32 v19, v19
	v_mul_f32_e32 v20, 0xbfb8aa3b, v20
	v_exp_f32_e32 v20, v20
	v_fma_mixlo_f16 v21, v12, v18, 0
	v_add_f32_e32 v12, 1.0, v19
	v_rcp_f32_e32 v18, v12
	v_add_f32_e32 v12, 1.0, v20
	v_rcp_f32_e32 v19, v12
	v_cvt_f32_f16_sdwa v20, v71 dst_sel:DWORD dst_unused:UNUSED_PAD src0_sel:WORD_1
	v_mov_b32_e32 v12, v13
	v_mov_b32_e32 v13, v14
	v_cvt_f32_f16_e32 v14, v72
	v_pk_mul_f32 v[12:13], v[12:13], v[18:19]
	v_max_f32_e32 v18, 0xc1f00000, v20
	v_mul_f32_e32 v18, 0xbfb8aa3b, v18
	v_max_f32_e32 v14, 0xc1f00000, v14
	v_exp_f32_e32 v18, v18
	v_mul_f32_e32 v14, 0xbfb8aa3b, v14
	v_exp_f32_e32 v14, v14
	v_cvt_pk_f16_f32 v13, v12, v13
	v_add_f32_e32 v12, 1.0, v18
	v_rcp_f32_e32 v18, v12
	v_add_f32_e32 v12, 1.0, v14
	v_rcp_f32_e32 v19, v12
	v_pk_mov_b32 v[14:15], v[14:15], v[8:9] op_sel:[1,0]
	v_cvt_f32_f16_sdwa v8, v72 dst_sel:DWORD dst_unused:UNUSED_PAD src0_sel:WORD_1
	v_pack_b32_f16 v12, v21, v13
	v_pk_mul_f32 v[14:15], v[14:15], v[18:19]
	v_cvt_f32_f16_sdwa v19, v73 dst_sel:DWORD dst_unused:UNUSED_PAD src0_sel:WORD_1
	v_cvt_pk_f16_f32 v18, v14, v15
	v_cvt_f32_f16_e32 v14, v73
	v_max_f32_e32 v8, 0xc1f00000, v8
	v_mul_f32_e32 v8, 0xbfb8aa3b, v8
	v_exp_f32_e32 v8, v8
	v_max_f32_e32 v14, 0xc1f00000, v14
	v_mul_f32_e32 v14, 0xbfb8aa3b, v14
	v_exp_f32_e32 v15, v14
	v_add_f32_e32 v8, 1.0, v8
	v_rcp_f32_e32 v14, v8
	v_alignbit_b32 v13, v18, v13, 16
	v_add_f32_e32 v8, 1.0, v15
	v_rcp_f32_e32 v15, v8
	v_mov_b32_e32 v8, v9
	v_mov_b32_e32 v9, v10
	v_cvt_f32_f16_e32 v10, v66
	v_pk_mul_f32 v[8:9], v[8:9], v[14:15]
	global_store_dwordx4 v[34:35], v[28:31], off
	v_cvt_pk_f16_f32 v8, v8, v9
	v_max_f32_e32 v9, 0xc1f00000, v19
	v_mul_f32_e32 v9, 0xbfb8aa3b, v9
	v_exp_f32_e32 v9, v9
	v_alignbit_b32 v14, v8, v18, 16
	v_lshrrev_b32_e32 v15, 16, v8
	v_add_f32_e32 v8, 1.0, v9
	v_rcp_f32_e32 v8, v8
	v_max_f32_e32 v9, 0xc1f00000, v10
	v_mul_f32_e32 v9, 0xbfb8aa3b, v9
	v_exp_f32_e32 v9, v9
	v_fma_mixhi_f16 v15, v11, v8, 0
	v_cvt_f32_f16_sdwa v8, v66 dst_sel:DWORD dst_unused:UNUSED_PAD src0_sel:WORD_1
	v_cvt_f32_f16_e32 v10, v67
	v_add_f32_e32 v9, 1.0, v9
	v_rcp_f32_e32 v9, v9
	v_max_f32_e32 v8, 0xc1f00000, v8
	v_mul_f32_e32 v8, 0xbfb8aa3b, v8
	v_max_f32_e32 v10, 0xc1f00000, v10
	v_exp_f32_e32 v8, v8
	v_mul_f32_e32 v10, 0xbfb8aa3b, v10
	v_exp_f32_e32 v10, v10
	v_fma_mixlo_f16 v11, v4, v9, 0
	v_add_f32_e32 v4, 1.0, v8
	v_rcp_f32_e32 v8, v4
	v_add_f32_e32 v4, 1.0, v10
	v_rcp_f32_e32 v9, v4
	v_cvt_f32_f16_sdwa v10, v67 dst_sel:DWORD dst_unused:UNUSED_PAD src0_sel:WORD_1
	v_mov_b32_e32 v4, v5
	v_mov_b32_e32 v5, v6
	v_cvt_f32_f16_e32 v6, v68
	v_max_f32_e32 v10, 0xc1f00000, v10
	v_mul_f32_e32 v10, 0xbfb8aa3b, v10
	v_exp_f32_e32 v10, v10
	v_max_f32_e32 v6, 0xc1f00000, v6
	v_mul_f32_e32 v6, 0xbfb8aa3b, v6
	v_exp_f32_e32 v6, v6
	v_pk_mul_f32 v[4:5], v[4:5], v[8:9]
	v_add_f32_e32 v8, 1.0, v10
	v_rcp_f32_e32 v8, v8
	v_add_f32_e32 v6, 1.0, v6
	v_rcp_f32_e32 v9, v6
	v_pk_mov_b32 v[6:7], v[6:7], v[0:1] op_sel:[1,0]
	v_cvt_f32_f16_sdwa v0, v68 dst_sel:DWORD dst_unused:UNUSED_PAD src0_sel:WORD_1
	v_cvt_pk_f16_f32 v5, v4, v5
	v_pk_mul_f32 v[6:7], v[6:7], v[8:9]
	v_cvt_f32_f16_sdwa v9, v69 dst_sel:DWORD dst_unused:UNUSED_PAD src0_sel:WORD_1
	v_cvt_pk_f16_f32 v8, v6, v7
	v_cvt_f32_f16_e32 v6, v69
	v_max_f32_e32 v0, 0xc1f00000, v0
	v_mul_f32_e32 v0, 0xbfb8aa3b, v0
	v_exp_f32_e32 v0, v0
	v_max_f32_e32 v6, 0xc1f00000, v6
	v_mul_f32_e32 v6, 0xbfb8aa3b, v6
	v_exp_f32_e32 v7, v6
	v_add_f32_e32 v0, 1.0, v0
	v_rcp_f32_e32 v6, v0
	v_pack_b32_f16 v4, v11, v5
	v_add_f32_e32 v0, 1.0, v7
	v_rcp_f32_e32 v7, v0
	v_max_f32_e32 v0, 0xc1f00000, v9
	v_mul_f32_e32 v0, 0xbfb8aa3b, v0
	v_exp_f32_e32 v9, v0
	v_mov_b32_e32 v0, v1
	v_mov_b32_e32 v1, v2
	v_pk_mul_f32 v[0:1], v[0:1], v[6:7]
	v_add_f32_e32 v2, 1.0, v9
	v_rcp_f32_e32 v2, v2
	v_cvt_pk_f16_f32 v0, v0, v1
	v_lshrrev_b32_e32 v7, 16, v0
	v_alignbit_b32 v5, v8, v5, 16
	v_alignbit_b32 v6, v0, v8, 16
	v_fma_mixhi_f16 v7, v3, v2, 0
	global_store_dwordx4 v[16:17], v[12:15], off
	global_store_dwordx4 v[16:17], v[4:7], off offset:256
	s_cmp_eq_u32 s50, 0
	s_cbranch_scc1 .Lepib_ygc_nb
	s_mov_b32 s50, 0
	s_barrier
.Lepib_ygc_nb:
	s_and_b64 vcc, exec, s[4:5]
	s_mov_b32 s31, s30
	s_mov_b32 s34, s29
	s_mov_b64 s[12:13], s[0:1]
	s_mov_b64 s[10:11], s[2:3]
	s_cbranch_vccz .LBB0_955
	s_waitcnt vmcnt(0)
	s_cmpk_gt_u32 s19, 0xff
	s_cbranch_scc1 .LBB0_962
	s_barrier
